# peel first K-loop iteration per unit with srcC=0, drop accumulator zeroing moves
# speedup vs baseline: 1.0053x; 1.0053x over previous
.LBB0_169:
	v_cmp_gt_i32_e32 vcc, 1, v138
	s_cbranch_vccnz .LBB0_231
	v_lshl_add_u64 v[152:153], v[2:3], 0, s[22:23]
	v_add_u32_e32 v154, -2, v138
	s_waitcnt lgkmcnt(0)
	v_lshl_add_u64 v[150:151], v[4:5], 0, s[28:29]
	s_mov_b32 s7, 0
	v_add_u32_e32 v155, s76, v141
	ds_read_b128 v[164:167], v155
	ds_read_b128 v[168:171], v155 offset:1024
	ds_read_b128 v[172:175], v155 offset:2048
	ds_read_b128 v[176:179], v155 offset:3072
	v_add_u32_e32 v155, s77, v141
	ds_read_b128 v[180:183], v155
	ds_read_b128 v[184:187], v155 offset:1024
	ds_read_b128 v[188:191], v155 offset:2048
	ds_read_b128 v[192:195], v155 offset:3072
	v_lshl_add_u64 v[156:157], v[152:153], 0, s[44:45]
	v_cmp_eq_u32_e32 vcc, s7, v154
	s_add_i32 s51, s7, 2
	s_nop 0
	v_cndmask_b32_e32 v157, v157, v147, vcc
	v_cndmask_b32_e32 v156, v156, v146, vcc
	v_cndmask_b32_e32 v229, v151, v149, vcc
	v_cndmask_b32_e32 v228, v150, v148, vcc
	s_mov_b32 m0, s78
	v_lshl_add_u64 v[230:231], v[152:153], 0, v[144:145]
	ds_read_b128 v[196:199], v160
	ds_read_b128 v[200:203], v160 offset:1024
	ds_read_b128 v[204:207], v160 offset:2048
	ds_read_b128 v[208:211], v160 offset:3072
	ds_read_b128 v[212:215], v160 offset:4096
	ds_read_b128 v[216:219], v160 offset:5120
	ds_read_b128 v[220:223], v160 offset:6144
	ds_read_b128 v[224:227], v160 offset:7168
	global_load_lds_dwordx4 v[230:231], off
	v_lshl_add_u64 v[230:231], v[152:153], 0, v[142:143]
	s_mov_b32 m0, s79
	s_nop 0
	global_load_lds_dwordx4 v[230:231], off
	s_waitcnt vmcnt(8)
	s_waitcnt lgkmcnt(0)
	s_barrier
	s_setprio 1
	s_waitcnt lgkmcnt(0)
	v_mfma_f32_16x16x32_bf16 v[122:125], v[164:167], v[196:199], 0
	v_mfma_f32_16x16x32_bf16 v[118:121], v[172:175], v[196:199], 0
	v_mfma_f32_16x16x32_bf16 v[110:113], v[164:167], v[204:207], 0
	v_mfma_f32_16x16x32_bf16 v[102:105], v[172:175], v[204:207], 0
	v_mfma_f32_16x16x32_bf16 v[94:97], v[164:167], v[212:215], 0
	v_mfma_f32_16x16x32_bf16 v[86:89], v[172:175], v[212:215], 0
	v_mfma_f32_16x16x32_bf16 v[78:81], v[164:167], v[220:223], 0
	v_mfma_f32_16x16x32_bf16 v[70:73], v[172:175], v[220:223], 0
	v_mfma_f32_16x16x32_bf16 v[122:125], v[168:171], v[200:203], v[122:125]
	v_mfma_f32_16x16x32_bf16 v[118:121], v[176:179], v[200:203], v[118:121]
	v_mfma_f32_16x16x32_bf16 v[110:113], v[168:171], v[208:211], v[110:113]
	v_mfma_f32_16x16x32_bf16 v[102:105], v[176:179], v[208:211], v[102:105]
	v_mfma_f32_16x16x32_bf16 v[94:97], v[168:171], v[216:219], v[94:97]
	v_mfma_f32_16x16x32_bf16 v[86:89], v[176:179], v[216:219], v[86:89]
	v_mfma_f32_16x16x32_bf16 v[78:81], v[168:171], v[224:227], v[78:81]
	v_mfma_f32_16x16x32_bf16 v[70:73], v[176:179], v[224:227], v[70:73]
	s_setprio 0
	s_setprio 1
	v_mfma_f32_16x16x32_bf16 v[126:129], v[180:183], v[196:199], 0
	v_mfma_f32_16x16x32_bf16 v[114:117], v[188:191], v[196:199], 0
	v_mfma_f32_16x16x32_bf16 v[106:109], v[180:183], v[204:207], 0
	v_mfma_f32_16x16x32_bf16 v[98:101], v[188:191], v[204:207], 0
	v_mfma_f32_16x16x32_bf16 v[90:93], v[180:183], v[212:215], 0
	v_mfma_f32_16x16x32_bf16 v[82:85], v[188:191], v[212:215], 0
	v_mfma_f32_16x16x32_bf16 v[74:77], v[180:183], v[220:223], 0
	v_mfma_f32_16x16x32_bf16 v[66:69], v[188:191], v[220:223], 0
	v_mfma_f32_16x16x32_bf16 v[126:129], v[184:187], v[200:203], v[126:129]
	v_mfma_f32_16x16x32_bf16 v[114:117], v[192:195], v[200:203], v[114:117]
	v_mfma_f32_16x16x32_bf16 v[106:109], v[184:187], v[208:211], v[106:109]
	v_mfma_f32_16x16x32_bf16 v[98:101], v[192:195], v[208:211], v[98:101]
	v_mfma_f32_16x16x32_bf16 v[90:93], v[184:187], v[216:219], v[90:93]
	v_mfma_f32_16x16x32_bf16 v[82:85], v[192:195], v[216:219], v[82:85]
	v_mfma_f32_16x16x32_bf16 v[74:77], v[184:187], v[224:227], v[74:77]
	v_mfma_f32_16x16x32_bf16 v[66:69], v[192:195], v[224:227], v[66:69]
	s_setprio 0
	s_barrier
	s_mov_b32 m0, s80
	v_lshl_add_u64 v[230:231], v[228:229], 0, v[132:133]
	ds_read_b128 v[196:199], v160 offset:16384
	ds_read_b128 v[200:203], v160 offset:17408
	ds_read_b128 v[204:207], v160 offset:18432
	ds_read_b128 v[208:211], v160 offset:19456
	ds_read_b128 v[212:215], v160 offset:20480
	ds_read_b128 v[216:219], v160 offset:21504
	ds_read_b128 v[220:223], v160 offset:22528
	ds_read_b128 v[224:227], v160 offset:23552
	global_load_lds_dwordx4 v[230:231], off
	v_lshl_add_u64 v[232:233], v[228:229], 0, v[136:137]
	s_mov_b32 m0, s81
	v_lshl_add_u64 v[234:235], v[228:229], 0, s[14:15]
	s_add_i32 s7, s77, s47
	global_load_lds_dwordx4 v[232:233], off
	v_lshl_add_u64 v[236:237], v[234:235], 0, v[132:133]
	s_mov_b32 m0, s7
	v_lshl_add_u64 v[234:235], v[234:235], 0, v[136:137]
	global_load_lds_dwordx4 v[236:237], off
	s_add_i32 m0, s7, 0x2000
	v_lshl_add_u64 v[236:237], v[156:157], 0, v[134:135]
	global_load_lds_dwordx4 v[234:235], off
	v_lshl_add_u64 v[234:235], v[156:157], 0, v[130:131]
	s_mov_b32 m0, s57
	s_nop 0
	global_load_lds_dwordx4 v[234:235], off
	s_mov_b32 m0, s62
	s_nop 0
	global_load_lds_dwordx4 v[236:237], off
	s_waitcnt vmcnt(8)
	s_waitcnt lgkmcnt(0)
	s_barrier
	s_setprio 1
	s_waitcnt lgkmcnt(0)
	v_mfma_f32_16x16x32_bf16 v[62:65], v[164:167], v[196:199], 0
	v_mfma_f32_16x16x32_bf16 v[54:57], v[172:175], v[196:199], 0
	v_mfma_f32_16x16x32_bf16 v[46:49], v[164:167], v[204:207], 0
	v_mfma_f32_16x16x32_bf16 v[38:41], v[172:175], v[204:207], 0
	v_mfma_f32_16x16x32_bf16 v[30:33], v[164:167], v[212:215], 0
	v_mfma_f32_16x16x32_bf16 v[22:25], v[172:175], v[212:215], 0
	v_mfma_f32_16x16x32_bf16 v[14:17], v[164:167], v[220:223], 0
	v_mfma_f32_16x16x32_bf16 v[6:9], v[172:175], v[220:223], 0
	v_mfma_f32_16x16x32_bf16 v[62:65], v[168:171], v[200:203], v[62:65]
	v_mfma_f32_16x16x32_bf16 v[54:57], v[176:179], v[200:203], v[54:57]
	v_mfma_f32_16x16x32_bf16 v[46:49], v[168:171], v[208:211], v[46:49]
	v_mfma_f32_16x16x32_bf16 v[38:41], v[176:179], v[208:211], v[38:41]
	v_mfma_f32_16x16x32_bf16 v[30:33], v[168:171], v[216:219], v[30:33]
	v_mfma_f32_16x16x32_bf16 v[22:25], v[176:179], v[216:219], v[22:25]
	v_mfma_f32_16x16x32_bf16 v[14:17], v[168:171], v[224:227], v[14:17]
	v_mfma_f32_16x16x32_bf16 v[6:9], v[176:179], v[224:227], v[6:9]
	s_setprio 0
	s_setprio 1
	v_mfma_f32_16x16x32_bf16 v[58:61], v[180:183], v[196:199], 0
	v_mfma_f32_16x16x32_bf16 v[50:53], v[188:191], v[196:199], 0
	v_mfma_f32_16x16x32_bf16 v[42:45], v[180:183], v[204:207], 0
	v_mfma_f32_16x16x32_bf16 v[34:37], v[188:191], v[204:207], 0
	v_mfma_f32_16x16x32_bf16 v[26:29], v[180:183], v[212:215], 0
	v_mfma_f32_16x16x32_bf16 v[18:21], v[188:191], v[212:215], 0
	v_mfma_f32_16x16x32_bf16 v[10:13], v[180:183], v[220:223], 0
	v_mfma_f32_16x16x32_bf16 v[2:5], v[188:191], v[220:223], 0
	v_mfma_f32_16x16x32_bf16 v[58:61], v[184:187], v[200:203], v[58:61]
	v_mfma_f32_16x16x32_bf16 v[50:53], v[192:195], v[200:203], v[50:53]
	v_mfma_f32_16x16x32_bf16 v[42:45], v[184:187], v[208:211], v[42:45]
	v_mfma_f32_16x16x32_bf16 v[34:37], v[192:195], v[208:211], v[34:37]
	v_mfma_f32_16x16x32_bf16 v[26:29], v[184:187], v[216:219], v[26:29]
	v_mfma_f32_16x16x32_bf16 v[18:21], v[192:195], v[216:219], v[18:21]
	v_mfma_f32_16x16x32_bf16 v[10:13], v[184:187], v[224:227], v[10:13]
	v_mfma_f32_16x16x32_bf16 v[2:5], v[192:195], v[224:227], v[2:5]
	s_setprio 0
	s_barrier
	s_add_i32 s7, 0, 0x18000
	v_add_u32_e32 v155, s7, v141
	s_add_i32 s55, 0, 0x1c000
	ds_read_b128 v[164:167], v155
	ds_read_b128 v[168:171], v155 offset:1024
	ds_read_b128 v[172:175], v155 offset:2048
	ds_read_b128 v[176:179], v155 offset:3072
	v_add_u32_e32 v155, s55, v141
	ds_read_b128 v[180:183], v155
	ds_read_b128 v[184:187], v155 offset:1024
	ds_read_b128 v[188:191], v155 offset:2048
	ds_read_b128 v[192:195], v155 offset:3072
	v_lshl_add_u64 v[156:157], v[156:157], 0, s[14:15]
	s_mov_b32 m0, s63
	v_lshl_add_u64 v[238:239], v[156:157], 0, v[130:131]
	ds_read_b128 v[196:199], v160 offset:32768
	ds_read_b128 v[200:203], v160 offset:33792
	ds_read_b128 v[204:207], v160 offset:34816
	ds_read_b128 v[208:211], v160 offset:35840
	ds_read_b128 v[212:215], v160 offset:36864
	ds_read_b128 v[216:219], v160 offset:37888
	ds_read_b128 v[220:223], v160 offset:38912
	ds_read_b128 v[224:227], v160 offset:39936
	global_load_lds_dwordx4 v[238:239], off
	v_lshl_add_u64 v[156:157], v[156:157], 0, v[134:135]
	s_mov_b32 m0, s64
	s_nop 0
	global_load_lds_dwordx4 v[156:157], off
	s_waitcnt vmcnt(8)
	s_waitcnt lgkmcnt(0)
	s_barrier
	s_setprio 1
	s_waitcnt lgkmcnt(0)
	v_mfma_f32_16x16x32_bf16 v[122:125], v[164:167], v[196:199], v[122:125]
	v_mfma_f32_16x16x32_bf16 v[118:121], v[172:175], v[196:199], v[118:121]
	v_mfma_f32_16x16x32_bf16 v[110:113], v[164:167], v[204:207], v[110:113]
	v_mfma_f32_16x16x32_bf16 v[102:105], v[172:175], v[204:207], v[102:105]
	v_mfma_f32_16x16x32_bf16 v[94:97], v[164:167], v[212:215], v[94:97]
	v_mfma_f32_16x16x32_bf16 v[86:89], v[172:175], v[212:215], v[86:89]
	v_mfma_f32_16x16x32_bf16 v[78:81], v[164:167], v[220:223], v[78:81]
	v_mfma_f32_16x16x32_bf16 v[70:73], v[172:175], v[220:223], v[70:73]
	v_mfma_f32_16x16x32_bf16 v[122:125], v[168:171], v[200:203], v[122:125]
	v_mfma_f32_16x16x32_bf16 v[118:121], v[176:179], v[200:203], v[118:121]
	v_mfma_f32_16x16x32_bf16 v[110:113], v[168:171], v[208:211], v[110:113]
	v_mfma_f32_16x16x32_bf16 v[102:105], v[176:179], v[208:211], v[102:105]
	v_mfma_f32_16x16x32_bf16 v[94:97], v[168:171], v[216:219], v[94:97]
	v_mfma_f32_16x16x32_bf16 v[86:89], v[176:179], v[216:219], v[86:89]
	v_mfma_f32_16x16x32_bf16 v[78:81], v[168:171], v[224:227], v[78:81]
	v_mfma_f32_16x16x32_bf16 v[70:73], v[176:179], v[224:227], v[70:73]
	s_setprio 0
	s_setprio 1
	v_mfma_f32_16x16x32_bf16 v[126:129], v[180:183], v[196:199], v[126:129]
	v_mfma_f32_16x16x32_bf16 v[114:117], v[188:191], v[196:199], v[114:117]
	v_mfma_f32_16x16x32_bf16 v[106:109], v[180:183], v[204:207], v[106:109]
	v_mfma_f32_16x16x32_bf16 v[98:101], v[188:191], v[204:207], v[98:101]
	v_mfma_f32_16x16x32_bf16 v[90:93], v[180:183], v[212:215], v[90:93]
	v_mfma_f32_16x16x32_bf16 v[82:85], v[188:191], v[212:215], v[82:85]
	v_mfma_f32_16x16x32_bf16 v[74:77], v[180:183], v[220:223], v[74:77]
	v_mfma_f32_16x16x32_bf16 v[66:69], v[188:191], v[220:223], v[66:69]
	v_mfma_f32_16x16x32_bf16 v[126:129], v[184:187], v[200:203], v[126:129]
	v_mfma_f32_16x16x32_bf16 v[114:117], v[192:195], v[200:203], v[114:117]
	v_mfma_f32_16x16x32_bf16 v[106:109], v[184:187], v[208:211], v[106:109]
	v_mfma_f32_16x16x32_bf16 v[98:101], v[192:195], v[208:211], v[98:101]
	v_mfma_f32_16x16x32_bf16 v[90:93], v[184:187], v[216:219], v[90:93]
	v_mfma_f32_16x16x32_bf16 v[82:85], v[192:195], v[216:219], v[82:85]
	v_mfma_f32_16x16x32_bf16 v[74:77], v[184:187], v[224:227], v[74:77]
	v_mfma_f32_16x16x32_bf16 v[66:69], v[192:195], v[224:227], v[66:69]
	s_setprio 0
	s_barrier
	s_add_i32 s7, s7, s47
	v_lshl_add_u64 v[156:157], v[230:231], 0, s[20:21]
	s_mov_b32 m0, s7
	ds_read_b128 v[196:199], v160 offset:49152
	ds_read_b128 v[200:203], v160 offset:50176
	ds_read_b128 v[204:207], v160 offset:51200
	ds_read_b128 v[208:211], v160 offset:52224
	ds_read_b128 v[212:215], v160 offset:53248
	ds_read_b128 v[216:219], v160 offset:54272
	ds_read_b128 v[220:223], v160 offset:55296
	ds_read_b128 v[224:227], v160 offset:56320
	global_load_lds_dwordx4 v[156:157], off
	v_lshl_add_u64 v[156:157], v[232:233], 0, s[20:21]
	s_add_i32 m0, s7, 0x2000
	s_add_i32 s7, s55, s47
	global_load_lds_dwordx4 v[156:157], off
	v_lshl_add_u64 v[156:157], v[228:229], 0, s[22:23]
	v_lshl_add_u64 v[228:229], v[156:157], 0, v[132:133]
	s_mov_b32 m0, s7
	v_lshl_add_u64 v[156:157], v[156:157], 0, v[136:137]
	global_load_lds_dwordx4 v[228:229], off
	s_add_i32 m0, s7, 0x2000
	s_nop 0
	global_load_lds_dwordx4 v[156:157], off
	v_lshl_add_u64 v[156:157], v[234:235], 0, s[20:21]
	s_mov_b32 m0, s65
	s_nop 0
	global_load_lds_dwordx4 v[156:157], off
	v_lshl_add_u64 v[156:157], v[236:237], 0, s[20:21]
	s_mov_b32 m0, s66
	s_nop 0
	global_load_lds_dwordx4 v[156:157], off
	s_waitcnt vmcnt(8)
	s_waitcnt lgkmcnt(0)
	s_barrier
	s_setprio 1
	s_waitcnt lgkmcnt(0)
	v_mfma_f32_16x16x32_bf16 v[62:65], v[164:167], v[196:199], v[62:65]
	v_mfma_f32_16x16x32_bf16 v[54:57], v[172:175], v[196:199], v[54:57]
	v_mfma_f32_16x16x32_bf16 v[46:49], v[164:167], v[204:207], v[46:49]
	v_mfma_f32_16x16x32_bf16 v[38:41], v[172:175], v[204:207], v[38:41]
	v_mfma_f32_16x16x32_bf16 v[30:33], v[164:167], v[212:215], v[30:33]
	v_mfma_f32_16x16x32_bf16 v[22:25], v[172:175], v[212:215], v[22:25]
	v_mfma_f32_16x16x32_bf16 v[14:17], v[164:167], v[220:223], v[14:17]
	v_mfma_f32_16x16x32_bf16 v[6:9], v[172:175], v[220:223], v[6:9]
	v_mfma_f32_16x16x32_bf16 v[62:65], v[168:171], v[200:203], v[62:65]
	v_mfma_f32_16x16x32_bf16 v[54:57], v[176:179], v[200:203], v[54:57]
	v_mfma_f32_16x16x32_bf16 v[46:49], v[168:171], v[208:211], v[46:49]
	v_mfma_f32_16x16x32_bf16 v[38:41], v[176:179], v[208:211], v[38:41]
	v_mfma_f32_16x16x32_bf16 v[30:33], v[168:171], v[216:219], v[30:33]
	v_mfma_f32_16x16x32_bf16 v[22:25], v[176:179], v[216:219], v[22:25]
	v_mfma_f32_16x16x32_bf16 v[14:17], v[168:171], v[224:227], v[14:17]
	v_mfma_f32_16x16x32_bf16 v[6:9], v[176:179], v[224:227], v[6:9]
	s_setprio 0
	s_setprio 1
	v_mfma_f32_16x16x32_bf16 v[58:61], v[180:183], v[196:199], v[58:61]
	v_mfma_f32_16x16x32_bf16 v[50:53], v[188:191], v[196:199], v[50:53]
	v_mfma_f32_16x16x32_bf16 v[42:45], v[180:183], v[204:207], v[42:45]
	v_mfma_f32_16x16x32_bf16 v[34:37], v[188:191], v[204:207], v[34:37]
	v_mfma_f32_16x16x32_bf16 v[26:29], v[180:183], v[212:215], v[26:29]
	v_mfma_f32_16x16x32_bf16 v[18:21], v[188:191], v[212:215], v[18:21]
	v_mfma_f32_16x16x32_bf16 v[10:13], v[180:183], v[220:223], v[10:13]
	v_mfma_f32_16x16x32_bf16 v[2:5], v[188:191], v[220:223], v[2:5]
	v_mfma_f32_16x16x32_bf16 v[58:61], v[184:187], v[200:203], v[58:61]
	v_mfma_f32_16x16x32_bf16 v[50:53], v[192:195], v[200:203], v[50:53]
	v_mfma_f32_16x16x32_bf16 v[42:45], v[184:187], v[208:211], v[42:45]
	v_mfma_f32_16x16x32_bf16 v[34:37], v[192:195], v[208:211], v[34:37]
	v_mfma_f32_16x16x32_bf16 v[26:29], v[184:187], v[216:219], v[26:29]
	v_mfma_f32_16x16x32_bf16 v[18:21], v[192:195], v[216:219], v[18:21]
	v_mfma_f32_16x16x32_bf16 v[10:13], v[184:187], v[224:227], v[10:13]
	v_mfma_f32_16x16x32_bf16 v[2:5], v[192:195], v[224:227], v[2:5]
	s_setprio 0
	s_barrier
	v_cmp_ge_i32_e32 vcc, s51, v138
	v_lshl_add_u64 v[150:151], v[150:151], 0, s[28:29]
	v_lshl_add_u64 v[152:153], v[152:153], 0, s[28:29]
	s_mov_b32 s7, s51
	s_cbranch_vccnz .Lmy_kexit_0
.LBB0_171:
	v_add_u32_e32 v155, s76, v141
	ds_read_b128 v[164:167], v155
	ds_read_b128 v[168:171], v155 offset:1024
	ds_read_b128 v[172:175], v155 offset:2048
	ds_read_b128 v[176:179], v155 offset:3072
	v_add_u32_e32 v155, s77, v141
	ds_read_b128 v[180:183], v155
	ds_read_b128 v[184:187], v155 offset:1024
	ds_read_b128 v[188:191], v155 offset:2048
	ds_read_b128 v[192:195], v155 offset:3072
	v_lshl_add_u64 v[156:157], v[152:153], 0, s[44:45]
	v_cmp_eq_u32_e32 vcc, s7, v154
	s_add_i32 s51, s7, 2
	s_nop 0
	v_cndmask_b32_e32 v157, v157, v147, vcc
	v_cndmask_b32_e32 v156, v156, v146, vcc
	v_cndmask_b32_e32 v229, v151, v149, vcc
	v_cndmask_b32_e32 v228, v150, v148, vcc
	s_mov_b32 m0, s78
	v_lshl_add_u64 v[230:231], v[152:153], 0, v[144:145]
	ds_read_b128 v[196:199], v160
	ds_read_b128 v[200:203], v160 offset:1024
	ds_read_b128 v[204:207], v160 offset:2048
	ds_read_b128 v[208:211], v160 offset:3072
	ds_read_b128 v[212:215], v160 offset:4096
	ds_read_b128 v[216:219], v160 offset:5120
	ds_read_b128 v[220:223], v160 offset:6144
	ds_read_b128 v[224:227], v160 offset:7168
	global_load_lds_dwordx4 v[230:231], off
	v_lshl_add_u64 v[230:231], v[152:153], 0, v[142:143]
	s_mov_b32 m0, s79
	s_nop 0
	global_load_lds_dwordx4 v[230:231], off
	s_waitcnt vmcnt(8)
	s_waitcnt lgkmcnt(0)
	s_barrier
	s_setprio 1
	s_waitcnt lgkmcnt(0)
	v_mfma_f32_16x16x32_bf16 v[122:125], v[164:167], v[196:199], v[122:125]
	v_mfma_f32_16x16x32_bf16 v[118:121], v[172:175], v[196:199], v[118:121]
	v_mfma_f32_16x16x32_bf16 v[110:113], v[164:167], v[204:207], v[110:113]
	v_mfma_f32_16x16x32_bf16 v[102:105], v[172:175], v[204:207], v[102:105]
	v_mfma_f32_16x16x32_bf16 v[94:97], v[164:167], v[212:215], v[94:97]
	v_mfma_f32_16x16x32_bf16 v[86:89], v[172:175], v[212:215], v[86:89]
	v_mfma_f32_16x16x32_bf16 v[78:81], v[164:167], v[220:223], v[78:81]
	v_mfma_f32_16x16x32_bf16 v[70:73], v[172:175], v[220:223], v[70:73]
	v_mfma_f32_16x16x32_bf16 v[122:125], v[168:171], v[200:203], v[122:125]
	v_mfma_f32_16x16x32_bf16 v[118:121], v[176:179], v[200:203], v[118:121]
	v_mfma_f32_16x16x32_bf16 v[110:113], v[168:171], v[208:211], v[110:113]
	v_mfma_f32_16x16x32_bf16 v[102:105], v[176:179], v[208:211], v[102:105]
	v_mfma_f32_16x16x32_bf16 v[94:97], v[168:171], v[216:219], v[94:97]
	v_mfma_f32_16x16x32_bf16 v[86:89], v[176:179], v[216:219], v[86:89]
	v_mfma_f32_16x16x32_bf16 v[78:81], v[168:171], v[224:227], v[78:81]
	v_mfma_f32_16x16x32_bf16 v[70:73], v[176:179], v[224:227], v[70:73]
	s_setprio 0
	s_setprio 1
	v_mfma_f32_16x16x32_bf16 v[126:129], v[180:183], v[196:199], v[126:129]
	v_mfma_f32_16x16x32_bf16 v[114:117], v[188:191], v[196:199], v[114:117]
	v_mfma_f32_16x16x32_bf16 v[106:109], v[180:183], v[204:207], v[106:109]
	v_mfma_f32_16x16x32_bf16 v[98:101], v[188:191], v[204:207], v[98:101]
	v_mfma_f32_16x16x32_bf16 v[90:93], v[180:183], v[212:215], v[90:93]
	v_mfma_f32_16x16x32_bf16 v[82:85], v[188:191], v[212:215], v[82:85]
	v_mfma_f32_16x16x32_bf16 v[74:77], v[180:183], v[220:223], v[74:77]
	v_mfma_f32_16x16x32_bf16 v[66:69], v[188:191], v[220:223], v[66:69]
	v_mfma_f32_16x16x32_bf16 v[126:129], v[184:187], v[200:203], v[126:129]
	v_mfma_f32_16x16x32_bf16 v[114:117], v[192:195], v[200:203], v[114:117]
	v_mfma_f32_16x16x32_bf16 v[106:109], v[184:187], v[208:211], v[106:109]
	v_mfma_f32_16x16x32_bf16 v[98:101], v[192:195], v[208:211], v[98:101]
	v_mfma_f32_16x16x32_bf16 v[90:93], v[184:187], v[216:219], v[90:93]
	v_mfma_f32_16x16x32_bf16 v[82:85], v[192:195], v[216:219], v[82:85]
	v_mfma_f32_16x16x32_bf16 v[74:77], v[184:187], v[224:227], v[74:77]
	v_mfma_f32_16x16x32_bf16 v[66:69], v[192:195], v[224:227], v[66:69]
	s_setprio 0
	s_barrier
	s_mov_b32 m0, s80
	v_lshl_add_u64 v[230:231], v[228:229], 0, v[132:133]
	ds_read_b128 v[196:199], v160 offset:16384
	ds_read_b128 v[200:203], v160 offset:17408
	ds_read_b128 v[204:207], v160 offset:18432
	ds_read_b128 v[208:211], v160 offset:19456
	ds_read_b128 v[212:215], v160 offset:20480
	ds_read_b128 v[216:219], v160 offset:21504
	ds_read_b128 v[220:223], v160 offset:22528
	ds_read_b128 v[224:227], v160 offset:23552
	global_load_lds_dwordx4 v[230:231], off
	v_lshl_add_u64 v[232:233], v[228:229], 0, v[136:137]
	s_mov_b32 m0, s81
	v_lshl_add_u64 v[234:235], v[228:229], 0, s[14:15]
	s_add_i32 s7, s77, s47
	global_load_lds_dwordx4 v[232:233], off
	v_lshl_add_u64 v[236:237], v[234:235], 0, v[132:133]
	s_mov_b32 m0, s7
	v_lshl_add_u64 v[234:235], v[234:235], 0, v[136:137]
	global_load_lds_dwordx4 v[236:237], off
	s_add_i32 m0, s7, 0x2000
	v_lshl_add_u64 v[236:237], v[156:157], 0, v[134:135]
	global_load_lds_dwordx4 v[234:235], off
	v_lshl_add_u64 v[234:235], v[156:157], 0, v[130:131]
	s_mov_b32 m0, s57
	s_nop 0
	global_load_lds_dwordx4 v[234:235], off
	s_mov_b32 m0, s62
	s_nop 0
	global_load_lds_dwordx4 v[236:237], off
	s_waitcnt vmcnt(8)
	s_waitcnt lgkmcnt(0)
	s_barrier
	s_setprio 1
	s_waitcnt lgkmcnt(0)
	v_mfma_f32_16x16x32_bf16 v[62:65], v[164:167], v[196:199], v[62:65]
	v_mfma_f32_16x16x32_bf16 v[54:57], v[172:175], v[196:199], v[54:57]
	v_mfma_f32_16x16x32_bf16 v[46:49], v[164:167], v[204:207], v[46:49]
	v_mfma_f32_16x16x32_bf16 v[38:41], v[172:175], v[204:207], v[38:41]
	v_mfma_f32_16x16x32_bf16 v[30:33], v[164:167], v[212:215], v[30:33]
	v_mfma_f32_16x16x32_bf16 v[22:25], v[172:175], v[212:215], v[22:25]
	v_mfma_f32_16x16x32_bf16 v[14:17], v[164:167], v[220:223], v[14:17]
	v_mfma_f32_16x16x32_bf16 v[6:9], v[172:175], v[220:223], v[6:9]
	v_mfma_f32_16x16x32_bf16 v[62:65], v[168:171], v[200:203], v[62:65]
	v_mfma_f32_16x16x32_bf16 v[54:57], v[176:179], v[200:203], v[54:57]
	v_mfma_f32_16x16x32_bf16 v[46:49], v[168:171], v[208:211], v[46:49]
	v_mfma_f32_16x16x32_bf16 v[38:41], v[176:179], v[208:211], v[38:41]
	v_mfma_f32_16x16x32_bf16 v[30:33], v[168:171], v[216:219], v[30:33]
	v_mfma_f32_16x16x32_bf16 v[22:25], v[176:179], v[216:219], v[22:25]
	v_mfma_f32_16x16x32_bf16 v[14:17], v[168:171], v[224:227], v[14:17]
	v_mfma_f32_16x16x32_bf16 v[6:9], v[176:179], v[224:227], v[6:9]
	s_setprio 0
	s_setprio 1
	v_mfma_f32_16x16x32_bf16 v[58:61], v[180:183], v[196:199], v[58:61]
	v_mfma_f32_16x16x32_bf16 v[50:53], v[188:191], v[196:199], v[50:53]
	v_mfma_f32_16x16x32_bf16 v[42:45], v[180:183], v[204:207], v[42:45]
	v_mfma_f32_16x16x32_bf16 v[34:37], v[188:191], v[204:207], v[34:37]
	v_mfma_f32_16x16x32_bf16 v[26:29], v[180:183], v[212:215], v[26:29]
	v_mfma_f32_16x16x32_bf16 v[18:21], v[188:191], v[212:215], v[18:21]
	v_mfma_f32_16x16x32_bf16 v[10:13], v[180:183], v[220:223], v[10:13]
	v_mfma_f32_16x16x32_bf16 v[2:5], v[188:191], v[220:223], v[2:5]
	v_mfma_f32_16x16x32_bf16 v[58:61], v[184:187], v[200:203], v[58:61]
	v_mfma_f32_16x16x32_bf16 v[50:53], v[192:195], v[200:203], v[50:53]
	v_mfma_f32_16x16x32_bf16 v[42:45], v[184:187], v[208:211], v[42:45]
	v_mfma_f32_16x16x32_bf16 v[34:37], v[192:195], v[208:211], v[34:37]
	v_mfma_f32_16x16x32_bf16 v[26:29], v[184:187], v[216:219], v[26:29]
	v_mfma_f32_16x16x32_bf16 v[18:21], v[192:195], v[216:219], v[18:21]
	v_mfma_f32_16x16x32_bf16 v[10:13], v[184:187], v[224:227], v[10:13]
	v_mfma_f32_16x16x32_bf16 v[2:5], v[192:195], v[224:227], v[2:5]
	s_setprio 0
	s_barrier
	s_add_i32 s7, 0, 0x18000
	v_add_u32_e32 v155, s7, v141
	s_add_i32 s55, 0, 0x1c000
	ds_read_b128 v[164:167], v155
	ds_read_b128 v[168:171], v155 offset:1024
	ds_read_b128 v[172:175], v155 offset:2048
	ds_read_b128 v[176:179], v155 offset:3072
	v_add_u32_e32 v155, s55, v141
	ds_read_b128 v[180:183], v155
	ds_read_b128 v[184:187], v155 offset:1024
	ds_read_b128 v[188:191], v155 offset:2048
	ds_read_b128 v[192:195], v155 offset:3072
	v_lshl_add_u64 v[156:157], v[156:157], 0, s[14:15]
	s_mov_b32 m0, s63
	v_lshl_add_u64 v[238:239], v[156:157], 0, v[130:131]
	ds_read_b128 v[196:199], v160 offset:32768
	ds_read_b128 v[200:203], v160 offset:33792
	ds_read_b128 v[204:207], v160 offset:34816
	ds_read_b128 v[208:211], v160 offset:35840
	ds_read_b128 v[212:215], v160 offset:36864
	ds_read_b128 v[216:219], v160 offset:37888
	ds_read_b128 v[220:223], v160 offset:38912
	ds_read_b128 v[224:227], v160 offset:39936
	global_load_lds_dwordx4 v[238:239], off
	v_lshl_add_u64 v[156:157], v[156:157], 0, v[134:135]
	s_mov_b32 m0, s64
	s_nop 0
	global_load_lds_dwordx4 v[156:157], off
	s_waitcnt vmcnt(8)
	s_waitcnt lgkmcnt(0)
	s_barrier
	s_setprio 1
	s_waitcnt lgkmcnt(0)
	v_mfma_f32_16x16x32_bf16 v[122:125], v[164:167], v[196:199], v[122:125]
	v_mfma_f32_16x16x32_bf16 v[118:121], v[172:175], v[196:199], v[118:121]
	v_mfma_f32_16x16x32_bf16 v[110:113], v[164:167], v[204:207], v[110:113]
	v_mfma_f32_16x16x32_bf16 v[102:105], v[172:175], v[204:207], v[102:105]
	v_mfma_f32_16x16x32_bf16 v[94:97], v[164:167], v[212:215], v[94:97]
	v_mfma_f32_16x16x32_bf16 v[86:89], v[172:175], v[212:215], v[86:89]
	v_mfma_f32_16x16x32_bf16 v[78:81], v[164:167], v[220:223], v[78:81]
	v_mfma_f32_16x16x32_bf16 v[70:73], v[172:175], v[220:223], v[70:73]
	v_mfma_f32_16x16x32_bf16 v[122:125], v[168:171], v[200:203], v[122:125]
	v_mfma_f32_16x16x32_bf16 v[118:121], v[176:179], v[200:203], v[118:121]
	v_mfma_f32_16x16x32_bf16 v[110:113], v[168:171], v[208:211], v[110:113]
	v_mfma_f32_16x16x32_bf16 v[102:105], v[176:179], v[208:211], v[102:105]
	v_mfma_f32_16x16x32_bf16 v[94:97], v[168:171], v[216:219], v[94:97]
	v_mfma_f32_16x16x32_bf16 v[86:89], v[176:179], v[216:219], v[86:89]
	v_mfma_f32_16x16x32_bf16 v[78:81], v[168:171], v[224:227], v[78:81]
	v_mfma_f32_16x16x32_bf16 v[70:73], v[176:179], v[224:227], v[70:73]
	s_setprio 0
	s_setprio 1
	v_mfma_f32_16x16x32_bf16 v[126:129], v[180:183], v[196:199], v[126:129]
	v_mfma_f32_16x16x32_bf16 v[114:117], v[188:191], v[196:199], v[114:117]
	v_mfma_f32_16x16x32_bf16 v[106:109], v[180:183], v[204:207], v[106:109]
	v_mfma_f32_16x16x32_bf16 v[98:101], v[188:191], v[204:207], v[98:101]
	v_mfma_f32_16x16x32_bf16 v[90:93], v[180:183], v[212:215], v[90:93]
	v_mfma_f32_16x16x32_bf16 v[82:85], v[188:191], v[212:215], v[82:85]
	v_mfma_f32_16x16x32_bf16 v[74:77], v[180:183], v[220:223], v[74:77]
	v_mfma_f32_16x16x32_bf16 v[66:69], v[188:191], v[220:223], v[66:69]
	v_mfma_f32_16x16x32_bf16 v[126:129], v[184:187], v[200:203], v[126:129]
	v_mfma_f32_16x16x32_bf16 v[114:117], v[192:195], v[200:203], v[114:117]
	v_mfma_f32_16x16x32_bf16 v[106:109], v[184:187], v[208:211], v[106:109]
	v_mfma_f32_16x16x32_bf16 v[98:101], v[192:195], v[208:211], v[98:101]
	v_mfma_f32_16x16x32_bf16 v[90:93], v[184:187], v[216:219], v[90:93]
	v_mfma_f32_16x16x32_bf16 v[82:85], v[192:195], v[216:219], v[82:85]
	v_mfma_f32_16x16x32_bf16 v[74:77], v[184:187], v[224:227], v[74:77]
	v_mfma_f32_16x16x32_bf16 v[66:69], v[192:195], v[224:227], v[66:69]
	s_setprio 0
	s_barrier
	s_add_i32 s7, s7, s47
	v_lshl_add_u64 v[156:157], v[230:231], 0, s[20:21]
	s_mov_b32 m0, s7
	ds_read_b128 v[196:199], v160 offset:49152
	ds_read_b128 v[200:203], v160 offset:50176
	ds_read_b128 v[204:207], v160 offset:51200
	ds_read_b128 v[208:211], v160 offset:52224
	ds_read_b128 v[212:215], v160 offset:53248
	ds_read_b128 v[216:219], v160 offset:54272
	ds_read_b128 v[220:223], v160 offset:55296
	ds_read_b128 v[224:227], v160 offset:56320
	global_load_lds_dwordx4 v[156:157], off
	v_lshl_add_u64 v[156:157], v[232:233], 0, s[20:21]
	s_add_i32 m0, s7, 0x2000
	s_add_i32 s7, s55, s47
	global_load_lds_dwordx4 v[156:157], off
	v_lshl_add_u64 v[156:157], v[228:229], 0, s[22:23]
	v_lshl_add_u64 v[228:229], v[156:157], 0, v[132:133]
	s_mov_b32 m0, s7
	v_lshl_add_u64 v[156:157], v[156:157], 0, v[136:137]
	global_load_lds_dwordx4 v[228:229], off
	s_add_i32 m0, s7, 0x2000
	s_nop 0
	global_load_lds_dwordx4 v[156:157], off
	v_lshl_add_u64 v[156:157], v[234:235], 0, s[20:21]
	s_mov_b32 m0, s65
	s_nop 0
	global_load_lds_dwordx4 v[156:157], off
	v_lshl_add_u64 v[156:157], v[236:237], 0, s[20:21]
	s_mov_b32 m0, s66
	s_nop 0
	global_load_lds_dwordx4 v[156:157], off
	s_waitcnt vmcnt(8)
	s_waitcnt lgkmcnt(0)
	s_barrier
	s_setprio 1
	s_waitcnt lgkmcnt(0)
	v_mfma_f32_16x16x32_bf16 v[62:65], v[164:167], v[196:199], v[62:65]
	v_mfma_f32_16x16x32_bf16 v[54:57], v[172:175], v[196:199], v[54:57]
	v_mfma_f32_16x16x32_bf16 v[46:49], v[164:167], v[204:207], v[46:49]
	v_mfma_f32_16x16x32_bf16 v[38:41], v[172:175], v[204:207], v[38:41]
	v_mfma_f32_16x16x32_bf16 v[30:33], v[164:167], v[212:215], v[30:33]
	v_mfma_f32_16x16x32_bf16 v[22:25], v[172:175], v[212:215], v[22:25]
	v_mfma_f32_16x16x32_bf16 v[14:17], v[164:167], v[220:223], v[14:17]
	v_mfma_f32_16x16x32_bf16 v[6:9], v[172:175], v[220:223], v[6:9]
	v_mfma_f32_16x16x32_bf16 v[62:65], v[168:171], v[200:203], v[62:65]
	v_mfma_f32_16x16x32_bf16 v[54:57], v[176:179], v[200:203], v[54:57]
	v_mfma_f32_16x16x32_bf16 v[46:49], v[168:171], v[208:211], v[46:49]
	v_mfma_f32_16x16x32_bf16 v[38:41], v[176:179], v[208:211], v[38:41]
	v_mfma_f32_16x16x32_bf16 v[30:33], v[168:171], v[216:219], v[30:33]
	v_mfma_f32_16x16x32_bf16 v[22:25], v[176:179], v[216:219], v[22:25]
	v_mfma_f32_16x16x32_bf16 v[14:17], v[168:171], v[224:227], v[14:17]
	v_mfma_f32_16x16x32_bf16 v[6:9], v[176:179], v[224:227], v[6:9]
	s_setprio 0
	s_setprio 1
	v_mfma_f32_16x16x32_bf16 v[58:61], v[180:183], v[196:199], v[58:61]
	v_mfma_f32_16x16x32_bf16 v[50:53], v[188:191], v[196:199], v[50:53]
	v_mfma_f32_16x16x32_bf16 v[42:45], v[180:183], v[204:207], v[42:45]
	v_mfma_f32_16x16x32_bf16 v[34:37], v[188:191], v[204:207], v[34:37]
	v_mfma_f32_16x16x32_bf16 v[26:29], v[180:183], v[212:215], v[26:29]
	v_mfma_f32_16x16x32_bf16 v[18:21], v[188:191], v[212:215], v[18:21]
	v_mfma_f32_16x16x32_bf16 v[10:13], v[180:183], v[220:223], v[10:13]
	v_mfma_f32_16x16x32_bf16 v[2:5], v[188:191], v[220:223], v[2:5]
	v_mfma_f32_16x16x32_bf16 v[58:61], v[184:187], v[200:203], v[58:61]
	v_mfma_f32_16x16x32_bf16 v[50:53], v[192:195], v[200:203], v[50:53]
	v_mfma_f32_16x16x32_bf16 v[42:45], v[184:187], v[208:211], v[42:45]
	v_mfma_f32_16x16x32_bf16 v[34:37], v[192:195], v[208:211], v[34:37]
	v_mfma_f32_16x16x32_bf16 v[26:29], v[184:187], v[216:219], v[26:29]
	v_mfma_f32_16x16x32_bf16 v[18:21], v[192:195], v[216:219], v[18:21]
	v_mfma_f32_16x16x32_bf16 v[10:13], v[184:187], v[224:227], v[10:13]
	v_mfma_f32_16x16x32_bf16 v[2:5], v[192:195], v[224:227], v[2:5]
	s_setprio 0
	s_barrier
	v_cmp_ge_i32_e32 vcc, s51, v138
	v_lshl_add_u64 v[150:151], v[150:151], 0, s[28:29]
	v_lshl_add_u64 v[152:153], v[152:153], 0, s[28:29]
	s_mov_b32 s7, s51
	s_cbranch_vccz .LBB0_171
.Lmy_kexit_0:
	s_and_b64 vcc, exec, s[24:25]
	s_cbranch_vccz .LBB0_174
.LBB0_173:
	s_barrier

.LBB0_308:
	v_cmp_gt_i32_e32 vcc, 1, v141
	s_cbranch_vccnz .LBB0_370
	v_lshl_add_u64 v[154:155], v[2:3], 0, s[28:29]
	v_add_u32_e32 v138, -2, v141
	s_mov_b32 s8, 0
	v_add_u32_e32 v146, s69, v160
	ds_read_b128 v[166:169], v146
	ds_read_b128 v[170:173], v146 offset:1024
	ds_read_b128 v[174:177], v146 offset:2048
	ds_read_b128 v[178:181], v146 offset:3072
	v_add_u32_e32 v146, s72, v160
	ds_read_b128 v[182:185], v146
	ds_read_b128 v[186:189], v146 offset:1024
	ds_read_b128 v[190:193], v146 offset:2048
	ds_read_b128 v[194:197], v146 offset:3072
	v_lshl_add_u64 v[156:157], v[152:153], 0, s[28:29]
	v_cmp_eq_u32_e32 vcc, s8, v138
	s_add_i32 s9, s8, 2
	s_nop 0
	v_cndmask_b32_e32 v159, v157, v149, vcc
	v_cndmask_b32_e32 v158, v156, v148, vcc
	v_cndmask_b32_e32 v231, v155, v151, vcc
	v_cndmask_b32_e32 v230, v154, v150, vcc
	v_lshl_add_u64 v[232:233], v[152:153], 0, v[144:145]
	s_add_i32 m0, s55, 0xc000
	ds_read_b128 v[198:201], v163
	ds_read_b128 v[202:205], v163 offset:1024
	ds_read_b128 v[206:209], v163 offset:2048
	ds_read_b128 v[210:213], v163 offset:3072
	ds_read_b128 v[214:217], v163 offset:4096
	ds_read_b128 v[218:221], v163 offset:5120
	ds_read_b128 v[222:225], v163 offset:6144
	ds_read_b128 v[226:229], v163 offset:7168
	global_load_lds_dwordx4 v[232:233], off
	v_lshl_add_u64 v[152:153], v[152:153], 0, v[142:143]
	s_add_i32 m0, s55, 0xe000
	s_nop 0
	global_load_lds_dwordx4 v[152:153], off
	s_waitcnt vmcnt(8)
	s_waitcnt lgkmcnt(0)
	s_barrier
	s_setprio 1
	s_waitcnt lgkmcnt(0)
	v_mfma_f32_16x16x32_bf16 v[122:125], v[166:169], v[198:201], 0
	v_mfma_f32_16x16x32_bf16 v[118:121], v[174:177], v[198:201], 0
	v_mfma_f32_16x16x32_bf16 v[110:113], v[166:169], v[206:209], 0
	v_mfma_f32_16x16x32_bf16 v[102:105], v[174:177], v[206:209], 0
	v_mfma_f32_16x16x32_bf16 v[94:97], v[166:169], v[214:217], 0
	v_mfma_f32_16x16x32_bf16 v[86:89], v[174:177], v[214:217], 0
	v_mfma_f32_16x16x32_bf16 v[78:81], v[166:169], v[222:225], 0
	v_mfma_f32_16x16x32_bf16 v[70:73], v[174:177], v[222:225], 0
	v_mfma_f32_16x16x32_bf16 v[122:125], v[170:173], v[202:205], v[122:125]
	v_mfma_f32_16x16x32_bf16 v[118:121], v[178:181], v[202:205], v[118:121]
	v_mfma_f32_16x16x32_bf16 v[110:113], v[170:173], v[210:213], v[110:113]
	v_mfma_f32_16x16x32_bf16 v[102:105], v[178:181], v[210:213], v[102:105]
	v_mfma_f32_16x16x32_bf16 v[94:97], v[170:173], v[218:221], v[94:97]
	v_mfma_f32_16x16x32_bf16 v[86:89], v[178:181], v[218:221], v[86:89]
	v_mfma_f32_16x16x32_bf16 v[78:81], v[170:173], v[226:229], v[78:81]
	v_mfma_f32_16x16x32_bf16 v[70:73], v[178:181], v[226:229], v[70:73]
	s_setprio 0
	s_setprio 1
	v_mfma_f32_16x16x32_bf16 v[126:129], v[182:185], v[198:201], 0
	v_mfma_f32_16x16x32_bf16 v[114:117], v[190:193], v[198:201], 0
	v_mfma_f32_16x16x32_bf16 v[106:109], v[182:185], v[206:209], 0
	v_mfma_f32_16x16x32_bf16 v[98:101], v[190:193], v[206:209], 0
	v_mfma_f32_16x16x32_bf16 v[90:93], v[182:185], v[214:217], 0
	v_mfma_f32_16x16x32_bf16 v[82:85], v[190:193], v[214:217], 0
	v_mfma_f32_16x16x32_bf16 v[74:77], v[182:185], v[222:225], 0
	v_mfma_f32_16x16x32_bf16 v[66:69], v[190:193], v[222:225], 0
	v_mfma_f32_16x16x32_bf16 v[126:129], v[186:189], v[202:205], v[126:129]
	v_mfma_f32_16x16x32_bf16 v[114:117], v[194:197], v[202:205], v[114:117]
	v_mfma_f32_16x16x32_bf16 v[106:109], v[186:189], v[210:213], v[106:109]
	v_mfma_f32_16x16x32_bf16 v[98:101], v[194:197], v[210:213], v[98:101]
	v_mfma_f32_16x16x32_bf16 v[90:93], v[186:189], v[218:221], v[90:93]
	v_mfma_f32_16x16x32_bf16 v[82:85], v[194:197], v[218:221], v[82:85]
	v_mfma_f32_16x16x32_bf16 v[74:77], v[186:189], v[226:229], v[74:77]
	v_mfma_f32_16x16x32_bf16 v[66:69], v[194:197], v[226:229], v[66:69]
	s_setprio 0
	s_barrier
	s_add_i32 s8, s69, s54
	v_lshl_add_u64 v[152:153], v[230:231], 0, v[132:133]
	s_mov_b32 m0, s8
	ds_read_b128 v[198:201], v163 offset:16384
	ds_read_b128 v[202:205], v163 offset:17408
	ds_read_b128 v[206:209], v163 offset:18432
	ds_read_b128 v[210:213], v163 offset:19456
	ds_read_b128 v[214:217], v163 offset:20480
	ds_read_b128 v[218:221], v163 offset:21504
	ds_read_b128 v[222:225], v163 offset:22528
	ds_read_b128 v[226:229], v163 offset:23552
	global_load_lds_dwordx4 v[152:153], off
	v_lshl_add_u64 v[232:233], v[230:231], 0, v[136:137]
	s_add_i32 m0, s8, 0x2000
	v_lshl_add_u64 v[234:235], v[230:231], 0, s[16:17]
	s_add_i32 s8, s72, s54
	global_load_lds_dwordx4 v[232:233], off
	v_lshl_add_u64 v[236:237], v[234:235], 0, v[132:133]
	s_mov_b32 m0, s8
	v_lshl_add_u64 v[234:235], v[234:235], 0, v[136:137]
	global_load_lds_dwordx4 v[236:237], off
	s_add_i32 m0, s8, 0x2000
	v_lshl_add_u64 v[236:237], v[158:159], 0, v[134:135]
	global_load_lds_dwordx4 v[234:235], off
	v_lshl_add_u64 v[234:235], v[158:159], 0, v[130:131]
	s_mov_b32 m0, s55
	s_nop 0
	global_load_lds_dwordx4 v[234:235], off
	s_mov_b32 m0, s56
	s_nop 0
	global_load_lds_dwordx4 v[236:237], off
	s_waitcnt vmcnt(8)
	s_waitcnt lgkmcnt(0)
	s_barrier
	s_setprio 1
	s_waitcnt lgkmcnt(0)
	v_mfma_f32_16x16x32_bf16 v[62:65], v[166:169], v[198:201], 0
	v_mfma_f32_16x16x32_bf16 v[54:57], v[174:177], v[198:201], 0
	v_mfma_f32_16x16x32_bf16 v[46:49], v[166:169], v[206:209], 0
	v_mfma_f32_16x16x32_bf16 v[38:41], v[174:177], v[206:209], 0
	v_mfma_f32_16x16x32_bf16 v[30:33], v[166:169], v[214:217], 0
	v_mfma_f32_16x16x32_bf16 v[22:25], v[174:177], v[214:217], 0
	v_mfma_f32_16x16x32_bf16 v[14:17], v[166:169], v[222:225], 0
	v_mfma_f32_16x16x32_bf16 v[6:9], v[174:177], v[222:225], 0
	v_mfma_f32_16x16x32_bf16 v[62:65], v[170:173], v[202:205], v[62:65]
	v_mfma_f32_16x16x32_bf16 v[54:57], v[178:181], v[202:205], v[54:57]
	v_mfma_f32_16x16x32_bf16 v[46:49], v[170:173], v[210:213], v[46:49]
	v_mfma_f32_16x16x32_bf16 v[38:41], v[178:181], v[210:213], v[38:41]
	v_mfma_f32_16x16x32_bf16 v[30:33], v[170:173], v[218:221], v[30:33]
	v_mfma_f32_16x16x32_bf16 v[22:25], v[178:181], v[218:221], v[22:25]
	v_mfma_f32_16x16x32_bf16 v[14:17], v[170:173], v[226:229], v[14:17]
	v_mfma_f32_16x16x32_bf16 v[6:9], v[178:181], v[226:229], v[6:9]
	s_setprio 0
	s_setprio 1
	v_mfma_f32_16x16x32_bf16 v[58:61], v[182:185], v[198:201], 0
	v_mfma_f32_16x16x32_bf16 v[50:53], v[190:193], v[198:201], 0
	v_mfma_f32_16x16x32_bf16 v[42:45], v[182:185], v[206:209], 0
	v_mfma_f32_16x16x32_bf16 v[34:37], v[190:193], v[206:209], 0
	v_mfma_f32_16x16x32_bf16 v[26:29], v[182:185], v[214:217], 0
	v_mfma_f32_16x16x32_bf16 v[18:21], v[190:193], v[214:217], 0
	v_mfma_f32_16x16x32_bf16 v[10:13], v[182:185], v[222:225], 0
	v_mfma_f32_16x16x32_bf16 v[2:5], v[190:193], v[222:225], 0
	v_mfma_f32_16x16x32_bf16 v[58:61], v[186:189], v[202:205], v[58:61]
	v_mfma_f32_16x16x32_bf16 v[50:53], v[194:197], v[202:205], v[50:53]
	v_mfma_f32_16x16x32_bf16 v[42:45], v[186:189], v[210:213], v[42:45]
	v_mfma_f32_16x16x32_bf16 v[34:37], v[194:197], v[210:213], v[34:37]
	v_mfma_f32_16x16x32_bf16 v[26:29], v[186:189], v[218:221], v[26:29]
	v_mfma_f32_16x16x32_bf16 v[18:21], v[194:197], v[218:221], v[18:21]
	v_mfma_f32_16x16x32_bf16 v[10:13], v[186:189], v[226:229], v[10:13]
	v_mfma_f32_16x16x32_bf16 v[2:5], v[194:197], v[226:229], v[2:5]
	s_setprio 0
	s_barrier
	s_add_i32 s8, 0, 0x18000
	v_add_u32_e32 v146, s8, v160
	s_add_i32 s50, 0, 0x1c000
	ds_read_b128 v[166:169], v146
	ds_read_b128 v[170:173], v146 offset:1024
	ds_read_b128 v[174:177], v146 offset:2048
	ds_read_b128 v[178:181], v146 offset:3072
	v_add_u32_e32 v146, s50, v160
	ds_read_b128 v[182:185], v146
	ds_read_b128 v[186:189], v146 offset:1024
	ds_read_b128 v[190:193], v146 offset:2048
	ds_read_b128 v[194:197], v146 offset:3072
	v_lshl_add_u64 v[158:159], v[158:159], 0, s[16:17]
	s_mov_b32 m0, s57
	v_lshl_add_u64 v[238:239], v[158:159], 0, v[130:131]
	ds_read_b128 v[198:201], v163 offset:32768
	ds_read_b128 v[202:205], v163 offset:33792
	ds_read_b128 v[206:209], v163 offset:34816
	ds_read_b128 v[210:213], v163 offset:35840
	ds_read_b128 v[214:217], v163 offset:36864
	ds_read_b128 v[218:221], v163 offset:37888
	ds_read_b128 v[222:225], v163 offset:38912
	ds_read_b128 v[226:229], v163 offset:39936
	global_load_lds_dwordx4 v[238:239], off
	v_lshl_add_u64 v[158:159], v[158:159], 0, v[134:135]
	s_mov_b32 m0, s58
	s_nop 0
	global_load_lds_dwordx4 v[158:159], off
	s_waitcnt vmcnt(8)
	s_waitcnt lgkmcnt(0)
	s_barrier
	s_setprio 1
	s_waitcnt lgkmcnt(0)
	v_mfma_f32_16x16x32_bf16 v[122:125], v[166:169], v[198:201], v[122:125]
	v_mfma_f32_16x16x32_bf16 v[118:121], v[174:177], v[198:201], v[118:121]
	v_mfma_f32_16x16x32_bf16 v[110:113], v[166:169], v[206:209], v[110:113]
	v_mfma_f32_16x16x32_bf16 v[102:105], v[174:177], v[206:209], v[102:105]
	v_mfma_f32_16x16x32_bf16 v[94:97], v[166:169], v[214:217], v[94:97]
	v_mfma_f32_16x16x32_bf16 v[86:89], v[174:177], v[214:217], v[86:89]
	v_mfma_f32_16x16x32_bf16 v[78:81], v[166:169], v[222:225], v[78:81]
	v_mfma_f32_16x16x32_bf16 v[70:73], v[174:177], v[222:225], v[70:73]
	v_mfma_f32_16x16x32_bf16 v[122:125], v[170:173], v[202:205], v[122:125]
	v_mfma_f32_16x16x32_bf16 v[118:121], v[178:181], v[202:205], v[118:121]
	v_mfma_f32_16x16x32_bf16 v[110:113], v[170:173], v[210:213], v[110:113]
	v_mfma_f32_16x16x32_bf16 v[102:105], v[178:181], v[210:213], v[102:105]
	v_mfma_f32_16x16x32_bf16 v[94:97], v[170:173], v[218:221], v[94:97]
	v_mfma_f32_16x16x32_bf16 v[86:89], v[178:181], v[218:221], v[86:89]
	v_mfma_f32_16x16x32_bf16 v[78:81], v[170:173], v[226:229], v[78:81]
	v_mfma_f32_16x16x32_bf16 v[70:73], v[178:181], v[226:229], v[70:73]
	s_setprio 0
	s_setprio 1
	v_mfma_f32_16x16x32_bf16 v[126:129], v[182:185], v[198:201], v[126:129]
	v_mfma_f32_16x16x32_bf16 v[114:117], v[190:193], v[198:201], v[114:117]
	v_mfma_f32_16x16x32_bf16 v[106:109], v[182:185], v[206:209], v[106:109]
	v_mfma_f32_16x16x32_bf16 v[98:101], v[190:193], v[206:209], v[98:101]
	v_mfma_f32_16x16x32_bf16 v[90:93], v[182:185], v[214:217], v[90:93]
	v_mfma_f32_16x16x32_bf16 v[82:85], v[190:193], v[214:217], v[82:85]
	v_mfma_f32_16x16x32_bf16 v[74:77], v[182:185], v[222:225], v[74:77]
	v_mfma_f32_16x16x32_bf16 v[66:69], v[190:193], v[222:225], v[66:69]
	v_mfma_f32_16x16x32_bf16 v[126:129], v[186:189], v[202:205], v[126:129]
	v_mfma_f32_16x16x32_bf16 v[114:117], v[194:197], v[202:205], v[114:117]
	v_mfma_f32_16x16x32_bf16 v[106:109], v[186:189], v[210:213], v[106:109]
	v_mfma_f32_16x16x32_bf16 v[98:101], v[194:197], v[210:213], v[98:101]
	v_mfma_f32_16x16x32_bf16 v[90:93], v[186:189], v[218:221], v[90:93]
	v_mfma_f32_16x16x32_bf16 v[82:85], v[194:197], v[218:221], v[82:85]
	v_mfma_f32_16x16x32_bf16 v[74:77], v[186:189], v[226:229], v[74:77]
	v_mfma_f32_16x16x32_bf16 v[66:69], v[194:197], v[226:229], v[66:69]
	s_setprio 0
	s_barrier
	s_add_i32 s8, s8, s54
	v_lshl_add_u64 v[152:153], v[152:153], 0, s[20:21]
	s_mov_b32 m0, s8
	ds_read_b128 v[198:201], v163 offset:49152
	ds_read_b128 v[202:205], v163 offset:50176
	ds_read_b128 v[206:209], v163 offset:51200
	ds_read_b128 v[210:213], v163 offset:52224
	ds_read_b128 v[214:217], v163 offset:53248
	ds_read_b128 v[218:221], v163 offset:54272
	ds_read_b128 v[222:225], v163 offset:55296
	ds_read_b128 v[226:229], v163 offset:56320
	global_load_lds_dwordx4 v[152:153], off
	v_lshl_add_u64 v[152:153], v[232:233], 0, s[20:21]
	s_add_i32 m0, s8, 0x2000
	s_add_i32 s8, s50, s54
	global_load_lds_dwordx4 v[152:153], off
	v_lshl_add_u64 v[152:153], v[230:231], 0, s[22:23]
	v_lshl_add_u64 v[158:159], v[152:153], 0, v[132:133]
	s_mov_b32 m0, s8
	v_lshl_add_u64 v[152:153], v[152:153], 0, v[136:137]
	global_load_lds_dwordx4 v[158:159], off
	s_add_i32 m0, s8, 0x2000
	s_nop 0
	global_load_lds_dwordx4 v[152:153], off
	v_lshl_add_u64 v[152:153], v[234:235], 0, s[20:21]
	s_mov_b32 m0, s64
	s_nop 0
	global_load_lds_dwordx4 v[152:153], off
	v_lshl_add_u64 v[152:153], v[236:237], 0, s[20:21]
	s_mov_b32 m0, s65
	s_nop 0
	global_load_lds_dwordx4 v[152:153], off
	s_waitcnt vmcnt(8)
	s_waitcnt lgkmcnt(0)
	s_barrier
	s_setprio 1
	s_waitcnt lgkmcnt(0)
	v_mfma_f32_16x16x32_bf16 v[62:65], v[166:169], v[198:201], v[62:65]
	v_mfma_f32_16x16x32_bf16 v[54:57], v[174:177], v[198:201], v[54:57]
	v_mfma_f32_16x16x32_bf16 v[46:49], v[166:169], v[206:209], v[46:49]
	v_mfma_f32_16x16x32_bf16 v[38:41], v[174:177], v[206:209], v[38:41]
	v_mfma_f32_16x16x32_bf16 v[30:33], v[166:169], v[214:217], v[30:33]
	v_mfma_f32_16x16x32_bf16 v[22:25], v[174:177], v[214:217], v[22:25]
	v_mfma_f32_16x16x32_bf16 v[14:17], v[166:169], v[222:225], v[14:17]
	v_mfma_f32_16x16x32_bf16 v[6:9], v[174:177], v[222:225], v[6:9]
	v_mfma_f32_16x16x32_bf16 v[62:65], v[170:173], v[202:205], v[62:65]
	v_mfma_f32_16x16x32_bf16 v[54:57], v[178:181], v[202:205], v[54:57]
	v_mfma_f32_16x16x32_bf16 v[46:49], v[170:173], v[210:213], v[46:49]
	v_mfma_f32_16x16x32_bf16 v[38:41], v[178:181], v[210:213], v[38:41]
	v_mfma_f32_16x16x32_bf16 v[30:33], v[170:173], v[218:221], v[30:33]
	v_mfma_f32_16x16x32_bf16 v[22:25], v[178:181], v[218:221], v[22:25]
	v_mfma_f32_16x16x32_bf16 v[14:17], v[170:173], v[226:229], v[14:17]
	v_mfma_f32_16x16x32_bf16 v[6:9], v[178:181], v[226:229], v[6:9]
	s_setprio 0
	s_setprio 1
	v_mfma_f32_16x16x32_bf16 v[58:61], v[182:185], v[198:201], v[58:61]
	v_mfma_f32_16x16x32_bf16 v[50:53], v[190:193], v[198:201], v[50:53]
	v_mfma_f32_16x16x32_bf16 v[42:45], v[182:185], v[206:209], v[42:45]
	v_mfma_f32_16x16x32_bf16 v[34:37], v[190:193], v[206:209], v[34:37]
	v_mfma_f32_16x16x32_bf16 v[26:29], v[182:185], v[214:217], v[26:29]
	v_mfma_f32_16x16x32_bf16 v[18:21], v[190:193], v[214:217], v[18:21]
	v_mfma_f32_16x16x32_bf16 v[10:13], v[182:185], v[222:225], v[10:13]
	v_mfma_f32_16x16x32_bf16 v[2:5], v[190:193], v[222:225], v[2:5]
	v_mfma_f32_16x16x32_bf16 v[58:61], v[186:189], v[202:205], v[58:61]
	v_mfma_f32_16x16x32_bf16 v[50:53], v[194:197], v[202:205], v[50:53]
	v_mfma_f32_16x16x32_bf16 v[42:45], v[186:189], v[210:213], v[42:45]
	v_mfma_f32_16x16x32_bf16 v[34:37], v[194:197], v[210:213], v[34:37]
	v_mfma_f32_16x16x32_bf16 v[26:29], v[186:189], v[218:221], v[26:29]
	v_mfma_f32_16x16x32_bf16 v[18:21], v[194:197], v[218:221], v[18:21]
	v_mfma_f32_16x16x32_bf16 v[10:13], v[186:189], v[226:229], v[10:13]
	v_mfma_f32_16x16x32_bf16 v[2:5], v[194:197], v[226:229], v[2:5]
	s_setprio 0
	s_barrier
	v_cmp_ge_i32_e32 vcc, s9, v141
	v_lshl_add_u64 v[154:155], v[154:155], 0, s[28:29]
	v_mov_b64_e32 v[152:153], v[156:157]
	s_mov_b32 s8, s9
	s_cbranch_vccnz .Lmy_kexit_1
.LBB0_310:
	v_add_u32_e32 v146, s69, v160
	ds_read_b128 v[166:169], v146
	ds_read_b128 v[170:173], v146 offset:1024
	ds_read_b128 v[174:177], v146 offset:2048
	ds_read_b128 v[178:181], v146 offset:3072
	v_add_u32_e32 v146, s72, v160
	ds_read_b128 v[182:185], v146
	ds_read_b128 v[186:189], v146 offset:1024
	ds_read_b128 v[190:193], v146 offset:2048
	ds_read_b128 v[194:197], v146 offset:3072
	v_lshl_add_u64 v[156:157], v[152:153], 0, s[28:29]
	v_cmp_eq_u32_e32 vcc, s8, v138
	s_add_i32 s9, s8, 2
	s_nop 0
	v_cndmask_b32_e32 v159, v157, v149, vcc
	v_cndmask_b32_e32 v158, v156, v148, vcc
	v_cndmask_b32_e32 v231, v155, v151, vcc
	v_cndmask_b32_e32 v230, v154, v150, vcc
	v_lshl_add_u64 v[232:233], v[152:153], 0, v[144:145]
	s_add_i32 m0, s55, 0xc000
	ds_read_b128 v[198:201], v163
	ds_read_b128 v[202:205], v163 offset:1024
	ds_read_b128 v[206:209], v163 offset:2048
	ds_read_b128 v[210:213], v163 offset:3072
	ds_read_b128 v[214:217], v163 offset:4096
	ds_read_b128 v[218:221], v163 offset:5120
	ds_read_b128 v[222:225], v163 offset:6144
	ds_read_b128 v[226:229], v163 offset:7168
	global_load_lds_dwordx4 v[232:233], off
	v_lshl_add_u64 v[152:153], v[152:153], 0, v[142:143]
	s_add_i32 m0, s55, 0xe000
	s_nop 0
	global_load_lds_dwordx4 v[152:153], off
	s_waitcnt vmcnt(8)
	s_waitcnt lgkmcnt(0)
	s_barrier
	s_setprio 1
	s_waitcnt lgkmcnt(0)
	v_mfma_f32_16x16x32_bf16 v[122:125], v[166:169], v[198:201], v[122:125]
	v_mfma_f32_16x16x32_bf16 v[118:121], v[174:177], v[198:201], v[118:121]
	v_mfma_f32_16x16x32_bf16 v[110:113], v[166:169], v[206:209], v[110:113]
	v_mfma_f32_16x16x32_bf16 v[102:105], v[174:177], v[206:209], v[102:105]
	v_mfma_f32_16x16x32_bf16 v[94:97], v[166:169], v[214:217], v[94:97]
	v_mfma_f32_16x16x32_bf16 v[86:89], v[174:177], v[214:217], v[86:89]
	v_mfma_f32_16x16x32_bf16 v[78:81], v[166:169], v[222:225], v[78:81]
	v_mfma_f32_16x16x32_bf16 v[70:73], v[174:177], v[222:225], v[70:73]
	v_mfma_f32_16x16x32_bf16 v[122:125], v[170:173], v[202:205], v[122:125]
	v_mfma_f32_16x16x32_bf16 v[118:121], v[178:181], v[202:205], v[118:121]
	v_mfma_f32_16x16x32_bf16 v[110:113], v[170:173], v[210:213], v[110:113]
	v_mfma_f32_16x16x32_bf16 v[102:105], v[178:181], v[210:213], v[102:105]
	v_mfma_f32_16x16x32_bf16 v[94:97], v[170:173], v[218:221], v[94:97]
	v_mfma_f32_16x16x32_bf16 v[86:89], v[178:181], v[218:221], v[86:89]
	v_mfma_f32_16x16x32_bf16 v[78:81], v[170:173], v[226:229], v[78:81]
	v_mfma_f32_16x16x32_bf16 v[70:73], v[178:181], v[226:229], v[70:73]
	s_setprio 0
	s_setprio 1
	v_mfma_f32_16x16x32_bf16 v[126:129], v[182:185], v[198:201], v[126:129]
	v_mfma_f32_16x16x32_bf16 v[114:117], v[190:193], v[198:201], v[114:117]
	v_mfma_f32_16x16x32_bf16 v[106:109], v[182:185], v[206:209], v[106:109]
	v_mfma_f32_16x16x32_bf16 v[98:101], v[190:193], v[206:209], v[98:101]
	v_mfma_f32_16x16x32_bf16 v[90:93], v[182:185], v[214:217], v[90:93]
	v_mfma_f32_16x16x32_bf16 v[82:85], v[190:193], v[214:217], v[82:85]
	v_mfma_f32_16x16x32_bf16 v[74:77], v[182:185], v[222:225], v[74:77]
	v_mfma_f32_16x16x32_bf16 v[66:69], v[190:193], v[222:225], v[66:69]
	v_mfma_f32_16x16x32_bf16 v[126:129], v[186:189], v[202:205], v[126:129]
	v_mfma_f32_16x16x32_bf16 v[114:117], v[194:197], v[202:205], v[114:117]
	v_mfma_f32_16x16x32_bf16 v[106:109], v[186:189], v[210:213], v[106:109]
	v_mfma_f32_16x16x32_bf16 v[98:101], v[194:197], v[210:213], v[98:101]
	v_mfma_f32_16x16x32_bf16 v[90:93], v[186:189], v[218:221], v[90:93]
	v_mfma_f32_16x16x32_bf16 v[82:85], v[194:197], v[218:221], v[82:85]
	v_mfma_f32_16x16x32_bf16 v[74:77], v[186:189], v[226:229], v[74:77]
	v_mfma_f32_16x16x32_bf16 v[66:69], v[194:197], v[226:229], v[66:69]
	s_setprio 0
	s_barrier
	s_add_i32 s8, s69, s54
	v_lshl_add_u64 v[152:153], v[230:231], 0, v[132:133]
	s_mov_b32 m0, s8
	ds_read_b128 v[198:201], v163 offset:16384
	ds_read_b128 v[202:205], v163 offset:17408
	ds_read_b128 v[206:209], v163 offset:18432
	ds_read_b128 v[210:213], v163 offset:19456
	ds_read_b128 v[214:217], v163 offset:20480
	ds_read_b128 v[218:221], v163 offset:21504
	ds_read_b128 v[222:225], v163 offset:22528
	ds_read_b128 v[226:229], v163 offset:23552
	global_load_lds_dwordx4 v[152:153], off
	v_lshl_add_u64 v[232:233], v[230:231], 0, v[136:137]
	s_add_i32 m0, s8, 0x2000
	v_lshl_add_u64 v[234:235], v[230:231], 0, s[16:17]
	s_add_i32 s8, s72, s54
	global_load_lds_dwordx4 v[232:233], off
	v_lshl_add_u64 v[236:237], v[234:235], 0, v[132:133]
	s_mov_b32 m0, s8
	v_lshl_add_u64 v[234:235], v[234:235], 0, v[136:137]
	global_load_lds_dwordx4 v[236:237], off
	s_add_i32 m0, s8, 0x2000
	v_lshl_add_u64 v[236:237], v[158:159], 0, v[134:135]
	global_load_lds_dwordx4 v[234:235], off
	v_lshl_add_u64 v[234:235], v[158:159], 0, v[130:131]
	s_mov_b32 m0, s55
	s_nop 0
	global_load_lds_dwordx4 v[234:235], off
	s_mov_b32 m0, s56
	s_nop 0
	global_load_lds_dwordx4 v[236:237], off
	s_waitcnt vmcnt(8)
	s_waitcnt lgkmcnt(0)
	s_barrier
	s_setprio 1
	s_waitcnt lgkmcnt(0)
	v_mfma_f32_16x16x32_bf16 v[62:65], v[166:169], v[198:201], v[62:65]
	v_mfma_f32_16x16x32_bf16 v[54:57], v[174:177], v[198:201], v[54:57]
	v_mfma_f32_16x16x32_bf16 v[46:49], v[166:169], v[206:209], v[46:49]
	v_mfma_f32_16x16x32_bf16 v[38:41], v[174:177], v[206:209], v[38:41]
	v_mfma_f32_16x16x32_bf16 v[30:33], v[166:169], v[214:217], v[30:33]
	v_mfma_f32_16x16x32_bf16 v[22:25], v[174:177], v[214:217], v[22:25]
	v_mfma_f32_16x16x32_bf16 v[14:17], v[166:169], v[222:225], v[14:17]
	v_mfma_f32_16x16x32_bf16 v[6:9], v[174:177], v[222:225], v[6:9]
	v_mfma_f32_16x16x32_bf16 v[62:65], v[170:173], v[202:205], v[62:65]
	v_mfma_f32_16x16x32_bf16 v[54:57], v[178:181], v[202:205], v[54:57]
	v_mfma_f32_16x16x32_bf16 v[46:49], v[170:173], v[210:213], v[46:49]
	v_mfma_f32_16x16x32_bf16 v[38:41], v[178:181], v[210:213], v[38:41]
	v_mfma_f32_16x16x32_bf16 v[30:33], v[170:173], v[218:221], v[30:33]
	v_mfma_f32_16x16x32_bf16 v[22:25], v[178:181], v[218:221], v[22:25]
	v_mfma_f32_16x16x32_bf16 v[14:17], v[170:173], v[226:229], v[14:17]
	v_mfma_f32_16x16x32_bf16 v[6:9], v[178:181], v[226:229], v[6:9]
	s_setprio 0
	s_setprio 1
	v_mfma_f32_16x16x32_bf16 v[58:61], v[182:185], v[198:201], v[58:61]
	v_mfma_f32_16x16x32_bf16 v[50:53], v[190:193], v[198:201], v[50:53]
	v_mfma_f32_16x16x32_bf16 v[42:45], v[182:185], v[206:209], v[42:45]
	v_mfma_f32_16x16x32_bf16 v[34:37], v[190:193], v[206:209], v[34:37]
	v_mfma_f32_16x16x32_bf16 v[26:29], v[182:185], v[214:217], v[26:29]
	v_mfma_f32_16x16x32_bf16 v[18:21], v[190:193], v[214:217], v[18:21]
	v_mfma_f32_16x16x32_bf16 v[10:13], v[182:185], v[222:225], v[10:13]
	v_mfma_f32_16x16x32_bf16 v[2:5], v[190:193], v[222:225], v[2:5]
	v_mfma_f32_16x16x32_bf16 v[58:61], v[186:189], v[202:205], v[58:61]
	v_mfma_f32_16x16x32_bf16 v[50:53], v[194:197], v[202:205], v[50:53]
	v_mfma_f32_16x16x32_bf16 v[42:45], v[186:189], v[210:213], v[42:45]
	v_mfma_f32_16x16x32_bf16 v[34:37], v[194:197], v[210:213], v[34:37]
	v_mfma_f32_16x16x32_bf16 v[26:29], v[186:189], v[218:221], v[26:29]
	v_mfma_f32_16x16x32_bf16 v[18:21], v[194:197], v[218:221], v[18:21]
	v_mfma_f32_16x16x32_bf16 v[10:13], v[186:189], v[226:229], v[10:13]
	v_mfma_f32_16x16x32_bf16 v[2:5], v[194:197], v[226:229], v[2:5]
	s_setprio 0
	s_barrier
	s_add_i32 s8, 0, 0x18000
	v_add_u32_e32 v146, s8, v160
	s_add_i32 s50, 0, 0x1c000
	ds_read_b128 v[166:169], v146
	ds_read_b128 v[170:173], v146 offset:1024
	ds_read_b128 v[174:177], v146 offset:2048
	ds_read_b128 v[178:181], v146 offset:3072
	v_add_u32_e32 v146, s50, v160
	ds_read_b128 v[182:185], v146
	ds_read_b128 v[186:189], v146 offset:1024
	ds_read_b128 v[190:193], v146 offset:2048
	ds_read_b128 v[194:197], v146 offset:3072
	v_lshl_add_u64 v[158:159], v[158:159], 0, s[16:17]
	s_mov_b32 m0, s57
	v_lshl_add_u64 v[238:239], v[158:159], 0, v[130:131]
	ds_read_b128 v[198:201], v163 offset:32768
	ds_read_b128 v[202:205], v163 offset:33792
	ds_read_b128 v[206:209], v163 offset:34816
	ds_read_b128 v[210:213], v163 offset:35840
	ds_read_b128 v[214:217], v163 offset:36864
	ds_read_b128 v[218:221], v163 offset:37888
	ds_read_b128 v[222:225], v163 offset:38912
	ds_read_b128 v[226:229], v163 offset:39936
	global_load_lds_dwordx4 v[238:239], off
	v_lshl_add_u64 v[158:159], v[158:159], 0, v[134:135]
	s_mov_b32 m0, s58
	s_nop 0
	global_load_lds_dwordx4 v[158:159], off
	s_waitcnt vmcnt(8)
	s_waitcnt lgkmcnt(0)
	s_barrier
	s_setprio 1
	s_waitcnt lgkmcnt(0)
	v_mfma_f32_16x16x32_bf16 v[122:125], v[166:169], v[198:201], v[122:125]
	v_mfma_f32_16x16x32_bf16 v[118:121], v[174:177], v[198:201], v[118:121]
	v_mfma_f32_16x16x32_bf16 v[110:113], v[166:169], v[206:209], v[110:113]
	v_mfma_f32_16x16x32_bf16 v[102:105], v[174:177], v[206:209], v[102:105]
	v_mfma_f32_16x16x32_bf16 v[94:97], v[166:169], v[214:217], v[94:97]
	v_mfma_f32_16x16x32_bf16 v[86:89], v[174:177], v[214:217], v[86:89]
	v_mfma_f32_16x16x32_bf16 v[78:81], v[166:169], v[222:225], v[78:81]
	v_mfma_f32_16x16x32_bf16 v[70:73], v[174:177], v[222:225], v[70:73]
	v_mfma_f32_16x16x32_bf16 v[122:125], v[170:173], v[202:205], v[122:125]
	v_mfma_f32_16x16x32_bf16 v[118:121], v[178:181], v[202:205], v[118:121]
	v_mfma_f32_16x16x32_bf16 v[110:113], v[170:173], v[210:213], v[110:113]
	v_mfma_f32_16x16x32_bf16 v[102:105], v[178:181], v[210:213], v[102:105]
	v_mfma_f32_16x16x32_bf16 v[94:97], v[170:173], v[218:221], v[94:97]
	v_mfma_f32_16x16x32_bf16 v[86:89], v[178:181], v[218:221], v[86:89]
	v_mfma_f32_16x16x32_bf16 v[78:81], v[170:173], v[226:229], v[78:81]
	v_mfma_f32_16x16x32_bf16 v[70:73], v[178:181], v[226:229], v[70:73]
	s_setprio 0
	s_setprio 1
	v_mfma_f32_16x16x32_bf16 v[126:129], v[182:185], v[198:201], v[126:129]
	v_mfma_f32_16x16x32_bf16 v[114:117], v[190:193], v[198:201], v[114:117]
	v_mfma_f32_16x16x32_bf16 v[106:109], v[182:185], v[206:209], v[106:109]
	v_mfma_f32_16x16x32_bf16 v[98:101], v[190:193], v[206:209], v[98:101]
	v_mfma_f32_16x16x32_bf16 v[90:93], v[182:185], v[214:217], v[90:93]
	v_mfma_f32_16x16x32_bf16 v[82:85], v[190:193], v[214:217], v[82:85]
	v_mfma_f32_16x16x32_bf16 v[74:77], v[182:185], v[222:225], v[74:77]
	v_mfma_f32_16x16x32_bf16 v[66:69], v[190:193], v[222:225], v[66:69]
	v_mfma_f32_16x16x32_bf16 v[126:129], v[186:189], v[202:205], v[126:129]
	v_mfma_f32_16x16x32_bf16 v[114:117], v[194:197], v[202:205], v[114:117]
	v_mfma_f32_16x16x32_bf16 v[106:109], v[186:189], v[210:213], v[106:109]
	v_mfma_f32_16x16x32_bf16 v[98:101], v[194:197], v[210:213], v[98:101]
	v_mfma_f32_16x16x32_bf16 v[90:93], v[186:189], v[218:221], v[90:93]
	v_mfma_f32_16x16x32_bf16 v[82:85], v[194:197], v[218:221], v[82:85]
	v_mfma_f32_16x16x32_bf16 v[74:77], v[186:189], v[226:229], v[74:77]
	v_mfma_f32_16x16x32_bf16 v[66:69], v[194:197], v[226:229], v[66:69]
	s_setprio 0
	s_barrier
	s_add_i32 s8, s8, s54
	v_lshl_add_u64 v[152:153], v[152:153], 0, s[20:21]
	s_mov_b32 m0, s8
	ds_read_b128 v[198:201], v163 offset:49152
	ds_read_b128 v[202:205], v163 offset:50176
	ds_read_b128 v[206:209], v163 offset:51200
	ds_read_b128 v[210:213], v163 offset:52224
	ds_read_b128 v[214:217], v163 offset:53248
	ds_read_b128 v[218:221], v163 offset:54272
	ds_read_b128 v[222:225], v163 offset:55296
	ds_read_b128 v[226:229], v163 offset:56320
	global_load_lds_dwordx4 v[152:153], off
	v_lshl_add_u64 v[152:153], v[232:233], 0, s[20:21]
	s_add_i32 m0, s8, 0x2000
	s_add_i32 s8, s50, s54
	global_load_lds_dwordx4 v[152:153], off
	v_lshl_add_u64 v[152:153], v[230:231], 0, s[22:23]
	v_lshl_add_u64 v[158:159], v[152:153], 0, v[132:133]
	s_mov_b32 m0, s8
	v_lshl_add_u64 v[152:153], v[152:153], 0, v[136:137]
	global_load_lds_dwordx4 v[158:159], off
	s_add_i32 m0, s8, 0x2000
	s_nop 0
	global_load_lds_dwordx4 v[152:153], off
	v_lshl_add_u64 v[152:153], v[234:235], 0, s[20:21]
	s_mov_b32 m0, s64
	s_nop 0
	global_load_lds_dwordx4 v[152:153], off
	v_lshl_add_u64 v[152:153], v[236:237], 0, s[20:21]
	s_mov_b32 m0, s65
	s_nop 0
	global_load_lds_dwordx4 v[152:153], off
	s_waitcnt vmcnt(8)
	s_waitcnt lgkmcnt(0)
	s_barrier
	s_setprio 1
	s_waitcnt lgkmcnt(0)
	v_mfma_f32_16x16x32_bf16 v[62:65], v[166:169], v[198:201], v[62:65]
	v_mfma_f32_16x16x32_bf16 v[54:57], v[174:177], v[198:201], v[54:57]
	v_mfma_f32_16x16x32_bf16 v[46:49], v[166:169], v[206:209], v[46:49]
	v_mfma_f32_16x16x32_bf16 v[38:41], v[174:177], v[206:209], v[38:41]
	v_mfma_f32_16x16x32_bf16 v[30:33], v[166:169], v[214:217], v[30:33]
	v_mfma_f32_16x16x32_bf16 v[22:25], v[174:177], v[214:217], v[22:25]
	v_mfma_f32_16x16x32_bf16 v[14:17], v[166:169], v[222:225], v[14:17]
	v_mfma_f32_16x16x32_bf16 v[6:9], v[174:177], v[222:225], v[6:9]
	v_mfma_f32_16x16x32_bf16 v[62:65], v[170:173], v[202:205], v[62:65]
	v_mfma_f32_16x16x32_bf16 v[54:57], v[178:181], v[202:205], v[54:57]
	v_mfma_f32_16x16x32_bf16 v[46:49], v[170:173], v[210:213], v[46:49]
	v_mfma_f32_16x16x32_bf16 v[38:41], v[178:181], v[210:213], v[38:41]
	v_mfma_f32_16x16x32_bf16 v[30:33], v[170:173], v[218:221], v[30:33]
	v_mfma_f32_16x16x32_bf16 v[22:25], v[178:181], v[218:221], v[22:25]
	v_mfma_f32_16x16x32_bf16 v[14:17], v[170:173], v[226:229], v[14:17]
	v_mfma_f32_16x16x32_bf16 v[6:9], v[178:181], v[226:229], v[6:9]
	s_setprio 0
	s_setprio 1
	v_mfma_f32_16x16x32_bf16 v[58:61], v[182:185], v[198:201], v[58:61]
	v_mfma_f32_16x16x32_bf16 v[50:53], v[190:193], v[198:201], v[50:53]
	v_mfma_f32_16x16x32_bf16 v[42:45], v[182:185], v[206:209], v[42:45]
	v_mfma_f32_16x16x32_bf16 v[34:37], v[190:193], v[206:209], v[34:37]
	v_mfma_f32_16x16x32_bf16 v[26:29], v[182:185], v[214:217], v[26:29]
	v_mfma_f32_16x16x32_bf16 v[18:21], v[190:193], v[214:217], v[18:21]
	v_mfma_f32_16x16x32_bf16 v[10:13], v[182:185], v[222:225], v[10:13]
	v_mfma_f32_16x16x32_bf16 v[2:5], v[190:193], v[222:225], v[2:5]
	v_mfma_f32_16x16x32_bf16 v[58:61], v[186:189], v[202:205], v[58:61]
	v_mfma_f32_16x16x32_bf16 v[50:53], v[194:197], v[202:205], v[50:53]
	v_mfma_f32_16x16x32_bf16 v[42:45], v[186:189], v[210:213], v[42:45]
	v_mfma_f32_16x16x32_bf16 v[34:37], v[194:197], v[210:213], v[34:37]
	v_mfma_f32_16x16x32_bf16 v[26:29], v[186:189], v[218:221], v[26:29]
	v_mfma_f32_16x16x32_bf16 v[18:21], v[194:197], v[218:221], v[18:21]
	v_mfma_f32_16x16x32_bf16 v[10:13], v[186:189], v[226:229], v[10:13]
	v_mfma_f32_16x16x32_bf16 v[2:5], v[194:197], v[226:229], v[2:5]
	s_setprio 0
	s_barrier
	v_cmp_ge_i32_e32 vcc, s9, v141
	v_lshl_add_u64 v[154:155], v[154:155], 0, s[28:29]
	v_mov_b64_e32 v[152:153], v[156:157]
	s_mov_b32 s8, s9
	s_cbranch_vccz .LBB0_310
.Lmy_kexit_1:
	s_and_b64 vcc, exec, s[24:25]
	s_cbranch_vccz .LBB0_313
.LBB0_312:
	s_barrier

.LBB0_497:
	v_cmp_gt_i32_e32 vcc, 1, v141
	s_cbranch_vccnz .LBB0_559
	v_lshl_add_u64 v[154:155], v[2:3], 0, s[16:17]
	v_add_u32_e32 v138, -2, v141
	v_lshl_add_u64 v[152:153], v[4:5], 0, s[20:21]
	s_mov_b32 s7, 0
	v_add_u32_e32 v146, s77, v160
	ds_read_b128 v[156:159], v146
	ds_read_b128 v[166:169], v146 offset:1024
	ds_read_b128 v[170:173], v146 offset:2048
	ds_read_b128 v[174:177], v146 offset:3072
	v_add_u32_e32 v146, s78, v160
	ds_read_b128 v[178:181], v146
	ds_read_b128 v[182:185], v146 offset:1024
	ds_read_b128 v[186:189], v146 offset:2048
	ds_read_b128 v[190:193], v146 offset:3072
	v_lshl_add_u64 v[194:195], v[154:155], 0, s[22:23]
	v_cmp_eq_u32_e32 vcc, s7, v138
	s_add_i32 s45, s7, 2
	s_nop 0
	v_cndmask_b32_e32 v227, v195, v149, vcc
	v_cndmask_b32_e32 v226, v194, v148, vcc
	v_cndmask_b32_e32 v229, v153, v151, vcc
	v_cndmask_b32_e32 v228, v152, v150, vcc
	v_lshl_add_u64 v[230:231], v[154:155], 0, v[144:145]
	s_add_i32 m0, s49, 0xc000
	ds_read_b128 v[194:197], v163
	ds_read_b128 v[198:201], v163 offset:1024
	ds_read_b128 v[202:205], v163 offset:2048
	ds_read_b128 v[206:209], v163 offset:3072
	ds_read_b128 v[210:213], v163 offset:4096
	ds_read_b128 v[214:217], v163 offset:5120
	ds_read_b128 v[218:221], v163 offset:6144
	ds_read_b128 v[222:225], v163 offset:7168
	global_load_lds_dwordx4 v[230:231], off
	v_lshl_add_u64 v[230:231], v[154:155], 0, v[142:143]
	s_add_i32 m0, s49, 0xe000
	s_nop 0
	global_load_lds_dwordx4 v[230:231], off
	s_waitcnt vmcnt(8)
	s_waitcnt lgkmcnt(0)
	s_barrier
	s_setprio 1
	s_waitcnt lgkmcnt(0)
	v_mfma_f32_16x16x32_bf16 v[122:125], v[156:159], v[194:197], 0
	v_mfma_f32_16x16x32_bf16 v[118:121], v[170:173], v[194:197], 0
	v_mfma_f32_16x16x32_bf16 v[110:113], v[156:159], v[202:205], 0
	v_mfma_f32_16x16x32_bf16 v[102:105], v[170:173], v[202:205], 0
	v_mfma_f32_16x16x32_bf16 v[94:97], v[156:159], v[210:213], 0
	v_mfma_f32_16x16x32_bf16 v[86:89], v[170:173], v[210:213], 0
	v_mfma_f32_16x16x32_bf16 v[78:81], v[156:159], v[218:221], 0
	v_mfma_f32_16x16x32_bf16 v[70:73], v[170:173], v[218:221], 0
	v_mfma_f32_16x16x32_bf16 v[122:125], v[166:169], v[198:201], v[122:125]
	v_mfma_f32_16x16x32_bf16 v[118:121], v[174:177], v[198:201], v[118:121]
	v_mfma_f32_16x16x32_bf16 v[110:113], v[166:169], v[206:209], v[110:113]
	v_mfma_f32_16x16x32_bf16 v[102:105], v[174:177], v[206:209], v[102:105]
	v_mfma_f32_16x16x32_bf16 v[94:97], v[166:169], v[214:217], v[94:97]
	v_mfma_f32_16x16x32_bf16 v[86:89], v[174:177], v[214:217], v[86:89]
	v_mfma_f32_16x16x32_bf16 v[78:81], v[166:169], v[222:225], v[78:81]
	v_mfma_f32_16x16x32_bf16 v[70:73], v[174:177], v[222:225], v[70:73]
	s_setprio 0
	s_setprio 1
	v_mfma_f32_16x16x32_bf16 v[126:129], v[178:181], v[194:197], 0
	v_mfma_f32_16x16x32_bf16 v[114:117], v[186:189], v[194:197], 0
	v_mfma_f32_16x16x32_bf16 v[106:109], v[178:181], v[202:205], 0
	v_mfma_f32_16x16x32_bf16 v[98:101], v[186:189], v[202:205], 0
	v_mfma_f32_16x16x32_bf16 v[90:93], v[178:181], v[210:213], 0
	v_mfma_f32_16x16x32_bf16 v[82:85], v[186:189], v[210:213], 0
	v_mfma_f32_16x16x32_bf16 v[74:77], v[178:181], v[218:221], 0
	v_mfma_f32_16x16x32_bf16 v[66:69], v[186:189], v[218:221], 0
	v_mfma_f32_16x16x32_bf16 v[126:129], v[182:185], v[198:201], v[126:129]
	v_mfma_f32_16x16x32_bf16 v[114:117], v[190:193], v[198:201], v[114:117]
	v_mfma_f32_16x16x32_bf16 v[106:109], v[182:185], v[206:209], v[106:109]
	v_mfma_f32_16x16x32_bf16 v[98:101], v[190:193], v[206:209], v[98:101]
	v_mfma_f32_16x16x32_bf16 v[90:93], v[182:185], v[214:217], v[90:93]
	v_mfma_f32_16x16x32_bf16 v[82:85], v[190:193], v[214:217], v[82:85]
	v_mfma_f32_16x16x32_bf16 v[74:77], v[182:185], v[222:225], v[74:77]
	v_mfma_f32_16x16x32_bf16 v[66:69], v[190:193], v[222:225], v[66:69]
	s_setprio 0
	s_barrier
	s_add_i32 s7, s77, s25
	v_lshl_add_u64 v[230:231], v[228:229], 0, v[132:133]
	s_mov_b32 m0, s7
	ds_read_b128 v[194:197], v163 offset:16384
	ds_read_b128 v[198:201], v163 offset:17408
	ds_read_b128 v[202:205], v163 offset:18432
	ds_read_b128 v[206:209], v163 offset:19456
	ds_read_b128 v[210:213], v163 offset:20480
	ds_read_b128 v[214:217], v163 offset:21504
	ds_read_b128 v[218:221], v163 offset:22528
	ds_read_b128 v[222:225], v163 offset:23552
	global_load_lds_dwordx4 v[230:231], off
	v_lshl_add_u64 v[232:233], v[228:229], 0, v[136:137]
	s_add_i32 m0, s7, 0x2000
	v_lshl_add_u64 v[234:235], v[228:229], 0, s[10:11]
	s_add_i32 s7, s78, s25
	global_load_lds_dwordx4 v[232:233], off
	v_lshl_add_u64 v[236:237], v[234:235], 0, v[132:133]
	s_mov_b32 m0, s7
	v_lshl_add_u64 v[234:235], v[234:235], 0, v[136:137]
	global_load_lds_dwordx4 v[236:237], off
	s_add_i32 m0, s7, 0x2000
	v_lshl_add_u64 v[236:237], v[226:227], 0, v[134:135]
	global_load_lds_dwordx4 v[234:235], off
	v_lshl_add_u64 v[234:235], v[226:227], 0, v[130:131]
	s_mov_b32 m0, s49
	s_nop 0
	global_load_lds_dwordx4 v[234:235], off
	s_mov_b32 m0, s58
	s_nop 0
	global_load_lds_dwordx4 v[236:237], off
	s_waitcnt vmcnt(8)
	s_waitcnt lgkmcnt(0)
	s_barrier
	s_setprio 1
	s_waitcnt lgkmcnt(0)
	v_mfma_f32_16x16x32_bf16 v[62:65], v[156:159], v[194:197], 0
	v_mfma_f32_16x16x32_bf16 v[54:57], v[170:173], v[194:197], 0
	v_mfma_f32_16x16x32_bf16 v[46:49], v[156:159], v[202:205], 0
	v_mfma_f32_16x16x32_bf16 v[38:41], v[170:173], v[202:205], 0
	v_mfma_f32_16x16x32_bf16 v[30:33], v[156:159], v[210:213], 0
	v_mfma_f32_16x16x32_bf16 v[22:25], v[170:173], v[210:213], 0
	v_mfma_f32_16x16x32_bf16 v[14:17], v[156:159], v[218:221], 0
	v_mfma_f32_16x16x32_bf16 v[6:9], v[170:173], v[218:221], 0
	v_mfma_f32_16x16x32_bf16 v[62:65], v[166:169], v[198:201], v[62:65]
	v_mfma_f32_16x16x32_bf16 v[54:57], v[174:177], v[198:201], v[54:57]
	v_mfma_f32_16x16x32_bf16 v[46:49], v[166:169], v[206:209], v[46:49]
	v_mfma_f32_16x16x32_bf16 v[38:41], v[174:177], v[206:209], v[38:41]
	v_mfma_f32_16x16x32_bf16 v[30:33], v[166:169], v[214:217], v[30:33]
	v_mfma_f32_16x16x32_bf16 v[22:25], v[174:177], v[214:217], v[22:25]
	v_mfma_f32_16x16x32_bf16 v[14:17], v[166:169], v[222:225], v[14:17]
	v_mfma_f32_16x16x32_bf16 v[6:9], v[174:177], v[222:225], v[6:9]
	s_setprio 0
	s_setprio 1
	v_mfma_f32_16x16x32_bf16 v[58:61], v[178:181], v[194:197], 0
	v_mfma_f32_16x16x32_bf16 v[50:53], v[186:189], v[194:197], 0
	v_mfma_f32_16x16x32_bf16 v[42:45], v[178:181], v[202:205], 0
	v_mfma_f32_16x16x32_bf16 v[34:37], v[186:189], v[202:205], 0
	v_mfma_f32_16x16x32_bf16 v[26:29], v[178:181], v[210:213], 0
	v_mfma_f32_16x16x32_bf16 v[18:21], v[186:189], v[210:213], 0
	v_mfma_f32_16x16x32_bf16 v[10:13], v[178:181], v[218:221], 0
	v_mfma_f32_16x16x32_bf16 v[2:5], v[186:189], v[218:221], 0
	v_mfma_f32_16x16x32_bf16 v[58:61], v[182:185], v[198:201], v[58:61]
	v_mfma_f32_16x16x32_bf16 v[50:53], v[190:193], v[198:201], v[50:53]
	v_mfma_f32_16x16x32_bf16 v[42:45], v[182:185], v[206:209], v[42:45]
	v_mfma_f32_16x16x32_bf16 v[34:37], v[190:193], v[206:209], v[34:37]
	v_mfma_f32_16x16x32_bf16 v[26:29], v[182:185], v[214:217], v[26:29]
	v_mfma_f32_16x16x32_bf16 v[18:21], v[190:193], v[214:217], v[18:21]
	v_mfma_f32_16x16x32_bf16 v[10:13], v[182:185], v[222:225], v[10:13]
	v_mfma_f32_16x16x32_bf16 v[2:5], v[190:193], v[222:225], v[2:5]
	s_setprio 0
	s_barrier
	s_add_i32 s7, 0, 0x18000
	v_add_u32_e32 v146, s7, v160
	s_add_i32 s47, 0, 0x1c000
	ds_read_b128 v[156:159], v146
	ds_read_b128 v[166:169], v146 offset:1024
	ds_read_b128 v[170:173], v146 offset:2048
	ds_read_b128 v[174:177], v146 offset:3072
	v_add_u32_e32 v146, s47, v160
	ds_read_b128 v[178:181], v146
	ds_read_b128 v[182:185], v146 offset:1024
	ds_read_b128 v[186:189], v146 offset:2048
	ds_read_b128 v[190:193], v146 offset:3072
	v_lshl_add_u64 v[226:227], v[226:227], 0, s[10:11]
	s_mov_b32 m0, s59
	v_lshl_add_u64 v[238:239], v[226:227], 0, v[130:131]
	ds_read_b128 v[194:197], v163 offset:32768
	ds_read_b128 v[198:201], v163 offset:33792
	ds_read_b128 v[202:205], v163 offset:34816
	ds_read_b128 v[206:209], v163 offset:35840
	ds_read_b128 v[210:213], v163 offset:36864
	ds_read_b128 v[214:217], v163 offset:37888
	ds_read_b128 v[218:221], v163 offset:38912
	ds_read_b128 v[222:225], v163 offset:39936
	global_load_lds_dwordx4 v[238:239], off
	v_lshl_add_u64 v[226:227], v[226:227], 0, v[134:135]
	s_mov_b32 m0, s60
	s_nop 0
	global_load_lds_dwordx4 v[226:227], off
	s_waitcnt vmcnt(8)
	s_waitcnt lgkmcnt(0)
	s_barrier
	s_setprio 1
	s_waitcnt lgkmcnt(0)
	v_mfma_f32_16x16x32_bf16 v[122:125], v[156:159], v[194:197], v[122:125]
	v_mfma_f32_16x16x32_bf16 v[118:121], v[170:173], v[194:197], v[118:121]
	v_mfma_f32_16x16x32_bf16 v[110:113], v[156:159], v[202:205], v[110:113]
	v_mfma_f32_16x16x32_bf16 v[102:105], v[170:173], v[202:205], v[102:105]
	v_mfma_f32_16x16x32_bf16 v[94:97], v[156:159], v[210:213], v[94:97]
	v_mfma_f32_16x16x32_bf16 v[86:89], v[170:173], v[210:213], v[86:89]
	v_mfma_f32_16x16x32_bf16 v[78:81], v[156:159], v[218:221], v[78:81]
	v_mfma_f32_16x16x32_bf16 v[70:73], v[170:173], v[218:221], v[70:73]
	v_mfma_f32_16x16x32_bf16 v[122:125], v[166:169], v[198:201], v[122:125]
	v_mfma_f32_16x16x32_bf16 v[118:121], v[174:177], v[198:201], v[118:121]
	v_mfma_f32_16x16x32_bf16 v[110:113], v[166:169], v[206:209], v[110:113]
	v_mfma_f32_16x16x32_bf16 v[102:105], v[174:177], v[206:209], v[102:105]
	v_mfma_f32_16x16x32_bf16 v[94:97], v[166:169], v[214:217], v[94:97]
	v_mfma_f32_16x16x32_bf16 v[86:89], v[174:177], v[214:217], v[86:89]
	v_mfma_f32_16x16x32_bf16 v[78:81], v[166:169], v[222:225], v[78:81]
	v_mfma_f32_16x16x32_bf16 v[70:73], v[174:177], v[222:225], v[70:73]
	s_setprio 0
	s_setprio 1
	v_mfma_f32_16x16x32_bf16 v[126:129], v[178:181], v[194:197], v[126:129]
	v_mfma_f32_16x16x32_bf16 v[114:117], v[186:189], v[194:197], v[114:117]
	v_mfma_f32_16x16x32_bf16 v[106:109], v[178:181], v[202:205], v[106:109]
	v_mfma_f32_16x16x32_bf16 v[98:101], v[186:189], v[202:205], v[98:101]
	v_mfma_f32_16x16x32_bf16 v[90:93], v[178:181], v[210:213], v[90:93]
	v_mfma_f32_16x16x32_bf16 v[82:85], v[186:189], v[210:213], v[82:85]
	v_mfma_f32_16x16x32_bf16 v[74:77], v[178:181], v[218:221], v[74:77]
	v_mfma_f32_16x16x32_bf16 v[66:69], v[186:189], v[218:221], v[66:69]
	v_mfma_f32_16x16x32_bf16 v[126:129], v[182:185], v[198:201], v[126:129]
	v_mfma_f32_16x16x32_bf16 v[114:117], v[190:193], v[198:201], v[114:117]
	v_mfma_f32_16x16x32_bf16 v[106:109], v[182:185], v[206:209], v[106:109]
	v_mfma_f32_16x16x32_bf16 v[98:101], v[190:193], v[206:209], v[98:101]
	v_mfma_f32_16x16x32_bf16 v[90:93], v[182:185], v[214:217], v[90:93]
	v_mfma_f32_16x16x32_bf16 v[82:85], v[190:193], v[214:217], v[82:85]
	v_mfma_f32_16x16x32_bf16 v[74:77], v[182:185], v[222:225], v[74:77]
	v_mfma_f32_16x16x32_bf16 v[66:69], v[190:193], v[222:225], v[66:69]
	s_setprio 0
	s_barrier
	s_add_i32 s7, s7, s25
	v_lshl_add_u64 v[226:227], v[230:231], 0, s[14:15]
	s_mov_b32 m0, s7
	ds_read_b128 v[194:197], v163 offset:49152
	ds_read_b128 v[198:201], v163 offset:50176
	ds_read_b128 v[202:205], v163 offset:51200
	ds_read_b128 v[206:209], v163 offset:52224
	ds_read_b128 v[210:213], v163 offset:53248
	ds_read_b128 v[214:217], v163 offset:54272
	ds_read_b128 v[218:221], v163 offset:55296
	ds_read_b128 v[222:225], v163 offset:56320
	global_load_lds_dwordx4 v[226:227], off
	v_lshl_add_u64 v[226:227], v[232:233], 0, s[14:15]
	s_add_i32 m0, s7, 0x2000
	s_add_i32 s7, s47, s25
	global_load_lds_dwordx4 v[226:227], off
	v_lshl_add_u64 v[226:227], v[228:229], 0, s[16:17]
	v_lshl_add_u64 v[228:229], v[226:227], 0, v[132:133]
	s_mov_b32 m0, s7
	v_lshl_add_u64 v[226:227], v[226:227], 0, v[136:137]
	global_load_lds_dwordx4 v[228:229], off
	s_add_i32 m0, s7, 0x2000
	s_nop 0
	global_load_lds_dwordx4 v[226:227], off
	v_lshl_add_u64 v[226:227], v[234:235], 0, s[14:15]
	s_mov_b32 m0, s66
	s_nop 0
	global_load_lds_dwordx4 v[226:227], off
	v_lshl_add_u64 v[226:227], v[236:237], 0, s[14:15]
	s_mov_b32 m0, s67
	s_nop 0
	global_load_lds_dwordx4 v[226:227], off
	s_waitcnt vmcnt(8)
	s_waitcnt lgkmcnt(0)
	s_barrier
	s_setprio 1
	s_waitcnt lgkmcnt(0)
	v_mfma_f32_16x16x32_bf16 v[62:65], v[156:159], v[194:197], v[62:65]
	v_mfma_f32_16x16x32_bf16 v[54:57], v[170:173], v[194:197], v[54:57]
	v_mfma_f32_16x16x32_bf16 v[46:49], v[156:159], v[202:205], v[46:49]
	v_mfma_f32_16x16x32_bf16 v[38:41], v[170:173], v[202:205], v[38:41]
	v_mfma_f32_16x16x32_bf16 v[30:33], v[156:159], v[210:213], v[30:33]
	v_mfma_f32_16x16x32_bf16 v[22:25], v[170:173], v[210:213], v[22:25]
	v_mfma_f32_16x16x32_bf16 v[14:17], v[156:159], v[218:221], v[14:17]
	v_mfma_f32_16x16x32_bf16 v[6:9], v[170:173], v[218:221], v[6:9]
	v_mfma_f32_16x16x32_bf16 v[62:65], v[166:169], v[198:201], v[62:65]
	v_mfma_f32_16x16x32_bf16 v[54:57], v[174:177], v[198:201], v[54:57]
	v_mfma_f32_16x16x32_bf16 v[46:49], v[166:169], v[206:209], v[46:49]
	v_mfma_f32_16x16x32_bf16 v[38:41], v[174:177], v[206:209], v[38:41]
	v_mfma_f32_16x16x32_bf16 v[30:33], v[166:169], v[214:217], v[30:33]
	v_mfma_f32_16x16x32_bf16 v[22:25], v[174:177], v[214:217], v[22:25]
	v_mfma_f32_16x16x32_bf16 v[14:17], v[166:169], v[222:225], v[14:17]
	v_mfma_f32_16x16x32_bf16 v[6:9], v[174:177], v[222:225], v[6:9]
	s_setprio 0
	s_setprio 1
	v_mfma_f32_16x16x32_bf16 v[58:61], v[178:181], v[194:197], v[58:61]
	v_mfma_f32_16x16x32_bf16 v[50:53], v[186:189], v[194:197], v[50:53]
	v_mfma_f32_16x16x32_bf16 v[42:45], v[178:181], v[202:205], v[42:45]
	v_mfma_f32_16x16x32_bf16 v[34:37], v[186:189], v[202:205], v[34:37]
	v_mfma_f32_16x16x32_bf16 v[26:29], v[178:181], v[210:213], v[26:29]
	v_mfma_f32_16x16x32_bf16 v[18:21], v[186:189], v[210:213], v[18:21]
	v_mfma_f32_16x16x32_bf16 v[10:13], v[178:181], v[218:221], v[10:13]
	v_mfma_f32_16x16x32_bf16 v[2:5], v[186:189], v[218:221], v[2:5]
	v_mfma_f32_16x16x32_bf16 v[58:61], v[182:185], v[198:201], v[58:61]
	v_mfma_f32_16x16x32_bf16 v[50:53], v[190:193], v[198:201], v[50:53]
	v_mfma_f32_16x16x32_bf16 v[42:45], v[182:185], v[206:209], v[42:45]
	v_mfma_f32_16x16x32_bf16 v[34:37], v[190:193], v[206:209], v[34:37]
	v_mfma_f32_16x16x32_bf16 v[26:29], v[182:185], v[214:217], v[26:29]
	v_mfma_f32_16x16x32_bf16 v[18:21], v[190:193], v[214:217], v[18:21]
	v_mfma_f32_16x16x32_bf16 v[10:13], v[182:185], v[222:225], v[10:13]
	v_mfma_f32_16x16x32_bf16 v[2:5], v[190:193], v[222:225], v[2:5]
	s_setprio 0
	s_barrier
	v_cmp_ge_i32_e32 vcc, s45, v141
	v_lshl_add_u64 v[152:153], v[152:153], 0, s[20:21]
	v_lshl_add_u64 v[154:155], v[154:155], 0, s[20:21]
	s_mov_b32 s7, s45
	s_cbranch_vccnz .Lmy_kexit_2

.Lmy_kexit_2:
	s_and_b64 vcc, exec, s[18:19]
	s_cbranch_vccz .LBB0_502

.LBB0_766:
	v_cmp_gt_i32_e32 vcc, 1, v138
	s_cbranch_vccnz .LBB0_828
	v_lshl_add_u64 v[152:153], v[2:3], 0, s[16:17]
	v_add_u32_e32 v154, -2, v138
	s_waitcnt lgkmcnt(0)
	v_lshl_add_u64 v[150:151], v[4:5], 0, s[20:21]
	s_mov_b32 s7, 0
	v_add_u32_e32 v155, s76, v141
	ds_read_b128 v[164:167], v155
	ds_read_b128 v[168:171], v155 offset:1024
	ds_read_b128 v[172:175], v155 offset:2048
	ds_read_b128 v[176:179], v155 offset:3072
	v_add_u32_e32 v155, s77, v141
	ds_read_b128 v[180:183], v155
	ds_read_b128 v[184:187], v155 offset:1024
	ds_read_b128 v[188:191], v155 offset:2048
	ds_read_b128 v[192:195], v155 offset:3072
	v_lshl_add_u64 v[156:157], v[152:153], 0, s[22:23]
	v_cmp_eq_u32_e32 vcc, s7, v154
	s_add_i32 s45, s7, 2
	s_nop 0
	v_cndmask_b32_e32 v157, v157, v147, vcc
	v_cndmask_b32_e32 v156, v156, v146, vcc
	v_cndmask_b32_e32 v229, v151, v149, vcc
	v_cndmask_b32_e32 v228, v150, v148, vcc
	v_lshl_add_u64 v[230:231], v[152:153], 0, v[144:145]
	s_add_i32 m0, s49, 0xc000
	ds_read_b128 v[196:199], v160
	ds_read_b128 v[200:203], v160 offset:1024
	ds_read_b128 v[204:207], v160 offset:2048
	ds_read_b128 v[208:211], v160 offset:3072
	ds_read_b128 v[212:215], v160 offset:4096
	ds_read_b128 v[216:219], v160 offset:5120
	ds_read_b128 v[220:223], v160 offset:6144
	ds_read_b128 v[224:227], v160 offset:7168
	global_load_lds_dwordx4 v[230:231], off
	v_lshl_add_u64 v[230:231], v[152:153], 0, v[142:143]
	s_add_i32 m0, s49, 0xe000
	s_nop 0
	global_load_lds_dwordx4 v[230:231], off
	s_waitcnt vmcnt(8)
	s_waitcnt lgkmcnt(0)
	s_barrier
	s_setprio 1
	s_waitcnt lgkmcnt(0)
	v_mfma_f32_16x16x32_bf16 v[122:125], v[164:167], v[196:199], 0
	v_mfma_f32_16x16x32_bf16 v[118:121], v[172:175], v[196:199], 0
	v_mfma_f32_16x16x32_bf16 v[110:113], v[164:167], v[204:207], 0
	v_mfma_f32_16x16x32_bf16 v[102:105], v[172:175], v[204:207], 0
	v_mfma_f32_16x16x32_bf16 v[94:97], v[164:167], v[212:215], 0
	v_mfma_f32_16x16x32_bf16 v[86:89], v[172:175], v[212:215], 0
	v_mfma_f32_16x16x32_bf16 v[78:81], v[164:167], v[220:223], 0
	v_mfma_f32_16x16x32_bf16 v[70:73], v[172:175], v[220:223], 0
	v_mfma_f32_16x16x32_bf16 v[122:125], v[168:171], v[200:203], v[122:125]
	v_mfma_f32_16x16x32_bf16 v[118:121], v[176:179], v[200:203], v[118:121]
	v_mfma_f32_16x16x32_bf16 v[110:113], v[168:171], v[208:211], v[110:113]
	v_mfma_f32_16x16x32_bf16 v[102:105], v[176:179], v[208:211], v[102:105]
	v_mfma_f32_16x16x32_bf16 v[94:97], v[168:171], v[216:219], v[94:97]
	v_mfma_f32_16x16x32_bf16 v[86:89], v[176:179], v[216:219], v[86:89]
	v_mfma_f32_16x16x32_bf16 v[78:81], v[168:171], v[224:227], v[78:81]
	v_mfma_f32_16x16x32_bf16 v[70:73], v[176:179], v[224:227], v[70:73]
	s_setprio 0
	s_setprio 1
	v_mfma_f32_16x16x32_bf16 v[126:129], v[180:183], v[196:199], 0
	v_mfma_f32_16x16x32_bf16 v[114:117], v[188:191], v[196:199], 0
	v_mfma_f32_16x16x32_bf16 v[106:109], v[180:183], v[204:207], 0
	v_mfma_f32_16x16x32_bf16 v[98:101], v[188:191], v[204:207], 0
	v_mfma_f32_16x16x32_bf16 v[90:93], v[180:183], v[212:215], 0
	v_mfma_f32_16x16x32_bf16 v[82:85], v[188:191], v[212:215], 0
	v_mfma_f32_16x16x32_bf16 v[74:77], v[180:183], v[220:223], 0
	v_mfma_f32_16x16x32_bf16 v[66:69], v[188:191], v[220:223], 0
	v_mfma_f32_16x16x32_bf16 v[126:129], v[184:187], v[200:203], v[126:129]
	v_mfma_f32_16x16x32_bf16 v[114:117], v[192:195], v[200:203], v[114:117]
	v_mfma_f32_16x16x32_bf16 v[106:109], v[184:187], v[208:211], v[106:109]
	v_mfma_f32_16x16x32_bf16 v[98:101], v[192:195], v[208:211], v[98:101]
	v_mfma_f32_16x16x32_bf16 v[90:93], v[184:187], v[216:219], v[90:93]
	v_mfma_f32_16x16x32_bf16 v[82:85], v[192:195], v[216:219], v[82:85]
	v_mfma_f32_16x16x32_bf16 v[74:77], v[184:187], v[224:227], v[74:77]
	v_mfma_f32_16x16x32_bf16 v[66:69], v[192:195], v[224:227], v[66:69]
	s_setprio 0
	s_barrier
	s_add_i32 s7, s76, s25
	v_lshl_add_u64 v[230:231], v[228:229], 0, v[132:133]
	s_mov_b32 m0, s7
	ds_read_b128 v[196:199], v160 offset:16384
	ds_read_b128 v[200:203], v160 offset:17408
	ds_read_b128 v[204:207], v160 offset:18432
	ds_read_b128 v[208:211], v160 offset:19456
	ds_read_b128 v[212:215], v160 offset:20480
	ds_read_b128 v[216:219], v160 offset:21504
	ds_read_b128 v[220:223], v160 offset:22528
	ds_read_b128 v[224:227], v160 offset:23552
	global_load_lds_dwordx4 v[230:231], off
	v_lshl_add_u64 v[232:233], v[228:229], 0, v[136:137]
	s_add_i32 m0, s7, 0x2000
	v_lshl_add_u64 v[234:235], v[228:229], 0, s[10:11]
	s_add_i32 s7, s77, s25
	global_load_lds_dwordx4 v[232:233], off
	v_lshl_add_u64 v[236:237], v[234:235], 0, v[132:133]
	s_mov_b32 m0, s7
	v_lshl_add_u64 v[234:235], v[234:235], 0, v[136:137]
	global_load_lds_dwordx4 v[236:237], off
	s_add_i32 m0, s7, 0x2000
	v_lshl_add_u64 v[236:237], v[156:157], 0, v[134:135]
	global_load_lds_dwordx4 v[234:235], off
	v_lshl_add_u64 v[234:235], v[156:157], 0, v[130:131]
	s_mov_b32 m0, s49
	s_nop 0
	global_load_lds_dwordx4 v[234:235], off
	s_mov_b32 m0, s58
	s_nop 0
	global_load_lds_dwordx4 v[236:237], off
	s_waitcnt vmcnt(8)
	s_waitcnt lgkmcnt(0)
	s_barrier
	s_setprio 1
	s_waitcnt lgkmcnt(0)
	v_mfma_f32_16x16x32_bf16 v[62:65], v[164:167], v[196:199], 0
	v_mfma_f32_16x16x32_bf16 v[54:57], v[172:175], v[196:199], 0
	v_mfma_f32_16x16x32_bf16 v[46:49], v[164:167], v[204:207], 0
	v_mfma_f32_16x16x32_bf16 v[38:41], v[172:175], v[204:207], 0
	v_mfma_f32_16x16x32_bf16 v[30:33], v[164:167], v[212:215], 0
	v_mfma_f32_16x16x32_bf16 v[22:25], v[172:175], v[212:215], 0
	v_mfma_f32_16x16x32_bf16 v[14:17], v[164:167], v[220:223], 0
	v_mfma_f32_16x16x32_bf16 v[6:9], v[172:175], v[220:223], 0
	v_mfma_f32_16x16x32_bf16 v[62:65], v[168:171], v[200:203], v[62:65]
	v_mfma_f32_16x16x32_bf16 v[54:57], v[176:179], v[200:203], v[54:57]
	v_mfma_f32_16x16x32_bf16 v[46:49], v[168:171], v[208:211], v[46:49]
	v_mfma_f32_16x16x32_bf16 v[38:41], v[176:179], v[208:211], v[38:41]
	v_mfma_f32_16x16x32_bf16 v[30:33], v[168:171], v[216:219], v[30:33]
	v_mfma_f32_16x16x32_bf16 v[22:25], v[176:179], v[216:219], v[22:25]
	v_mfma_f32_16x16x32_bf16 v[14:17], v[168:171], v[224:227], v[14:17]
	v_mfma_f32_16x16x32_bf16 v[6:9], v[176:179], v[224:227], v[6:9]
	s_setprio 0
	s_setprio 1
	v_mfma_f32_16x16x32_bf16 v[58:61], v[180:183], v[196:199], 0
	v_mfma_f32_16x16x32_bf16 v[50:53], v[188:191], v[196:199], 0
	v_mfma_f32_16x16x32_bf16 v[42:45], v[180:183], v[204:207], 0
	v_mfma_f32_16x16x32_bf16 v[34:37], v[188:191], v[204:207], 0
	v_mfma_f32_16x16x32_bf16 v[26:29], v[180:183], v[212:215], 0
	v_mfma_f32_16x16x32_bf16 v[18:21], v[188:191], v[212:215], 0
	v_mfma_f32_16x16x32_bf16 v[10:13], v[180:183], v[220:223], 0
	v_mfma_f32_16x16x32_bf16 v[2:5], v[188:191], v[220:223], 0
	v_mfma_f32_16x16x32_bf16 v[58:61], v[184:187], v[200:203], v[58:61]
	v_mfma_f32_16x16x32_bf16 v[50:53], v[192:195], v[200:203], v[50:53]
	v_mfma_f32_16x16x32_bf16 v[42:45], v[184:187], v[208:211], v[42:45]
	v_mfma_f32_16x16x32_bf16 v[34:37], v[192:195], v[208:211], v[34:37]
	v_mfma_f32_16x16x32_bf16 v[26:29], v[184:187], v[216:219], v[26:29]
	v_mfma_f32_16x16x32_bf16 v[18:21], v[192:195], v[216:219], v[18:21]
	v_mfma_f32_16x16x32_bf16 v[10:13], v[184:187], v[224:227], v[10:13]
	v_mfma_f32_16x16x32_bf16 v[2:5], v[192:195], v[224:227], v[2:5]
	s_setprio 0
	s_barrier
	s_add_i32 s7, 0, 0x18000
	v_add_u32_e32 v155, s7, v141
	s_add_i32 s47, 0, 0x1c000
	ds_read_b128 v[164:167], v155
	ds_read_b128 v[168:171], v155 offset:1024
	ds_read_b128 v[172:175], v155 offset:2048
	ds_read_b128 v[176:179], v155 offset:3072
	v_add_u32_e32 v155, s47, v141
	ds_read_b128 v[180:183], v155
	ds_read_b128 v[184:187], v155 offset:1024
	ds_read_b128 v[188:191], v155 offset:2048
	ds_read_b128 v[192:195], v155 offset:3072
	v_lshl_add_u64 v[156:157], v[156:157], 0, s[10:11]
	s_mov_b32 m0, s59
	v_lshl_add_u64 v[238:239], v[156:157], 0, v[130:131]
	ds_read_b128 v[196:199], v160 offset:32768
	ds_read_b128 v[200:203], v160 offset:33792
	ds_read_b128 v[204:207], v160 offset:34816
	ds_read_b128 v[208:211], v160 offset:35840
	ds_read_b128 v[212:215], v160 offset:36864
	ds_read_b128 v[216:219], v160 offset:37888
	ds_read_b128 v[220:223], v160 offset:38912
	ds_read_b128 v[224:227], v160 offset:39936
	global_load_lds_dwordx4 v[238:239], off
	v_lshl_add_u64 v[156:157], v[156:157], 0, v[134:135]
	s_mov_b32 m0, s60
	s_nop 0
	global_load_lds_dwordx4 v[156:157], off
	s_waitcnt vmcnt(8)
	s_waitcnt lgkmcnt(0)
	s_barrier
	s_setprio 1
	s_waitcnt lgkmcnt(0)
	v_mfma_f32_16x16x32_bf16 v[122:125], v[164:167], v[196:199], v[122:125]
	v_mfma_f32_16x16x32_bf16 v[118:121], v[172:175], v[196:199], v[118:121]
	v_mfma_f32_16x16x32_bf16 v[110:113], v[164:167], v[204:207], v[110:113]
	v_mfma_f32_16x16x32_bf16 v[102:105], v[172:175], v[204:207], v[102:105]
	v_mfma_f32_16x16x32_bf16 v[94:97], v[164:167], v[212:215], v[94:97]
	v_mfma_f32_16x16x32_bf16 v[86:89], v[172:175], v[212:215], v[86:89]
	v_mfma_f32_16x16x32_bf16 v[78:81], v[164:167], v[220:223], v[78:81]
	v_mfma_f32_16x16x32_bf16 v[70:73], v[172:175], v[220:223], v[70:73]
	v_mfma_f32_16x16x32_bf16 v[122:125], v[168:171], v[200:203], v[122:125]
	v_mfma_f32_16x16x32_bf16 v[118:121], v[176:179], v[200:203], v[118:121]
	v_mfma_f32_16x16x32_bf16 v[110:113], v[168:171], v[208:211], v[110:113]
	v_mfma_f32_16x16x32_bf16 v[102:105], v[176:179], v[208:211], v[102:105]
	v_mfma_f32_16x16x32_bf16 v[94:97], v[168:171], v[216:219], v[94:97]
	v_mfma_f32_16x16x32_bf16 v[86:89], v[176:179], v[216:219], v[86:89]
	v_mfma_f32_16x16x32_bf16 v[78:81], v[168:171], v[224:227], v[78:81]
	v_mfma_f32_16x16x32_bf16 v[70:73], v[176:179], v[224:227], v[70:73]
	s_setprio 0
	s_setprio 1
	v_mfma_f32_16x16x32_bf16 v[126:129], v[180:183], v[196:199], v[126:129]
	v_mfma_f32_16x16x32_bf16 v[114:117], v[188:191], v[196:199], v[114:117]
	v_mfma_f32_16x16x32_bf16 v[106:109], v[180:183], v[204:207], v[106:109]
	v_mfma_f32_16x16x32_bf16 v[98:101], v[188:191], v[204:207], v[98:101]
	v_mfma_f32_16x16x32_bf16 v[90:93], v[180:183], v[212:215], v[90:93]
	v_mfma_f32_16x16x32_bf16 v[82:85], v[188:191], v[212:215], v[82:85]
	v_mfma_f32_16x16x32_bf16 v[74:77], v[180:183], v[220:223], v[74:77]
	v_mfma_f32_16x16x32_bf16 v[66:69], v[188:191], v[220:223], v[66:69]
	v_mfma_f32_16x16x32_bf16 v[126:129], v[184:187], v[200:203], v[126:129]
	v_mfma_f32_16x16x32_bf16 v[114:117], v[192:195], v[200:203], v[114:117]
	v_mfma_f32_16x16x32_bf16 v[106:109], v[184:187], v[208:211], v[106:109]
	v_mfma_f32_16x16x32_bf16 v[98:101], v[192:195], v[208:211], v[98:101]
	v_mfma_f32_16x16x32_bf16 v[90:93], v[184:187], v[216:219], v[90:93]
	v_mfma_f32_16x16x32_bf16 v[82:85], v[192:195], v[216:219], v[82:85]
	v_mfma_f32_16x16x32_bf16 v[74:77], v[184:187], v[224:227], v[74:77]
	v_mfma_f32_16x16x32_bf16 v[66:69], v[192:195], v[224:227], v[66:69]
	s_setprio 0
	s_barrier
	s_add_i32 s7, s7, s25
	v_lshl_add_u64 v[156:157], v[230:231], 0, s[14:15]
	s_mov_b32 m0, s7
	ds_read_b128 v[196:199], v160 offset:49152
	ds_read_b128 v[200:203], v160 offset:50176
	ds_read_b128 v[204:207], v160 offset:51200
	ds_read_b128 v[208:211], v160 offset:52224
	ds_read_b128 v[212:215], v160 offset:53248
	ds_read_b128 v[216:219], v160 offset:54272
	ds_read_b128 v[220:223], v160 offset:55296
	ds_read_b128 v[224:227], v160 offset:56320
	global_load_lds_dwordx4 v[156:157], off
	v_lshl_add_u64 v[156:157], v[232:233], 0, s[14:15]
	s_add_i32 m0, s7, 0x2000
	s_add_i32 s7, s47, s25
	global_load_lds_dwordx4 v[156:157], off
	v_lshl_add_u64 v[156:157], v[228:229], 0, s[16:17]
	v_lshl_add_u64 v[228:229], v[156:157], 0, v[132:133]
	s_mov_b32 m0, s7
	v_lshl_add_u64 v[156:157], v[156:157], 0, v[136:137]
	global_load_lds_dwordx4 v[228:229], off
	s_add_i32 m0, s7, 0x2000
	s_nop 0
	global_load_lds_dwordx4 v[156:157], off
	v_lshl_add_u64 v[156:157], v[234:235], 0, s[14:15]
	s_mov_b32 m0, s66
	s_nop 0
	global_load_lds_dwordx4 v[156:157], off
	v_lshl_add_u64 v[156:157], v[236:237], 0, s[14:15]
	s_mov_b32 m0, s67
	s_nop 0
	global_load_lds_dwordx4 v[156:157], off
	s_waitcnt vmcnt(8)
	s_waitcnt lgkmcnt(0)
	s_barrier
	s_setprio 1
	s_waitcnt lgkmcnt(0)
	v_mfma_f32_16x16x32_bf16 v[62:65], v[164:167], v[196:199], v[62:65]
	v_mfma_f32_16x16x32_bf16 v[54:57], v[172:175], v[196:199], v[54:57]
	v_mfma_f32_16x16x32_bf16 v[46:49], v[164:167], v[204:207], v[46:49]
	v_mfma_f32_16x16x32_bf16 v[38:41], v[172:175], v[204:207], v[38:41]
	v_mfma_f32_16x16x32_bf16 v[30:33], v[164:167], v[212:215], v[30:33]
	v_mfma_f32_16x16x32_bf16 v[22:25], v[172:175], v[212:215], v[22:25]
	v_mfma_f32_16x16x32_bf16 v[14:17], v[164:167], v[220:223], v[14:17]
	v_mfma_f32_16x16x32_bf16 v[6:9], v[172:175], v[220:223], v[6:9]
	v_mfma_f32_16x16x32_bf16 v[62:65], v[168:171], v[200:203], v[62:65]
	v_mfma_f32_16x16x32_bf16 v[54:57], v[176:179], v[200:203], v[54:57]
	v_mfma_f32_16x16x32_bf16 v[46:49], v[168:171], v[208:211], v[46:49]
	v_mfma_f32_16x16x32_bf16 v[38:41], v[176:179], v[208:211], v[38:41]
	v_mfma_f32_16x16x32_bf16 v[30:33], v[168:171], v[216:219], v[30:33]
	v_mfma_f32_16x16x32_bf16 v[22:25], v[176:179], v[216:219], v[22:25]
	v_mfma_f32_16x16x32_bf16 v[14:17], v[168:171], v[224:227], v[14:17]
	v_mfma_f32_16x16x32_bf16 v[6:9], v[176:179], v[224:227], v[6:9]
	s_setprio 0
	s_setprio 1
	v_mfma_f32_16x16x32_bf16 v[58:61], v[180:183], v[196:199], v[58:61]
	v_mfma_f32_16x16x32_bf16 v[50:53], v[188:191], v[196:199], v[50:53]
	v_mfma_f32_16x16x32_bf16 v[42:45], v[180:183], v[204:207], v[42:45]
	v_mfma_f32_16x16x32_bf16 v[34:37], v[188:191], v[204:207], v[34:37]
	v_mfma_f32_16x16x32_bf16 v[26:29], v[180:183], v[212:215], v[26:29]
	v_mfma_f32_16x16x32_bf16 v[18:21], v[188:191], v[212:215], v[18:21]
	v_mfma_f32_16x16x32_bf16 v[10:13], v[180:183], v[220:223], v[10:13]
	v_mfma_f32_16x16x32_bf16 v[2:5], v[188:191], v[220:223], v[2:5]
	v_mfma_f32_16x16x32_bf16 v[58:61], v[184:187], v[200:203], v[58:61]
	v_mfma_f32_16x16x32_bf16 v[50:53], v[192:195], v[200:203], v[50:53]
	v_mfma_f32_16x16x32_bf16 v[42:45], v[184:187], v[208:211], v[42:45]
	v_mfma_f32_16x16x32_bf16 v[34:37], v[192:195], v[208:211], v[34:37]
	v_mfma_f32_16x16x32_bf16 v[26:29], v[184:187], v[216:219], v[26:29]
	v_mfma_f32_16x16x32_bf16 v[18:21], v[192:195], v[216:219], v[18:21]
	v_mfma_f32_16x16x32_bf16 v[10:13], v[184:187], v[224:227], v[10:13]
	v_mfma_f32_16x16x32_bf16 v[2:5], v[192:195], v[224:227], v[2:5]
	s_setprio 0
	s_barrier
	v_cmp_ge_i32_e32 vcc, s45, v138
	v_lshl_add_u64 v[150:151], v[150:151], 0, s[20:21]
	v_lshl_add_u64 v[152:153], v[152:153], 0, s[20:21]
	s_mov_b32 s7, s45
	s_cbranch_vccnz .Lmy_kexit_3

.LBB0_947:
	v_cmp_gt_i32_e32 vcc, 1, v138
	s_cbranch_vccnz .LBB0_1009
	v_lshl_add_u64 v[152:153], v[2:3], 0, s[18:19]
	v_add_u32_e32 v154, -2, v138
	s_waitcnt lgkmcnt(0)
	v_lshl_add_u64 v[150:151], v[4:5], 0, s[22:23]
	s_mov_b32 s7, 0
	v_add_u32_e32 v155, s74, v141
	ds_read_b128 v[164:167], v155
	ds_read_b128 v[168:171], v155 offset:1024
	ds_read_b128 v[172:175], v155 offset:2048
	ds_read_b128 v[176:179], v155 offset:3072
	v_add_u32_e32 v155, s75, v141
	ds_read_b128 v[180:183], v155
	ds_read_b128 v[184:187], v155 offset:1024
	ds_read_b128 v[188:191], v155 offset:2048
	ds_read_b128 v[192:195], v155 offset:3072
	v_lshl_add_u64 v[156:157], v[152:153], 0, s[24:25]
	v_cmp_eq_u32_e32 vcc, s7, v154
	s_add_i32 s47, s7, 2
	s_nop 0
	v_cndmask_b32_e32 v157, v157, v147, vcc
	v_cndmask_b32_e32 v156, v156, v146, vcc
	v_cndmask_b32_e32 v229, v151, v149, vcc
	v_cndmask_b32_e32 v228, v150, v148, vcc
	s_mov_b32 m0, s76
	v_lshl_add_u64 v[230:231], v[152:153], 0, v[144:145]
	ds_read_b128 v[196:199], v160
	ds_read_b128 v[200:203], v160 offset:1024
	ds_read_b128 v[204:207], v160 offset:2048
	ds_read_b128 v[208:211], v160 offset:3072
	ds_read_b128 v[212:215], v160 offset:4096
	ds_read_b128 v[216:219], v160 offset:5120
	ds_read_b128 v[220:223], v160 offset:6144
	ds_read_b128 v[224:227], v160 offset:7168
	global_load_lds_dwordx4 v[230:231], off
	v_lshl_add_u64 v[230:231], v[152:153], 0, v[142:143]
	s_mov_b32 m0, s77
	s_nop 0
	global_load_lds_dwordx4 v[230:231], off
	s_waitcnt vmcnt(8)
	s_waitcnt lgkmcnt(0)
	s_barrier
	s_setprio 1
	s_waitcnt lgkmcnt(0)
	v_mfma_f32_16x16x32_bf16 v[122:125], v[164:167], v[196:199], 0
	v_mfma_f32_16x16x32_bf16 v[118:121], v[172:175], v[196:199], 0
	v_mfma_f32_16x16x32_bf16 v[110:113], v[164:167], v[204:207], 0
	v_mfma_f32_16x16x32_bf16 v[102:105], v[172:175], v[204:207], 0
	v_mfma_f32_16x16x32_bf16 v[94:97], v[164:167], v[212:215], 0
	v_mfma_f32_16x16x32_bf16 v[86:89], v[172:175], v[212:215], 0
	v_mfma_f32_16x16x32_bf16 v[78:81], v[164:167], v[220:223], 0
	v_mfma_f32_16x16x32_bf16 v[70:73], v[172:175], v[220:223], 0
	v_mfma_f32_16x16x32_bf16 v[122:125], v[168:171], v[200:203], v[122:125]
	v_mfma_f32_16x16x32_bf16 v[118:121], v[176:179], v[200:203], v[118:121]
	v_mfma_f32_16x16x32_bf16 v[110:113], v[168:171], v[208:211], v[110:113]
	v_mfma_f32_16x16x32_bf16 v[102:105], v[176:179], v[208:211], v[102:105]
	v_mfma_f32_16x16x32_bf16 v[94:97], v[168:171], v[216:219], v[94:97]
	v_mfma_f32_16x16x32_bf16 v[86:89], v[176:179], v[216:219], v[86:89]
	v_mfma_f32_16x16x32_bf16 v[78:81], v[168:171], v[224:227], v[78:81]
	v_mfma_f32_16x16x32_bf16 v[70:73], v[176:179], v[224:227], v[70:73]
	s_setprio 0
	s_setprio 1
	v_mfma_f32_16x16x32_bf16 v[126:129], v[180:183], v[196:199], 0
	v_mfma_f32_16x16x32_bf16 v[114:117], v[188:191], v[196:199], 0
	v_mfma_f32_16x16x32_bf16 v[106:109], v[180:183], v[204:207], 0
	v_mfma_f32_16x16x32_bf16 v[98:101], v[188:191], v[204:207], 0
	v_mfma_f32_16x16x32_bf16 v[90:93], v[180:183], v[212:215], 0
	v_mfma_f32_16x16x32_bf16 v[82:85], v[188:191], v[212:215], 0
	v_mfma_f32_16x16x32_bf16 v[74:77], v[180:183], v[220:223], 0
	v_mfma_f32_16x16x32_bf16 v[66:69], v[188:191], v[220:223], 0
	v_mfma_f32_16x16x32_bf16 v[126:129], v[184:187], v[200:203], v[126:129]
	v_mfma_f32_16x16x32_bf16 v[114:117], v[192:195], v[200:203], v[114:117]
	v_mfma_f32_16x16x32_bf16 v[106:109], v[184:187], v[208:211], v[106:109]
	v_mfma_f32_16x16x32_bf16 v[98:101], v[192:195], v[208:211], v[98:101]
	v_mfma_f32_16x16x32_bf16 v[90:93], v[184:187], v[216:219], v[90:93]
	v_mfma_f32_16x16x32_bf16 v[82:85], v[192:195], v[216:219], v[82:85]
	v_mfma_f32_16x16x32_bf16 v[74:77], v[184:187], v[224:227], v[74:77]
	v_mfma_f32_16x16x32_bf16 v[66:69], v[192:195], v[224:227], v[66:69]
	s_setprio 0
	s_barrier
	s_mov_b32 m0, s78
	v_lshl_add_u64 v[230:231], v[228:229], 0, v[132:133]
	ds_read_b128 v[196:199], v160 offset:16384
	ds_read_b128 v[200:203], v160 offset:17408
	ds_read_b128 v[204:207], v160 offset:18432
	ds_read_b128 v[208:211], v160 offset:19456
	ds_read_b128 v[212:215], v160 offset:20480
	ds_read_b128 v[216:219], v160 offset:21504
	ds_read_b128 v[220:223], v160 offset:22528
	ds_read_b128 v[224:227], v160 offset:23552
	global_load_lds_dwordx4 v[230:231], off
	v_lshl_add_u64 v[232:233], v[228:229], 0, v[136:137]
	s_mov_b32 m0, s79
	v_lshl_add_u64 v[234:235], v[228:229], 0, s[10:11]
	s_add_i32 s7, s75, s29
	global_load_lds_dwordx4 v[232:233], off
	v_lshl_add_u64 v[236:237], v[234:235], 0, v[132:133]
	s_mov_b32 m0, s7
	v_lshl_add_u64 v[234:235], v[234:235], 0, v[136:137]
	global_load_lds_dwordx4 v[236:237], off
	s_add_i32 m0, s7, 0x2000
	v_lshl_add_u64 v[236:237], v[156:157], 0, v[134:135]
	global_load_lds_dwordx4 v[234:235], off
	v_lshl_add_u64 v[234:235], v[156:157], 0, v[130:131]
	s_mov_b32 m0, s51
	s_nop 0
	global_load_lds_dwordx4 v[234:235], off
	s_mov_b32 m0, s60
	s_nop 0
	global_load_lds_dwordx4 v[236:237], off
	s_waitcnt vmcnt(8)
	s_waitcnt lgkmcnt(0)
	s_barrier
	s_setprio 1
	s_waitcnt lgkmcnt(0)
	v_mfma_f32_16x16x32_bf16 v[62:65], v[164:167], v[196:199], 0
	v_mfma_f32_16x16x32_bf16 v[54:57], v[172:175], v[196:199], 0
	v_mfma_f32_16x16x32_bf16 v[46:49], v[164:167], v[204:207], 0
	v_mfma_f32_16x16x32_bf16 v[38:41], v[172:175], v[204:207], 0
	v_mfma_f32_16x16x32_bf16 v[30:33], v[164:167], v[212:215], 0
	v_mfma_f32_16x16x32_bf16 v[22:25], v[172:175], v[212:215], 0
	v_mfma_f32_16x16x32_bf16 v[14:17], v[164:167], v[220:223], 0
	v_mfma_f32_16x16x32_bf16 v[6:9], v[172:175], v[220:223], 0
	v_mfma_f32_16x16x32_bf16 v[62:65], v[168:171], v[200:203], v[62:65]
	v_mfma_f32_16x16x32_bf16 v[54:57], v[176:179], v[200:203], v[54:57]
	v_mfma_f32_16x16x32_bf16 v[46:49], v[168:171], v[208:211], v[46:49]
	v_mfma_f32_16x16x32_bf16 v[38:41], v[176:179], v[208:211], v[38:41]
	v_mfma_f32_16x16x32_bf16 v[30:33], v[168:171], v[216:219], v[30:33]
	v_mfma_f32_16x16x32_bf16 v[22:25], v[176:179], v[216:219], v[22:25]
	v_mfma_f32_16x16x32_bf16 v[14:17], v[168:171], v[224:227], v[14:17]
	v_mfma_f32_16x16x32_bf16 v[6:9], v[176:179], v[224:227], v[6:9]
	s_setprio 0
	s_setprio 1
	v_mfma_f32_16x16x32_bf16 v[58:61], v[180:183], v[196:199], 0
	v_mfma_f32_16x16x32_bf16 v[50:53], v[188:191], v[196:199], 0
	v_mfma_f32_16x16x32_bf16 v[42:45], v[180:183], v[204:207], 0
	v_mfma_f32_16x16x32_bf16 v[34:37], v[188:191], v[204:207], 0
	v_mfma_f32_16x16x32_bf16 v[26:29], v[180:183], v[212:215], 0
	v_mfma_f32_16x16x32_bf16 v[18:21], v[188:191], v[212:215], 0
	v_mfma_f32_16x16x32_bf16 v[10:13], v[180:183], v[220:223], 0
	v_mfma_f32_16x16x32_bf16 v[2:5], v[188:191], v[220:223], 0
	v_mfma_f32_16x16x32_bf16 v[58:61], v[184:187], v[200:203], v[58:61]
	v_mfma_f32_16x16x32_bf16 v[50:53], v[192:195], v[200:203], v[50:53]
	v_mfma_f32_16x16x32_bf16 v[42:45], v[184:187], v[208:211], v[42:45]
	v_mfma_f32_16x16x32_bf16 v[34:37], v[192:195], v[208:211], v[34:37]
	v_mfma_f32_16x16x32_bf16 v[26:29], v[184:187], v[216:219], v[26:29]
	v_mfma_f32_16x16x32_bf16 v[18:21], v[192:195], v[216:219], v[18:21]
	v_mfma_f32_16x16x32_bf16 v[10:13], v[184:187], v[224:227], v[10:13]
	v_mfma_f32_16x16x32_bf16 v[2:5], v[192:195], v[224:227], v[2:5]
	s_setprio 0
	s_barrier
	s_add_i32 s7, 0, 0x18000
	v_add_u32_e32 v155, s7, v141
	s_add_i32 s49, 0, 0x1c000
	ds_read_b128 v[164:167], v155
	ds_read_b128 v[168:171], v155 offset:1024
	ds_read_b128 v[172:175], v155 offset:2048
	ds_read_b128 v[176:179], v155 offset:3072
	v_add_u32_e32 v155, s49, v141
	ds_read_b128 v[180:183], v155
	ds_read_b128 v[184:187], v155 offset:1024
	ds_read_b128 v[188:191], v155 offset:2048
	ds_read_b128 v[192:195], v155 offset:3072
	v_lshl_add_u64 v[156:157], v[156:157], 0, s[10:11]
	s_mov_b32 m0, s61
	v_lshl_add_u64 v[238:239], v[156:157], 0, v[130:131]
	ds_read_b128 v[196:199], v160 offset:32768
	ds_read_b128 v[200:203], v160 offset:33792
	ds_read_b128 v[204:207], v160 offset:34816
	ds_read_b128 v[208:211], v160 offset:35840
	ds_read_b128 v[212:215], v160 offset:36864
	ds_read_b128 v[216:219], v160 offset:37888
	ds_read_b128 v[220:223], v160 offset:38912
	ds_read_b128 v[224:227], v160 offset:39936
	global_load_lds_dwordx4 v[238:239], off
	v_lshl_add_u64 v[156:157], v[156:157], 0, v[134:135]
	s_mov_b32 m0, s62
	s_nop 0
	global_load_lds_dwordx4 v[156:157], off
	s_waitcnt vmcnt(8)
	s_waitcnt lgkmcnt(0)
	s_barrier
	s_setprio 1
	s_waitcnt lgkmcnt(0)
	v_mfma_f32_16x16x32_bf16 v[122:125], v[164:167], v[196:199], v[122:125]
	v_mfma_f32_16x16x32_bf16 v[118:121], v[172:175], v[196:199], v[118:121]
	v_mfma_f32_16x16x32_bf16 v[110:113], v[164:167], v[204:207], v[110:113]
	v_mfma_f32_16x16x32_bf16 v[102:105], v[172:175], v[204:207], v[102:105]
	v_mfma_f32_16x16x32_bf16 v[94:97], v[164:167], v[212:215], v[94:97]
	v_mfma_f32_16x16x32_bf16 v[86:89], v[172:175], v[212:215], v[86:89]
	v_mfma_f32_16x16x32_bf16 v[78:81], v[164:167], v[220:223], v[78:81]
	v_mfma_f32_16x16x32_bf16 v[70:73], v[172:175], v[220:223], v[70:73]
	v_mfma_f32_16x16x32_bf16 v[122:125], v[168:171], v[200:203], v[122:125]
	v_mfma_f32_16x16x32_bf16 v[118:121], v[176:179], v[200:203], v[118:121]
	v_mfma_f32_16x16x32_bf16 v[110:113], v[168:171], v[208:211], v[110:113]
	v_mfma_f32_16x16x32_bf16 v[102:105], v[176:179], v[208:211], v[102:105]
	v_mfma_f32_16x16x32_bf16 v[94:97], v[168:171], v[216:219], v[94:97]
	v_mfma_f32_16x16x32_bf16 v[86:89], v[176:179], v[216:219], v[86:89]
	v_mfma_f32_16x16x32_bf16 v[78:81], v[168:171], v[224:227], v[78:81]
	v_mfma_f32_16x16x32_bf16 v[70:73], v[176:179], v[224:227], v[70:73]
	s_setprio 0
	s_setprio 1
	v_mfma_f32_16x16x32_bf16 v[126:129], v[180:183], v[196:199], v[126:129]
	v_mfma_f32_16x16x32_bf16 v[114:117], v[188:191], v[196:199], v[114:117]
	v_mfma_f32_16x16x32_bf16 v[106:109], v[180:183], v[204:207], v[106:109]
	v_mfma_f32_16x16x32_bf16 v[98:101], v[188:191], v[204:207], v[98:101]
	v_mfma_f32_16x16x32_bf16 v[90:93], v[180:183], v[212:215], v[90:93]
	v_mfma_f32_16x16x32_bf16 v[82:85], v[188:191], v[212:215], v[82:85]
	v_mfma_f32_16x16x32_bf16 v[74:77], v[180:183], v[220:223], v[74:77]
	v_mfma_f32_16x16x32_bf16 v[66:69], v[188:191], v[220:223], v[66:69]
	v_mfma_f32_16x16x32_bf16 v[126:129], v[184:187], v[200:203], v[126:129]
	v_mfma_f32_16x16x32_bf16 v[114:117], v[192:195], v[200:203], v[114:117]
	v_mfma_f32_16x16x32_bf16 v[106:109], v[184:187], v[208:211], v[106:109]
	v_mfma_f32_16x16x32_bf16 v[98:101], v[192:195], v[208:211], v[98:101]
	v_mfma_f32_16x16x32_bf16 v[90:93], v[184:187], v[216:219], v[90:93]
	v_mfma_f32_16x16x32_bf16 v[82:85], v[192:195], v[216:219], v[82:85]
	v_mfma_f32_16x16x32_bf16 v[74:77], v[184:187], v[224:227], v[74:77]
	v_mfma_f32_16x16x32_bf16 v[66:69], v[192:195], v[224:227], v[66:69]
	s_setprio 0
	s_barrier
	s_add_i32 s7, s7, s29
	v_lshl_add_u64 v[156:157], v[230:231], 0, s[16:17]
	s_mov_b32 m0, s7
	ds_read_b128 v[196:199], v160 offset:49152
	ds_read_b128 v[200:203], v160 offset:50176
	ds_read_b128 v[204:207], v160 offset:51200
	ds_read_b128 v[208:211], v160 offset:52224
	ds_read_b128 v[212:215], v160 offset:53248
	ds_read_b128 v[216:219], v160 offset:54272
	ds_read_b128 v[220:223], v160 offset:55296
	ds_read_b128 v[224:227], v160 offset:56320
	global_load_lds_dwordx4 v[156:157], off
	v_lshl_add_u64 v[156:157], v[232:233], 0, s[16:17]
	s_add_i32 m0, s7, 0x2000
	s_add_i32 s7, s49, s29
	global_load_lds_dwordx4 v[156:157], off
	v_lshl_add_u64 v[156:157], v[228:229], 0, s[18:19]
	v_lshl_add_u64 v[228:229], v[156:157], 0, v[132:133]
	s_mov_b32 m0, s7
	v_lshl_add_u64 v[156:157], v[156:157], 0, v[136:137]
	global_load_lds_dwordx4 v[228:229], off
	s_add_i32 m0, s7, 0x2000
	s_nop 0
	global_load_lds_dwordx4 v[156:157], off
	v_lshl_add_u64 v[156:157], v[234:235], 0, s[16:17]
	s_mov_b32 m0, s63
	s_nop 0
	global_load_lds_dwordx4 v[156:157], off
	v_lshl_add_u64 v[156:157], v[236:237], 0, s[16:17]
	s_mov_b32 m0, s64
	s_nop 0
	global_load_lds_dwordx4 v[156:157], off
	s_waitcnt vmcnt(8)
	s_waitcnt lgkmcnt(0)
	s_barrier
	s_setprio 1
	s_waitcnt lgkmcnt(0)
	v_mfma_f32_16x16x32_bf16 v[62:65], v[164:167], v[196:199], v[62:65]
	v_mfma_f32_16x16x32_bf16 v[54:57], v[172:175], v[196:199], v[54:57]
	v_mfma_f32_16x16x32_bf16 v[46:49], v[164:167], v[204:207], v[46:49]
	v_mfma_f32_16x16x32_bf16 v[38:41], v[172:175], v[204:207], v[38:41]
	v_mfma_f32_16x16x32_bf16 v[30:33], v[164:167], v[212:215], v[30:33]
	v_mfma_f32_16x16x32_bf16 v[22:25], v[172:175], v[212:215], v[22:25]
	v_mfma_f32_16x16x32_bf16 v[14:17], v[164:167], v[220:223], v[14:17]
	v_mfma_f32_16x16x32_bf16 v[6:9], v[172:175], v[220:223], v[6:9]
	v_mfma_f32_16x16x32_bf16 v[62:65], v[168:171], v[200:203], v[62:65]
	v_mfma_f32_16x16x32_bf16 v[54:57], v[176:179], v[200:203], v[54:57]
	v_mfma_f32_16x16x32_bf16 v[46:49], v[168:171], v[208:211], v[46:49]
	v_mfma_f32_16x16x32_bf16 v[38:41], v[176:179], v[208:211], v[38:41]
	v_mfma_f32_16x16x32_bf16 v[30:33], v[168:171], v[216:219], v[30:33]
	v_mfma_f32_16x16x32_bf16 v[22:25], v[176:179], v[216:219], v[22:25]
	v_mfma_f32_16x16x32_bf16 v[14:17], v[168:171], v[224:227], v[14:17]
	v_mfma_f32_16x16x32_bf16 v[6:9], v[176:179], v[224:227], v[6:9]
	s_setprio 0
	s_setprio 1
	v_mfma_f32_16x16x32_bf16 v[58:61], v[180:183], v[196:199], v[58:61]
	v_mfma_f32_16x16x32_bf16 v[50:53], v[188:191], v[196:199], v[50:53]
	v_mfma_f32_16x16x32_bf16 v[42:45], v[180:183], v[204:207], v[42:45]
	v_mfma_f32_16x16x32_bf16 v[34:37], v[188:191], v[204:207], v[34:37]
	v_mfma_f32_16x16x32_bf16 v[26:29], v[180:183], v[212:215], v[26:29]
	v_mfma_f32_16x16x32_bf16 v[18:21], v[188:191], v[212:215], v[18:21]
	v_mfma_f32_16x16x32_bf16 v[10:13], v[180:183], v[220:223], v[10:13]
	v_mfma_f32_16x16x32_bf16 v[2:5], v[188:191], v[220:223], v[2:5]
	v_mfma_f32_16x16x32_bf16 v[58:61], v[184:187], v[200:203], v[58:61]
	v_mfma_f32_16x16x32_bf16 v[50:53], v[192:195], v[200:203], v[50:53]
	v_mfma_f32_16x16x32_bf16 v[42:45], v[184:187], v[208:211], v[42:45]
	v_mfma_f32_16x16x32_bf16 v[34:37], v[192:195], v[208:211], v[34:37]
	v_mfma_f32_16x16x32_bf16 v[26:29], v[184:187], v[216:219], v[26:29]
	v_mfma_f32_16x16x32_bf16 v[18:21], v[192:195], v[216:219], v[18:21]
	v_mfma_f32_16x16x32_bf16 v[10:13], v[184:187], v[224:227], v[10:13]
	v_mfma_f32_16x16x32_bf16 v[2:5], v[192:195], v[224:227], v[2:5]
	s_setprio 0
	s_barrier
	v_cmp_ge_i32_e32 vcc, s47, v138
	v_lshl_add_u64 v[150:151], v[150:151], 0, s[22:23]
	v_lshl_add_u64 v[152:153], v[152:153], 0, s[22:23]
	s_mov_b32 s7, s47
	s_cbranch_vccnz .Lmy_kexit_4

.Lmy_kexit_4:
	s_and_b64 vcc, exec, s[20:21]
	s_cbranch_vccz .LBB0_952

.LBB0_1078:
	v_cmp_gt_i32_e32 vcc, 1, v156
	s_cbranch_vccnz .LBB0_1140
	v_lshl_add_u64 v[152:153], v[2:3], 0, s[20:21]
	v_add_u32_e32 v138, -2, v156
	s_mov_b32 s6, 0
	v_add_u32_e32 v157, s67, v141
	ds_read_b128 v[164:167], v157
	ds_read_b128 v[168:171], v157 offset:1024
	ds_read_b128 v[172:175], v157 offset:2048
	ds_read_b128 v[176:179], v157 offset:3072
	v_add_u32_e32 v157, s68, v141
	ds_read_b128 v[180:183], v157
	ds_read_b128 v[184:187], v157 offset:1024
	ds_read_b128 v[188:191], v157 offset:2048
	ds_read_b128 v[192:195], v157 offset:3072
	v_lshl_add_u64 v[154:155], v[150:151], 0, s[20:21]
	v_cmp_eq_u32_e32 vcc, s6, v138
	s_add_i32 s7, s6, 2
	s_nop 0
	v_cndmask_b32_e32 v229, v155, v147, vcc
	v_cndmask_b32_e32 v228, v154, v146, vcc
	v_cndmask_b32_e32 v231, v153, v149, vcc
	v_cndmask_b32_e32 v230, v152, v148, vcc
	v_lshl_add_u64 v[232:233], v[150:151], 0, v[144:145]
	s_add_i32 m0, s46, 0xc000
	ds_read_b128 v[196:199], v160
	ds_read_b128 v[200:203], v160 offset:1024
	ds_read_b128 v[204:207], v160 offset:2048
	ds_read_b128 v[208:211], v160 offset:3072
	ds_read_b128 v[212:215], v160 offset:4096
	ds_read_b128 v[216:219], v160 offset:5120
	ds_read_b128 v[220:223], v160 offset:6144
	ds_read_b128 v[224:227], v160 offset:7168
	global_load_lds_dwordx4 v[232:233], off
	v_lshl_add_u64 v[150:151], v[150:151], 0, v[142:143]
	s_add_i32 m0, s46, 0xe000
	s_nop 0
	global_load_lds_dwordx4 v[150:151], off
	s_waitcnt vmcnt(8)
	s_waitcnt lgkmcnt(0)
	s_barrier
	s_setprio 1
	s_waitcnt lgkmcnt(0)
	v_mfma_f32_16x16x32_bf16 v[122:125], v[164:167], v[196:199], 0
	v_mfma_f32_16x16x32_bf16 v[118:121], v[172:175], v[196:199], 0
	v_mfma_f32_16x16x32_bf16 v[110:113], v[164:167], v[204:207], 0
	v_mfma_f32_16x16x32_bf16 v[102:105], v[172:175], v[204:207], 0
	v_mfma_f32_16x16x32_bf16 v[94:97], v[164:167], v[212:215], 0
	v_mfma_f32_16x16x32_bf16 v[86:89], v[172:175], v[212:215], 0
	v_mfma_f32_16x16x32_bf16 v[78:81], v[164:167], v[220:223], 0
	v_mfma_f32_16x16x32_bf16 v[70:73], v[172:175], v[220:223], 0
	v_mfma_f32_16x16x32_bf16 v[122:125], v[168:171], v[200:203], v[122:125]
	v_mfma_f32_16x16x32_bf16 v[118:121], v[176:179], v[200:203], v[118:121]
	v_mfma_f32_16x16x32_bf16 v[110:113], v[168:171], v[208:211], v[110:113]
	v_mfma_f32_16x16x32_bf16 v[102:105], v[176:179], v[208:211], v[102:105]
	v_mfma_f32_16x16x32_bf16 v[94:97], v[168:171], v[216:219], v[94:97]
	v_mfma_f32_16x16x32_bf16 v[86:89], v[176:179], v[216:219], v[86:89]
	v_mfma_f32_16x16x32_bf16 v[78:81], v[168:171], v[224:227], v[78:81]
	v_mfma_f32_16x16x32_bf16 v[70:73], v[176:179], v[224:227], v[70:73]
	s_setprio 0
	s_setprio 1
	v_mfma_f32_16x16x32_bf16 v[126:129], v[180:183], v[196:199], 0
	v_mfma_f32_16x16x32_bf16 v[114:117], v[188:191], v[196:199], 0
	v_mfma_f32_16x16x32_bf16 v[106:109], v[180:183], v[204:207], 0
	v_mfma_f32_16x16x32_bf16 v[98:101], v[188:191], v[204:207], 0
	v_mfma_f32_16x16x32_bf16 v[90:93], v[180:183], v[212:215], 0
	v_mfma_f32_16x16x32_bf16 v[82:85], v[188:191], v[212:215], 0
	v_mfma_f32_16x16x32_bf16 v[74:77], v[180:183], v[220:223], 0
	v_mfma_f32_16x16x32_bf16 v[66:69], v[188:191], v[220:223], 0
	v_mfma_f32_16x16x32_bf16 v[126:129], v[184:187], v[200:203], v[126:129]
	v_mfma_f32_16x16x32_bf16 v[114:117], v[192:195], v[200:203], v[114:117]
	v_mfma_f32_16x16x32_bf16 v[106:109], v[184:187], v[208:211], v[106:109]
	v_mfma_f32_16x16x32_bf16 v[98:101], v[192:195], v[208:211], v[98:101]
	v_mfma_f32_16x16x32_bf16 v[90:93], v[184:187], v[216:219], v[90:93]
	v_mfma_f32_16x16x32_bf16 v[82:85], v[192:195], v[216:219], v[82:85]
	v_mfma_f32_16x16x32_bf16 v[74:77], v[184:187], v[224:227], v[74:77]
	v_mfma_f32_16x16x32_bf16 v[66:69], v[192:195], v[224:227], v[66:69]
	s_setprio 0
	s_barrier
	s_add_i32 s6, s67, s23
	v_lshl_add_u64 v[150:151], v[230:231], 0, v[132:133]
	s_mov_b32 m0, s6
	ds_read_b128 v[196:199], v160 offset:16384
	ds_read_b128 v[200:203], v160 offset:17408
	ds_read_b128 v[204:207], v160 offset:18432
	ds_read_b128 v[208:211], v160 offset:19456
	ds_read_b128 v[212:215], v160 offset:20480
	ds_read_b128 v[216:219], v160 offset:21504
	ds_read_b128 v[220:223], v160 offset:22528
	ds_read_b128 v[224:227], v160 offset:23552
	global_load_lds_dwordx4 v[150:151], off
	v_lshl_add_u64 v[232:233], v[230:231], 0, v[136:137]
	s_add_i32 m0, s6, 0x2000
	v_lshl_add_u64 v[234:235], v[230:231], 0, s[10:11]
	s_add_i32 s6, s68, s23
	global_load_lds_dwordx4 v[232:233], off
	v_lshl_add_u64 v[236:237], v[234:235], 0, v[132:133]
	s_mov_b32 m0, s6
	v_lshl_add_u64 v[234:235], v[234:235], 0, v[136:137]
	global_load_lds_dwordx4 v[236:237], off
	s_add_i32 m0, s6, 0x2000
	v_lshl_add_u64 v[236:237], v[228:229], 0, v[134:135]
	global_load_lds_dwordx4 v[234:235], off
	v_lshl_add_u64 v[234:235], v[228:229], 0, v[130:131]
	s_mov_b32 m0, s46
	s_nop 0
	global_load_lds_dwordx4 v[234:235], off
	s_mov_b32 m0, s47
	s_nop 0
	global_load_lds_dwordx4 v[236:237], off
	s_waitcnt vmcnt(8)
	s_waitcnt lgkmcnt(0)
	s_barrier
	s_setprio 1
	s_waitcnt lgkmcnt(0)
	v_mfma_f32_16x16x32_bf16 v[62:65], v[164:167], v[196:199], 0
	v_mfma_f32_16x16x32_bf16 v[54:57], v[172:175], v[196:199], 0
	v_mfma_f32_16x16x32_bf16 v[46:49], v[164:167], v[204:207], 0
	v_mfma_f32_16x16x32_bf16 v[38:41], v[172:175], v[204:207], 0
	v_mfma_f32_16x16x32_bf16 v[30:33], v[164:167], v[212:215], 0
	v_mfma_f32_16x16x32_bf16 v[22:25], v[172:175], v[212:215], 0
	v_mfma_f32_16x16x32_bf16 v[14:17], v[164:167], v[220:223], 0
	v_mfma_f32_16x16x32_bf16 v[6:9], v[172:175], v[220:223], 0
	v_mfma_f32_16x16x32_bf16 v[62:65], v[168:171], v[200:203], v[62:65]
	v_mfma_f32_16x16x32_bf16 v[54:57], v[176:179], v[200:203], v[54:57]
	v_mfma_f32_16x16x32_bf16 v[46:49], v[168:171], v[208:211], v[46:49]
	v_mfma_f32_16x16x32_bf16 v[38:41], v[176:179], v[208:211], v[38:41]
	v_mfma_f32_16x16x32_bf16 v[30:33], v[168:171], v[216:219], v[30:33]
	v_mfma_f32_16x16x32_bf16 v[22:25], v[176:179], v[216:219], v[22:25]
	v_mfma_f32_16x16x32_bf16 v[14:17], v[168:171], v[224:227], v[14:17]
	v_mfma_f32_16x16x32_bf16 v[6:9], v[176:179], v[224:227], v[6:9]
	s_setprio 0
	s_setprio 1
	v_mfma_f32_16x16x32_bf16 v[58:61], v[180:183], v[196:199], 0
	v_mfma_f32_16x16x32_bf16 v[50:53], v[188:191], v[196:199], 0
	v_mfma_f32_16x16x32_bf16 v[42:45], v[180:183], v[204:207], 0
	v_mfma_f32_16x16x32_bf16 v[34:37], v[188:191], v[204:207], 0
	v_mfma_f32_16x16x32_bf16 v[26:29], v[180:183], v[212:215], 0
	v_mfma_f32_16x16x32_bf16 v[18:21], v[188:191], v[212:215], 0
	v_mfma_f32_16x16x32_bf16 v[10:13], v[180:183], v[220:223], 0
	v_mfma_f32_16x16x32_bf16 v[2:5], v[188:191], v[220:223], 0
	v_mfma_f32_16x16x32_bf16 v[58:61], v[184:187], v[200:203], v[58:61]
	v_mfma_f32_16x16x32_bf16 v[50:53], v[192:195], v[200:203], v[50:53]
	v_mfma_f32_16x16x32_bf16 v[42:45], v[184:187], v[208:211], v[42:45]
	v_mfma_f32_16x16x32_bf16 v[34:37], v[192:195], v[208:211], v[34:37]
	v_mfma_f32_16x16x32_bf16 v[26:29], v[184:187], v[216:219], v[26:29]
	v_mfma_f32_16x16x32_bf16 v[18:21], v[192:195], v[216:219], v[18:21]
	v_mfma_f32_16x16x32_bf16 v[10:13], v[184:187], v[224:227], v[10:13]
	v_mfma_f32_16x16x32_bf16 v[2:5], v[192:195], v[224:227], v[2:5]
	s_setprio 0
	s_barrier
	s_add_i32 s6, 0, 0x18000
	v_add_u32_e32 v157, s6, v141
	s_add_i32 s29, 0, 0x1c000
	ds_read_b128 v[164:167], v157
	ds_read_b128 v[168:171], v157 offset:1024
	ds_read_b128 v[172:175], v157 offset:2048
	ds_read_b128 v[176:179], v157 offset:3072
	v_add_u32_e32 v157, s29, v141
	ds_read_b128 v[180:183], v157
	ds_read_b128 v[184:187], v157 offset:1024
	ds_read_b128 v[188:191], v157 offset:2048
	ds_read_b128 v[192:195], v157 offset:3072
	v_lshl_add_u64 v[228:229], v[228:229], 0, s[10:11]
	s_mov_b32 m0, s48
	v_lshl_add_u64 v[238:239], v[228:229], 0, v[130:131]
	ds_read_b128 v[196:199], v160 offset:32768
	ds_read_b128 v[200:203], v160 offset:33792
	ds_read_b128 v[204:207], v160 offset:34816
	ds_read_b128 v[208:211], v160 offset:35840
	ds_read_b128 v[212:215], v160 offset:36864
	ds_read_b128 v[216:219], v160 offset:37888
	ds_read_b128 v[220:223], v160 offset:38912
	ds_read_b128 v[224:227], v160 offset:39936
	global_load_lds_dwordx4 v[238:239], off
	v_lshl_add_u64 v[228:229], v[228:229], 0, v[134:135]
	s_mov_b32 m0, s49
	s_nop 0
	global_load_lds_dwordx4 v[228:229], off
	s_waitcnt vmcnt(8)
	s_waitcnt lgkmcnt(0)
	s_barrier
	s_setprio 1
	s_waitcnt lgkmcnt(0)
	v_mfma_f32_16x16x32_bf16 v[122:125], v[164:167], v[196:199], v[122:125]
	v_mfma_f32_16x16x32_bf16 v[118:121], v[172:175], v[196:199], v[118:121]
	v_mfma_f32_16x16x32_bf16 v[110:113], v[164:167], v[204:207], v[110:113]
	v_mfma_f32_16x16x32_bf16 v[102:105], v[172:175], v[204:207], v[102:105]
	v_mfma_f32_16x16x32_bf16 v[94:97], v[164:167], v[212:215], v[94:97]
	v_mfma_f32_16x16x32_bf16 v[86:89], v[172:175], v[212:215], v[86:89]
	v_mfma_f32_16x16x32_bf16 v[78:81], v[164:167], v[220:223], v[78:81]
	v_mfma_f32_16x16x32_bf16 v[70:73], v[172:175], v[220:223], v[70:73]
	v_mfma_f32_16x16x32_bf16 v[122:125], v[168:171], v[200:203], v[122:125]
	v_mfma_f32_16x16x32_bf16 v[118:121], v[176:179], v[200:203], v[118:121]
	v_mfma_f32_16x16x32_bf16 v[110:113], v[168:171], v[208:211], v[110:113]
	v_mfma_f32_16x16x32_bf16 v[102:105], v[176:179], v[208:211], v[102:105]
	v_mfma_f32_16x16x32_bf16 v[94:97], v[168:171], v[216:219], v[94:97]
	v_mfma_f32_16x16x32_bf16 v[86:89], v[176:179], v[216:219], v[86:89]
	v_mfma_f32_16x16x32_bf16 v[78:81], v[168:171], v[224:227], v[78:81]
	v_mfma_f32_16x16x32_bf16 v[70:73], v[176:179], v[224:227], v[70:73]
	s_setprio 0
	s_setprio 1
	v_mfma_f32_16x16x32_bf16 v[126:129], v[180:183], v[196:199], v[126:129]
	v_mfma_f32_16x16x32_bf16 v[114:117], v[188:191], v[196:199], v[114:117]
	v_mfma_f32_16x16x32_bf16 v[106:109], v[180:183], v[204:207], v[106:109]
	v_mfma_f32_16x16x32_bf16 v[98:101], v[188:191], v[204:207], v[98:101]
	v_mfma_f32_16x16x32_bf16 v[90:93], v[180:183], v[212:215], v[90:93]
	v_mfma_f32_16x16x32_bf16 v[82:85], v[188:191], v[212:215], v[82:85]
	v_mfma_f32_16x16x32_bf16 v[74:77], v[180:183], v[220:223], v[74:77]
	v_mfma_f32_16x16x32_bf16 v[66:69], v[188:191], v[220:223], v[66:69]
	v_mfma_f32_16x16x32_bf16 v[126:129], v[184:187], v[200:203], v[126:129]
	v_mfma_f32_16x16x32_bf16 v[114:117], v[192:195], v[200:203], v[114:117]
	v_mfma_f32_16x16x32_bf16 v[106:109], v[184:187], v[208:211], v[106:109]
	v_mfma_f32_16x16x32_bf16 v[98:101], v[192:195], v[208:211], v[98:101]
	v_mfma_f32_16x16x32_bf16 v[90:93], v[184:187], v[216:219], v[90:93]
	v_mfma_f32_16x16x32_bf16 v[82:85], v[192:195], v[216:219], v[82:85]
	v_mfma_f32_16x16x32_bf16 v[74:77], v[184:187], v[224:227], v[74:77]
	v_mfma_f32_16x16x32_bf16 v[66:69], v[192:195], v[224:227], v[66:69]
	s_setprio 0
	s_barrier
	s_add_i32 s6, s6, s23
	v_lshl_add_u64 v[150:151], v[150:151], 0, s[14:15]
	s_mov_b32 m0, s6
	ds_read_b128 v[196:199], v160 offset:49152
	ds_read_b128 v[200:203], v160 offset:50176
	ds_read_b128 v[204:207], v160 offset:51200
	ds_read_b128 v[208:211], v160 offset:52224
	ds_read_b128 v[212:215], v160 offset:53248
	ds_read_b128 v[216:219], v160 offset:54272
	ds_read_b128 v[220:223], v160 offset:55296
	ds_read_b128 v[224:227], v160 offset:56320
	global_load_lds_dwordx4 v[150:151], off
	v_lshl_add_u64 v[150:151], v[232:233], 0, s[14:15]
	s_add_i32 m0, s6, 0x2000
	s_add_i32 s6, s29, s23
	global_load_lds_dwordx4 v[150:151], off
	v_lshl_add_u64 v[150:151], v[230:231], 0, s[16:17]
	v_lshl_add_u64 v[228:229], v[150:151], 0, v[132:133]
	s_mov_b32 m0, s6
	v_lshl_add_u64 v[150:151], v[150:151], 0, v[136:137]
	global_load_lds_dwordx4 v[228:229], off
	s_add_i32 m0, s6, 0x2000
	s_nop 0
	global_load_lds_dwordx4 v[150:151], off
	v_lshl_add_u64 v[150:151], v[234:235], 0, s[14:15]
	s_mov_b32 m0, s59
	s_nop 0
	global_load_lds_dwordx4 v[150:151], off
	v_lshl_add_u64 v[150:151], v[236:237], 0, s[14:15]
	s_mov_b32 m0, s60
	s_nop 0
	global_load_lds_dwordx4 v[150:151], off
	s_waitcnt vmcnt(8)
	s_waitcnt lgkmcnt(0)
	s_barrier
	s_setprio 1
	s_waitcnt lgkmcnt(0)
	v_mfma_f32_16x16x32_bf16 v[62:65], v[164:167], v[196:199], v[62:65]
	v_mfma_f32_16x16x32_bf16 v[54:57], v[172:175], v[196:199], v[54:57]
	v_mfma_f32_16x16x32_bf16 v[46:49], v[164:167], v[204:207], v[46:49]
	v_mfma_f32_16x16x32_bf16 v[38:41], v[172:175], v[204:207], v[38:41]
	v_mfma_f32_16x16x32_bf16 v[30:33], v[164:167], v[212:215], v[30:33]
	v_mfma_f32_16x16x32_bf16 v[22:25], v[172:175], v[212:215], v[22:25]
	v_mfma_f32_16x16x32_bf16 v[14:17], v[164:167], v[220:223], v[14:17]
	v_mfma_f32_16x16x32_bf16 v[6:9], v[172:175], v[220:223], v[6:9]
	v_mfma_f32_16x16x32_bf16 v[62:65], v[168:171], v[200:203], v[62:65]
	v_mfma_f32_16x16x32_bf16 v[54:57], v[176:179], v[200:203], v[54:57]
	v_mfma_f32_16x16x32_bf16 v[46:49], v[168:171], v[208:211], v[46:49]
	v_mfma_f32_16x16x32_bf16 v[38:41], v[176:179], v[208:211], v[38:41]
	v_mfma_f32_16x16x32_bf16 v[30:33], v[168:171], v[216:219], v[30:33]
	v_mfma_f32_16x16x32_bf16 v[22:25], v[176:179], v[216:219], v[22:25]
	v_mfma_f32_16x16x32_bf16 v[14:17], v[168:171], v[224:227], v[14:17]
	v_mfma_f32_16x16x32_bf16 v[6:9], v[176:179], v[224:227], v[6:9]
	s_setprio 0
	s_setprio 1
	v_mfma_f32_16x16x32_bf16 v[58:61], v[180:183], v[196:199], v[58:61]
	v_mfma_f32_16x16x32_bf16 v[50:53], v[188:191], v[196:199], v[50:53]
	v_mfma_f32_16x16x32_bf16 v[42:45], v[180:183], v[204:207], v[42:45]
	v_mfma_f32_16x16x32_bf16 v[34:37], v[188:191], v[204:207], v[34:37]
	v_mfma_f32_16x16x32_bf16 v[26:29], v[180:183], v[212:215], v[26:29]
	v_mfma_f32_16x16x32_bf16 v[18:21], v[188:191], v[212:215], v[18:21]
	v_mfma_f32_16x16x32_bf16 v[10:13], v[180:183], v[220:223], v[10:13]
	v_mfma_f32_16x16x32_bf16 v[2:5], v[188:191], v[220:223], v[2:5]
	v_mfma_f32_16x16x32_bf16 v[58:61], v[184:187], v[200:203], v[58:61]
	v_mfma_f32_16x16x32_bf16 v[50:53], v[192:195], v[200:203], v[50:53]
	v_mfma_f32_16x16x32_bf16 v[42:45], v[184:187], v[208:211], v[42:45]
	v_mfma_f32_16x16x32_bf16 v[34:37], v[192:195], v[208:211], v[34:37]
	v_mfma_f32_16x16x32_bf16 v[26:29], v[184:187], v[216:219], v[26:29]
	v_mfma_f32_16x16x32_bf16 v[18:21], v[192:195], v[216:219], v[18:21]
	v_mfma_f32_16x16x32_bf16 v[10:13], v[184:187], v[224:227], v[10:13]
	v_mfma_f32_16x16x32_bf16 v[2:5], v[192:195], v[224:227], v[2:5]
	s_setprio 0
	s_barrier
	v_cmp_ge_i32_e32 vcc, s7, v156
	v_lshl_add_u64 v[152:153], v[152:153], 0, s[20:21]
	v_mov_b64_e32 v[150:151], v[154:155]
	s_mov_b32 s6, s7
	s_cbranch_vccnz .Lmy_kexit_5

.LBB0_1390:
	v_cmp_gt_i32_e32 vcc, 1, v156
	s_cbranch_vccnz .LBB0_1452
	v_lshl_add_u64 v[152:153], v[2:3], 0, s[20:21]
	v_add_u32_e32 v138, -2, v156
	s_mov_b32 s6, 0
	v_add_u32_e32 v157, s67, v141
	ds_read_b128 v[164:167], v157
	ds_read_b128 v[168:171], v157 offset:1024
	ds_read_b128 v[172:175], v157 offset:2048
	ds_read_b128 v[176:179], v157 offset:3072
	v_add_u32_e32 v157, s70, v141
	ds_read_b128 v[180:183], v157
	ds_read_b128 v[184:187], v157 offset:1024
	ds_read_b128 v[188:191], v157 offset:2048
	ds_read_b128 v[192:195], v157 offset:3072
	v_lshl_add_u64 v[154:155], v[150:151], 0, s[20:21]
	v_cmp_eq_u32_e32 vcc, s6, v138
	s_add_i32 s7, s6, 2
	s_nop 0
	v_cndmask_b32_e32 v229, v155, v147, vcc
	v_cndmask_b32_e32 v228, v154, v146, vcc
	v_cndmask_b32_e32 v231, v153, v149, vcc
	v_cndmask_b32_e32 v230, v152, v148, vcc
	v_lshl_add_u64 v[232:233], v[150:151], 0, v[144:145]
	s_add_i32 m0, s46, 0xc000
	ds_read_b128 v[196:199], v160
	ds_read_b128 v[200:203], v160 offset:1024
	ds_read_b128 v[204:207], v160 offset:2048
	ds_read_b128 v[208:211], v160 offset:3072
	ds_read_b128 v[212:215], v160 offset:4096
	ds_read_b128 v[216:219], v160 offset:5120
	ds_read_b128 v[220:223], v160 offset:6144
	ds_read_b128 v[224:227], v160 offset:7168
	global_load_lds_dwordx4 v[232:233], off
	v_lshl_add_u64 v[150:151], v[150:151], 0, v[142:143]
	s_add_i32 m0, s46, 0xe000
	s_nop 0
	global_load_lds_dwordx4 v[150:151], off
	s_waitcnt vmcnt(8)
	s_waitcnt lgkmcnt(0)
	s_barrier
	s_setprio 1
	s_waitcnt lgkmcnt(0)
	v_mfma_f32_16x16x32_bf16 v[122:125], v[164:167], v[196:199], 0
	v_mfma_f32_16x16x32_bf16 v[118:121], v[172:175], v[196:199], 0
	v_mfma_f32_16x16x32_bf16 v[110:113], v[164:167], v[204:207], 0
	v_mfma_f32_16x16x32_bf16 v[102:105], v[172:175], v[204:207], 0
	v_mfma_f32_16x16x32_bf16 v[94:97], v[164:167], v[212:215], 0
	v_mfma_f32_16x16x32_bf16 v[86:89], v[172:175], v[212:215], 0
	v_mfma_f32_16x16x32_bf16 v[78:81], v[164:167], v[220:223], 0
	v_mfma_f32_16x16x32_bf16 v[70:73], v[172:175], v[220:223], 0
	v_mfma_f32_16x16x32_bf16 v[122:125], v[168:171], v[200:203], v[122:125]
	v_mfma_f32_16x16x32_bf16 v[118:121], v[176:179], v[200:203], v[118:121]
	v_mfma_f32_16x16x32_bf16 v[110:113], v[168:171], v[208:211], v[110:113]
	v_mfma_f32_16x16x32_bf16 v[102:105], v[176:179], v[208:211], v[102:105]
	v_mfma_f32_16x16x32_bf16 v[94:97], v[168:171], v[216:219], v[94:97]
	v_mfma_f32_16x16x32_bf16 v[86:89], v[176:179], v[216:219], v[86:89]
	v_mfma_f32_16x16x32_bf16 v[78:81], v[168:171], v[224:227], v[78:81]
	v_mfma_f32_16x16x32_bf16 v[70:73], v[176:179], v[224:227], v[70:73]
	s_setprio 0
	s_setprio 1
	v_mfma_f32_16x16x32_bf16 v[126:129], v[180:183], v[196:199], 0
	v_mfma_f32_16x16x32_bf16 v[114:117], v[188:191], v[196:199], 0
	v_mfma_f32_16x16x32_bf16 v[106:109], v[180:183], v[204:207], 0
	v_mfma_f32_16x16x32_bf16 v[98:101], v[188:191], v[204:207], 0
	v_mfma_f32_16x16x32_bf16 v[90:93], v[180:183], v[212:215], 0
	v_mfma_f32_16x16x32_bf16 v[82:85], v[188:191], v[212:215], 0
	v_mfma_f32_16x16x32_bf16 v[74:77], v[180:183], v[220:223], 0
	v_mfma_f32_16x16x32_bf16 v[66:69], v[188:191], v[220:223], 0
	v_mfma_f32_16x16x32_bf16 v[126:129], v[184:187], v[200:203], v[126:129]
	v_mfma_f32_16x16x32_bf16 v[114:117], v[192:195], v[200:203], v[114:117]
	v_mfma_f32_16x16x32_bf16 v[106:109], v[184:187], v[208:211], v[106:109]
	v_mfma_f32_16x16x32_bf16 v[98:101], v[192:195], v[208:211], v[98:101]
	v_mfma_f32_16x16x32_bf16 v[90:93], v[184:187], v[216:219], v[90:93]
	v_mfma_f32_16x16x32_bf16 v[82:85], v[192:195], v[216:219], v[82:85]
	v_mfma_f32_16x16x32_bf16 v[74:77], v[184:187], v[224:227], v[74:77]
	v_mfma_f32_16x16x32_bf16 v[66:69], v[192:195], v[224:227], v[66:69]
	s_setprio 0
	s_barrier
	s_add_i32 s6, s67, s23
	v_lshl_add_u64 v[150:151], v[230:231], 0, v[132:133]
	s_mov_b32 m0, s6
	ds_read_b128 v[196:199], v160 offset:16384
	ds_read_b128 v[200:203], v160 offset:17408
	ds_read_b128 v[204:207], v160 offset:18432
	ds_read_b128 v[208:211], v160 offset:19456
	ds_read_b128 v[212:215], v160 offset:20480
	ds_read_b128 v[216:219], v160 offset:21504
	ds_read_b128 v[220:223], v160 offset:22528
	ds_read_b128 v[224:227], v160 offset:23552
	global_load_lds_dwordx4 v[150:151], off
	v_lshl_add_u64 v[232:233], v[230:231], 0, v[136:137]
	s_add_i32 m0, s6, 0x2000
	v_lshl_add_u64 v[234:235], v[230:231], 0, s[10:11]
	s_add_i32 s6, s70, s23
	global_load_lds_dwordx4 v[232:233], off
	v_lshl_add_u64 v[236:237], v[234:235], 0, v[132:133]
	s_mov_b32 m0, s6
	v_lshl_add_u64 v[234:235], v[234:235], 0, v[136:137]
	global_load_lds_dwordx4 v[236:237], off
	s_add_i32 m0, s6, 0x2000
	v_lshl_add_u64 v[236:237], v[228:229], 0, v[134:135]
	global_load_lds_dwordx4 v[234:235], off
	v_lshl_add_u64 v[234:235], v[228:229], 0, v[130:131]
	s_mov_b32 m0, s46
	s_nop 0
	global_load_lds_dwordx4 v[234:235], off
	s_mov_b32 m0, s47
	s_nop 0
	global_load_lds_dwordx4 v[236:237], off
	s_waitcnt vmcnt(8)
	s_waitcnt lgkmcnt(0)
	s_barrier
	s_setprio 1
	s_waitcnt lgkmcnt(0)
	v_mfma_f32_16x16x32_bf16 v[62:65], v[164:167], v[196:199], 0
	v_mfma_f32_16x16x32_bf16 v[54:57], v[172:175], v[196:199], 0
	v_mfma_f32_16x16x32_bf16 v[46:49], v[164:167], v[204:207], 0
	v_mfma_f32_16x16x32_bf16 v[38:41], v[172:175], v[204:207], 0
	v_mfma_f32_16x16x32_bf16 v[30:33], v[164:167], v[212:215], 0
	v_mfma_f32_16x16x32_bf16 v[22:25], v[172:175], v[212:215], 0
	v_mfma_f32_16x16x32_bf16 v[14:17], v[164:167], v[220:223], 0
	v_mfma_f32_16x16x32_bf16 v[6:9], v[172:175], v[220:223], 0
	v_mfma_f32_16x16x32_bf16 v[62:65], v[168:171], v[200:203], v[62:65]
	v_mfma_f32_16x16x32_bf16 v[54:57], v[176:179], v[200:203], v[54:57]
	v_mfma_f32_16x16x32_bf16 v[46:49], v[168:171], v[208:211], v[46:49]
	v_mfma_f32_16x16x32_bf16 v[38:41], v[176:179], v[208:211], v[38:41]
	v_mfma_f32_16x16x32_bf16 v[30:33], v[168:171], v[216:219], v[30:33]
	v_mfma_f32_16x16x32_bf16 v[22:25], v[176:179], v[216:219], v[22:25]
	v_mfma_f32_16x16x32_bf16 v[14:17], v[168:171], v[224:227], v[14:17]
	v_mfma_f32_16x16x32_bf16 v[6:9], v[176:179], v[224:227], v[6:9]
	s_setprio 0
	s_setprio 1
	v_mfma_f32_16x16x32_bf16 v[58:61], v[180:183], v[196:199], 0
	v_mfma_f32_16x16x32_bf16 v[50:53], v[188:191], v[196:199], 0
	v_mfma_f32_16x16x32_bf16 v[42:45], v[180:183], v[204:207], 0
	v_mfma_f32_16x16x32_bf16 v[34:37], v[188:191], v[204:207], 0
	v_mfma_f32_16x16x32_bf16 v[26:29], v[180:183], v[212:215], 0
	v_mfma_f32_16x16x32_bf16 v[18:21], v[188:191], v[212:215], 0
	v_mfma_f32_16x16x32_bf16 v[10:13], v[180:183], v[220:223], 0
	v_mfma_f32_16x16x32_bf16 v[2:5], v[188:191], v[220:223], 0
	v_mfma_f32_16x16x32_bf16 v[58:61], v[184:187], v[200:203], v[58:61]
	v_mfma_f32_16x16x32_bf16 v[50:53], v[192:195], v[200:203], v[50:53]
	v_mfma_f32_16x16x32_bf16 v[42:45], v[184:187], v[208:211], v[42:45]
	v_mfma_f32_16x16x32_bf16 v[34:37], v[192:195], v[208:211], v[34:37]
	v_mfma_f32_16x16x32_bf16 v[26:29], v[184:187], v[216:219], v[26:29]
	v_mfma_f32_16x16x32_bf16 v[18:21], v[192:195], v[216:219], v[18:21]
	v_mfma_f32_16x16x32_bf16 v[10:13], v[184:187], v[224:227], v[10:13]
	v_mfma_f32_16x16x32_bf16 v[2:5], v[192:195], v[224:227], v[2:5]
	s_setprio 0
	s_barrier
	s_add_i32 s6, 0, 0x18000
	v_add_u32_e32 v157, s6, v141
	s_add_i32 s29, 0, 0x1c000
	ds_read_b128 v[164:167], v157
	ds_read_b128 v[168:171], v157 offset:1024
	ds_read_b128 v[172:175], v157 offset:2048
	ds_read_b128 v[176:179], v157 offset:3072
	v_add_u32_e32 v157, s29, v141
	ds_read_b128 v[180:183], v157
	ds_read_b128 v[184:187], v157 offset:1024
	ds_read_b128 v[188:191], v157 offset:2048
	ds_read_b128 v[192:195], v157 offset:3072
	v_lshl_add_u64 v[228:229], v[228:229], 0, s[10:11]
	s_mov_b32 m0, s48
	v_lshl_add_u64 v[238:239], v[228:229], 0, v[130:131]
	ds_read_b128 v[196:199], v160 offset:32768
	ds_read_b128 v[200:203], v160 offset:33792
	ds_read_b128 v[204:207], v160 offset:34816
	ds_read_b128 v[208:211], v160 offset:35840
	ds_read_b128 v[212:215], v160 offset:36864
	ds_read_b128 v[216:219], v160 offset:37888
	ds_read_b128 v[220:223], v160 offset:38912
	ds_read_b128 v[224:227], v160 offset:39936
	global_load_lds_dwordx4 v[238:239], off
	v_lshl_add_u64 v[228:229], v[228:229], 0, v[134:135]
	s_mov_b32 m0, s49
	s_nop 0
	global_load_lds_dwordx4 v[228:229], off
	s_waitcnt vmcnt(8)
	s_waitcnt lgkmcnt(0)
	s_barrier
	s_setprio 1
	s_waitcnt lgkmcnt(0)
	v_mfma_f32_16x16x32_bf16 v[122:125], v[164:167], v[196:199], v[122:125]
	v_mfma_f32_16x16x32_bf16 v[118:121], v[172:175], v[196:199], v[118:121]
	v_mfma_f32_16x16x32_bf16 v[110:113], v[164:167], v[204:207], v[110:113]
	v_mfma_f32_16x16x32_bf16 v[102:105], v[172:175], v[204:207], v[102:105]
	v_mfma_f32_16x16x32_bf16 v[94:97], v[164:167], v[212:215], v[94:97]
	v_mfma_f32_16x16x32_bf16 v[86:89], v[172:175], v[212:215], v[86:89]
	v_mfma_f32_16x16x32_bf16 v[78:81], v[164:167], v[220:223], v[78:81]
	v_mfma_f32_16x16x32_bf16 v[70:73], v[172:175], v[220:223], v[70:73]
	v_mfma_f32_16x16x32_bf16 v[122:125], v[168:171], v[200:203], v[122:125]
	v_mfma_f32_16x16x32_bf16 v[118:121], v[176:179], v[200:203], v[118:121]
	v_mfma_f32_16x16x32_bf16 v[110:113], v[168:171], v[208:211], v[110:113]
	v_mfma_f32_16x16x32_bf16 v[102:105], v[176:179], v[208:211], v[102:105]
	v_mfma_f32_16x16x32_bf16 v[94:97], v[168:171], v[216:219], v[94:97]
	v_mfma_f32_16x16x32_bf16 v[86:89], v[176:179], v[216:219], v[86:89]
	v_mfma_f32_16x16x32_bf16 v[78:81], v[168:171], v[224:227], v[78:81]
	v_mfma_f32_16x16x32_bf16 v[70:73], v[176:179], v[224:227], v[70:73]
	s_setprio 0
	s_setprio 1
	v_mfma_f32_16x16x32_bf16 v[126:129], v[180:183], v[196:199], v[126:129]
	v_mfma_f32_16x16x32_bf16 v[114:117], v[188:191], v[196:199], v[114:117]
	v_mfma_f32_16x16x32_bf16 v[106:109], v[180:183], v[204:207], v[106:109]
	v_mfma_f32_16x16x32_bf16 v[98:101], v[188:191], v[204:207], v[98:101]
	v_mfma_f32_16x16x32_bf16 v[90:93], v[180:183], v[212:215], v[90:93]
	v_mfma_f32_16x16x32_bf16 v[82:85], v[188:191], v[212:215], v[82:85]
	v_mfma_f32_16x16x32_bf16 v[74:77], v[180:183], v[220:223], v[74:77]
	v_mfma_f32_16x16x32_bf16 v[66:69], v[188:191], v[220:223], v[66:69]
	v_mfma_f32_16x16x32_bf16 v[126:129], v[184:187], v[200:203], v[126:129]
	v_mfma_f32_16x16x32_bf16 v[114:117], v[192:195], v[200:203], v[114:117]
	v_mfma_f32_16x16x32_bf16 v[106:109], v[184:187], v[208:211], v[106:109]
	v_mfma_f32_16x16x32_bf16 v[98:101], v[192:195], v[208:211], v[98:101]
	v_mfma_f32_16x16x32_bf16 v[90:93], v[184:187], v[216:219], v[90:93]
	v_mfma_f32_16x16x32_bf16 v[82:85], v[192:195], v[216:219], v[82:85]
	v_mfma_f32_16x16x32_bf16 v[74:77], v[184:187], v[224:227], v[74:77]
	v_mfma_f32_16x16x32_bf16 v[66:69], v[192:195], v[224:227], v[66:69]
	s_setprio 0
	s_barrier
	s_add_i32 s6, s6, s23
	v_lshl_add_u64 v[150:151], v[150:151], 0, s[14:15]
	s_mov_b32 m0, s6
	ds_read_b128 v[196:199], v160 offset:49152
	ds_read_b128 v[200:203], v160 offset:50176
	ds_read_b128 v[204:207], v160 offset:51200
	ds_read_b128 v[208:211], v160 offset:52224
	ds_read_b128 v[212:215], v160 offset:53248
	ds_read_b128 v[216:219], v160 offset:54272
	ds_read_b128 v[220:223], v160 offset:55296
	ds_read_b128 v[224:227], v160 offset:56320
	global_load_lds_dwordx4 v[150:151], off
	v_lshl_add_u64 v[150:151], v[232:233], 0, s[14:15]
	s_add_i32 m0, s6, 0x2000
	s_add_i32 s6, s29, s23
	global_load_lds_dwordx4 v[150:151], off
	v_lshl_add_u64 v[150:151], v[230:231], 0, s[16:17]
	v_lshl_add_u64 v[228:229], v[150:151], 0, v[132:133]
	s_mov_b32 m0, s6
	v_lshl_add_u64 v[150:151], v[150:151], 0, v[136:137]
	global_load_lds_dwordx4 v[228:229], off
	s_add_i32 m0, s6, 0x2000
	s_nop 0
	global_load_lds_dwordx4 v[150:151], off
	v_lshl_add_u64 v[150:151], v[234:235], 0, s[14:15]
	s_mov_b32 m0, s59
	s_nop 0
	global_load_lds_dwordx4 v[150:151], off
	v_lshl_add_u64 v[150:151], v[236:237], 0, s[14:15]
	s_mov_b32 m0, s60
	s_nop 0
	global_load_lds_dwordx4 v[150:151], off
	s_waitcnt vmcnt(8)
	s_waitcnt lgkmcnt(0)
	s_barrier
	s_setprio 1
	s_waitcnt lgkmcnt(0)
	v_mfma_f32_16x16x32_bf16 v[62:65], v[164:167], v[196:199], v[62:65]
	v_mfma_f32_16x16x32_bf16 v[54:57], v[172:175], v[196:199], v[54:57]
	v_mfma_f32_16x16x32_bf16 v[46:49], v[164:167], v[204:207], v[46:49]
	v_mfma_f32_16x16x32_bf16 v[38:41], v[172:175], v[204:207], v[38:41]
	v_mfma_f32_16x16x32_bf16 v[30:33], v[164:167], v[212:215], v[30:33]
	v_mfma_f32_16x16x32_bf16 v[22:25], v[172:175], v[212:215], v[22:25]
	v_mfma_f32_16x16x32_bf16 v[14:17], v[164:167], v[220:223], v[14:17]
	v_mfma_f32_16x16x32_bf16 v[6:9], v[172:175], v[220:223], v[6:9]
	v_mfma_f32_16x16x32_bf16 v[62:65], v[168:171], v[200:203], v[62:65]
	v_mfma_f32_16x16x32_bf16 v[54:57], v[176:179], v[200:203], v[54:57]
	v_mfma_f32_16x16x32_bf16 v[46:49], v[168:171], v[208:211], v[46:49]
	v_mfma_f32_16x16x32_bf16 v[38:41], v[176:179], v[208:211], v[38:41]
	v_mfma_f32_16x16x32_bf16 v[30:33], v[168:171], v[216:219], v[30:33]
	v_mfma_f32_16x16x32_bf16 v[22:25], v[176:179], v[216:219], v[22:25]
	v_mfma_f32_16x16x32_bf16 v[14:17], v[168:171], v[224:227], v[14:17]
	v_mfma_f32_16x16x32_bf16 v[6:9], v[176:179], v[224:227], v[6:9]
	s_setprio 0
	s_setprio 1
	v_mfma_f32_16x16x32_bf16 v[58:61], v[180:183], v[196:199], v[58:61]
	v_mfma_f32_16x16x32_bf16 v[50:53], v[188:191], v[196:199], v[50:53]
	v_mfma_f32_16x16x32_bf16 v[42:45], v[180:183], v[204:207], v[42:45]
	v_mfma_f32_16x16x32_bf16 v[34:37], v[188:191], v[204:207], v[34:37]
	v_mfma_f32_16x16x32_bf16 v[26:29], v[180:183], v[212:215], v[26:29]
	v_mfma_f32_16x16x32_bf16 v[18:21], v[188:191], v[212:215], v[18:21]
	v_mfma_f32_16x16x32_bf16 v[10:13], v[180:183], v[220:223], v[10:13]
	v_mfma_f32_16x16x32_bf16 v[2:5], v[188:191], v[220:223], v[2:5]
	v_mfma_f32_16x16x32_bf16 v[58:61], v[184:187], v[200:203], v[58:61]
	v_mfma_f32_16x16x32_bf16 v[50:53], v[192:195], v[200:203], v[50:53]
	v_mfma_f32_16x16x32_bf16 v[42:45], v[184:187], v[208:211], v[42:45]
	v_mfma_f32_16x16x32_bf16 v[34:37], v[192:195], v[208:211], v[34:37]
	v_mfma_f32_16x16x32_bf16 v[26:29], v[184:187], v[216:219], v[26:29]
	v_mfma_f32_16x16x32_bf16 v[18:21], v[192:195], v[216:219], v[18:21]
	v_mfma_f32_16x16x32_bf16 v[10:13], v[184:187], v[224:227], v[10:13]
	v_mfma_f32_16x16x32_bf16 v[2:5], v[192:195], v[224:227], v[2:5]
	s_setprio 0
	s_barrier
	v_cmp_ge_i32_e32 vcc, s7, v156
	v_lshl_add_u64 v[152:153], v[152:153], 0, s[20:21]
	v_mov_b64_e32 v[150:151], v[154:155]
	s_mov_b32 s6, s7
	s_cbranch_vccnz .Lmy_kexit_7

.LBB0_1571:
	v_cmp_gt_i32_e32 vcc, 1, v141
	s_cbranch_vccnz .LBB0_1633
	v_lshl_add_u64 v[154:155], v[2:3], 0, s[18:19]
	v_add_u32_e32 v138, -2, v141
	v_lshl_add_u64 v[152:153], v[4:5], 0, s[22:23]
	s_mov_b32 s7, 0
	v_add_u32_e32 v146, s71, v160
	ds_read_b128 v[156:159], v146
	ds_read_b128 v[166:169], v146 offset:1024
	ds_read_b128 v[170:173], v146 offset:2048
	ds_read_b128 v[174:177], v146 offset:3072
	v_add_u32_e32 v146, s72, v160
	ds_read_b128 v[178:181], v146
	ds_read_b128 v[182:185], v146 offset:1024
	ds_read_b128 v[186:189], v146 offset:2048
	ds_read_b128 v[190:193], v146 offset:3072
	v_lshl_add_u64 v[194:195], v[154:155], 0, s[24:25]
	v_cmp_eq_u32_e32 vcc, s7, v138
	s_add_i32 s47, s7, 2
	s_nop 0
	v_cndmask_b32_e32 v227, v195, v149, vcc
	v_cndmask_b32_e32 v226, v194, v148, vcc
	v_cndmask_b32_e32 v229, v153, v151, vcc
	v_cndmask_b32_e32 v228, v152, v150, vcc
	s_mov_b32 m0, s74
	v_lshl_add_u64 v[230:231], v[154:155], 0, v[144:145]
	ds_read_b128 v[194:197], v163
	ds_read_b128 v[198:201], v163 offset:1024
	ds_read_b128 v[202:205], v163 offset:2048
	ds_read_b128 v[206:209], v163 offset:3072
	ds_read_b128 v[210:213], v163 offset:4096
	ds_read_b128 v[214:217], v163 offset:5120
	ds_read_b128 v[218:221], v163 offset:6144
	ds_read_b128 v[222:225], v163 offset:7168
	global_load_lds_dwordx4 v[230:231], off
	v_lshl_add_u64 v[230:231], v[154:155], 0, v[142:143]
	s_mov_b32 m0, s75
	s_nop 0
	global_load_lds_dwordx4 v[230:231], off
	s_waitcnt vmcnt(8)
	s_waitcnt lgkmcnt(0)
	s_barrier
	s_setprio 1
	s_waitcnt lgkmcnt(0)
	v_mfma_f32_16x16x32_bf16 v[122:125], v[156:159], v[194:197], 0
	v_mfma_f32_16x16x32_bf16 v[118:121], v[170:173], v[194:197], 0
	v_mfma_f32_16x16x32_bf16 v[110:113], v[156:159], v[202:205], 0
	v_mfma_f32_16x16x32_bf16 v[102:105], v[170:173], v[202:205], 0
	v_mfma_f32_16x16x32_bf16 v[94:97], v[156:159], v[210:213], 0
	v_mfma_f32_16x16x32_bf16 v[86:89], v[170:173], v[210:213], 0
	v_mfma_f32_16x16x32_bf16 v[78:81], v[156:159], v[218:221], 0
	v_mfma_f32_16x16x32_bf16 v[70:73], v[170:173], v[218:221], 0
	v_mfma_f32_16x16x32_bf16 v[122:125], v[166:169], v[198:201], v[122:125]
	v_mfma_f32_16x16x32_bf16 v[118:121], v[174:177], v[198:201], v[118:121]
	v_mfma_f32_16x16x32_bf16 v[110:113], v[166:169], v[206:209], v[110:113]
	v_mfma_f32_16x16x32_bf16 v[102:105], v[174:177], v[206:209], v[102:105]
	v_mfma_f32_16x16x32_bf16 v[94:97], v[166:169], v[214:217], v[94:97]
	v_mfma_f32_16x16x32_bf16 v[86:89], v[174:177], v[214:217], v[86:89]
	v_mfma_f32_16x16x32_bf16 v[78:81], v[166:169], v[222:225], v[78:81]
	v_mfma_f32_16x16x32_bf16 v[70:73], v[174:177], v[222:225], v[70:73]
	s_setprio 0
	s_setprio 1
	v_mfma_f32_16x16x32_bf16 v[126:129], v[178:181], v[194:197], 0
	v_mfma_f32_16x16x32_bf16 v[114:117], v[186:189], v[194:197], 0
	v_mfma_f32_16x16x32_bf16 v[106:109], v[178:181], v[202:205], 0
	v_mfma_f32_16x16x32_bf16 v[98:101], v[186:189], v[202:205], 0
	v_mfma_f32_16x16x32_bf16 v[90:93], v[178:181], v[210:213], 0
	v_mfma_f32_16x16x32_bf16 v[82:85], v[186:189], v[210:213], 0
	v_mfma_f32_16x16x32_bf16 v[74:77], v[178:181], v[218:221], 0
	v_mfma_f32_16x16x32_bf16 v[66:69], v[186:189], v[218:221], 0
	v_mfma_f32_16x16x32_bf16 v[126:129], v[182:185], v[198:201], v[126:129]
	v_mfma_f32_16x16x32_bf16 v[114:117], v[190:193], v[198:201], v[114:117]
	v_mfma_f32_16x16x32_bf16 v[106:109], v[182:185], v[206:209], v[106:109]
	v_mfma_f32_16x16x32_bf16 v[98:101], v[190:193], v[206:209], v[98:101]
	v_mfma_f32_16x16x32_bf16 v[90:93], v[182:185], v[214:217], v[90:93]
	v_mfma_f32_16x16x32_bf16 v[82:85], v[190:193], v[214:217], v[82:85]
	v_mfma_f32_16x16x32_bf16 v[74:77], v[182:185], v[222:225], v[74:77]
	v_mfma_f32_16x16x32_bf16 v[66:69], v[190:193], v[222:225], v[66:69]
	s_setprio 0
	s_barrier
	s_add_i32 s7, s71, s29
	v_lshl_add_u64 v[230:231], v[228:229], 0, v[132:133]
	s_mov_b32 m0, s7
	ds_read_b128 v[194:197], v163 offset:16384
	ds_read_b128 v[198:201], v163 offset:17408
	ds_read_b128 v[202:205], v163 offset:18432
	ds_read_b128 v[206:209], v163 offset:19456
	ds_read_b128 v[210:213], v163 offset:20480
	ds_read_b128 v[214:217], v163 offset:21504
	ds_read_b128 v[218:221], v163 offset:22528
	ds_read_b128 v[222:225], v163 offset:23552
	global_load_lds_dwordx4 v[230:231], off
	v_lshl_add_u64 v[232:233], v[228:229], 0, v[136:137]
	s_add_i32 m0, s7, 0x2000
	v_lshl_add_u64 v[234:235], v[228:229], 0, s[10:11]
	s_add_i32 s7, s72, s29
	global_load_lds_dwordx4 v[232:233], off
	v_lshl_add_u64 v[236:237], v[234:235], 0, v[132:133]
	s_mov_b32 m0, s7
	v_lshl_add_u64 v[234:235], v[234:235], 0, v[136:137]
	global_load_lds_dwordx4 v[236:237], off
	s_add_i32 m0, s7, 0x2000
	v_lshl_add_u64 v[236:237], v[226:227], 0, v[134:135]
	global_load_lds_dwordx4 v[234:235], off
	v_lshl_add_u64 v[234:235], v[226:227], 0, v[130:131]
	s_mov_b32 m0, s51
	s_nop 0
	global_load_lds_dwordx4 v[234:235], off
	s_mov_b32 m0, s60
	s_nop 0
	global_load_lds_dwordx4 v[236:237], off
	s_waitcnt vmcnt(8)
	s_waitcnt lgkmcnt(0)
	s_barrier
	s_setprio 1
	s_waitcnt lgkmcnt(0)
	v_mfma_f32_16x16x32_bf16 v[62:65], v[156:159], v[194:197], 0
	v_mfma_f32_16x16x32_bf16 v[54:57], v[170:173], v[194:197], 0
	v_mfma_f32_16x16x32_bf16 v[46:49], v[156:159], v[202:205], 0
	v_mfma_f32_16x16x32_bf16 v[38:41], v[170:173], v[202:205], 0
	v_mfma_f32_16x16x32_bf16 v[30:33], v[156:159], v[210:213], 0
	v_mfma_f32_16x16x32_bf16 v[22:25], v[170:173], v[210:213], 0
	v_mfma_f32_16x16x32_bf16 v[14:17], v[156:159], v[218:221], 0
	v_mfma_f32_16x16x32_bf16 v[6:9], v[170:173], v[218:221], 0
	v_mfma_f32_16x16x32_bf16 v[62:65], v[166:169], v[198:201], v[62:65]
	v_mfma_f32_16x16x32_bf16 v[54:57], v[174:177], v[198:201], v[54:57]
	v_mfma_f32_16x16x32_bf16 v[46:49], v[166:169], v[206:209], v[46:49]
	v_mfma_f32_16x16x32_bf16 v[38:41], v[174:177], v[206:209], v[38:41]
	v_mfma_f32_16x16x32_bf16 v[30:33], v[166:169], v[214:217], v[30:33]
	v_mfma_f32_16x16x32_bf16 v[22:25], v[174:177], v[214:217], v[22:25]
	v_mfma_f32_16x16x32_bf16 v[14:17], v[166:169], v[222:225], v[14:17]
	v_mfma_f32_16x16x32_bf16 v[6:9], v[174:177], v[222:225], v[6:9]
	s_setprio 0
	s_setprio 1
	v_mfma_f32_16x16x32_bf16 v[58:61], v[178:181], v[194:197], 0
	v_mfma_f32_16x16x32_bf16 v[50:53], v[186:189], v[194:197], 0
	v_mfma_f32_16x16x32_bf16 v[42:45], v[178:181], v[202:205], 0
	v_mfma_f32_16x16x32_bf16 v[34:37], v[186:189], v[202:205], 0
	v_mfma_f32_16x16x32_bf16 v[26:29], v[178:181], v[210:213], 0
	v_mfma_f32_16x16x32_bf16 v[18:21], v[186:189], v[210:213], 0
	v_mfma_f32_16x16x32_bf16 v[10:13], v[178:181], v[218:221], 0
	v_mfma_f32_16x16x32_bf16 v[2:5], v[186:189], v[218:221], 0
	v_mfma_f32_16x16x32_bf16 v[58:61], v[182:185], v[198:201], v[58:61]
	v_mfma_f32_16x16x32_bf16 v[50:53], v[190:193], v[198:201], v[50:53]
	v_mfma_f32_16x16x32_bf16 v[42:45], v[182:185], v[206:209], v[42:45]
	v_mfma_f32_16x16x32_bf16 v[34:37], v[190:193], v[206:209], v[34:37]
	v_mfma_f32_16x16x32_bf16 v[26:29], v[182:185], v[214:217], v[26:29]
	v_mfma_f32_16x16x32_bf16 v[18:21], v[190:193], v[214:217], v[18:21]
	v_mfma_f32_16x16x32_bf16 v[10:13], v[182:185], v[222:225], v[10:13]
	v_mfma_f32_16x16x32_bf16 v[2:5], v[190:193], v[222:225], v[2:5]
	s_setprio 0
	s_barrier
	s_add_i32 s7, 0, 0x18000
	v_add_u32_e32 v146, s7, v160
	s_add_i32 s49, 0, 0x1c000
	ds_read_b128 v[156:159], v146
	ds_read_b128 v[166:169], v146 offset:1024
	ds_read_b128 v[170:173], v146 offset:2048
	ds_read_b128 v[174:177], v146 offset:3072
	v_add_u32_e32 v146, s49, v160
	ds_read_b128 v[178:181], v146
	ds_read_b128 v[182:185], v146 offset:1024
	ds_read_b128 v[186:189], v146 offset:2048
	ds_read_b128 v[190:193], v146 offset:3072
	v_lshl_add_u64 v[226:227], v[226:227], 0, s[10:11]
	s_mov_b32 m0, s61
	v_lshl_add_u64 v[238:239], v[226:227], 0, v[130:131]
	ds_read_b128 v[194:197], v163 offset:32768
	ds_read_b128 v[198:201], v163 offset:33792
	ds_read_b128 v[202:205], v163 offset:34816
	ds_read_b128 v[206:209], v163 offset:35840
	ds_read_b128 v[210:213], v163 offset:36864
	ds_read_b128 v[214:217], v163 offset:37888
	ds_read_b128 v[218:221], v163 offset:38912
	ds_read_b128 v[222:225], v163 offset:39936
	global_load_lds_dwordx4 v[238:239], off
	v_lshl_add_u64 v[226:227], v[226:227], 0, v[134:135]
	s_mov_b32 m0, s62
	s_nop 0
	global_load_lds_dwordx4 v[226:227], off
	s_waitcnt vmcnt(8)
	s_waitcnt lgkmcnt(0)
	s_barrier
	s_setprio 1
	s_waitcnt lgkmcnt(0)
	v_mfma_f32_16x16x32_bf16 v[122:125], v[156:159], v[194:197], v[122:125]
	v_mfma_f32_16x16x32_bf16 v[118:121], v[170:173], v[194:197], v[118:121]
	v_mfma_f32_16x16x32_bf16 v[110:113], v[156:159], v[202:205], v[110:113]
	v_mfma_f32_16x16x32_bf16 v[102:105], v[170:173], v[202:205], v[102:105]
	v_mfma_f32_16x16x32_bf16 v[94:97], v[156:159], v[210:213], v[94:97]
	v_mfma_f32_16x16x32_bf16 v[86:89], v[170:173], v[210:213], v[86:89]
	v_mfma_f32_16x16x32_bf16 v[78:81], v[156:159], v[218:221], v[78:81]
	v_mfma_f32_16x16x32_bf16 v[70:73], v[170:173], v[218:221], v[70:73]
	v_mfma_f32_16x16x32_bf16 v[122:125], v[166:169], v[198:201], v[122:125]
	v_mfma_f32_16x16x32_bf16 v[118:121], v[174:177], v[198:201], v[118:121]
	v_mfma_f32_16x16x32_bf16 v[110:113], v[166:169], v[206:209], v[110:113]
	v_mfma_f32_16x16x32_bf16 v[102:105], v[174:177], v[206:209], v[102:105]
	v_mfma_f32_16x16x32_bf16 v[94:97], v[166:169], v[214:217], v[94:97]
	v_mfma_f32_16x16x32_bf16 v[86:89], v[174:177], v[214:217], v[86:89]
	v_mfma_f32_16x16x32_bf16 v[78:81], v[166:169], v[222:225], v[78:81]
	v_mfma_f32_16x16x32_bf16 v[70:73], v[174:177], v[222:225], v[70:73]
	s_setprio 0
	s_setprio 1
	v_mfma_f32_16x16x32_bf16 v[126:129], v[178:181], v[194:197], v[126:129]
	v_mfma_f32_16x16x32_bf16 v[114:117], v[186:189], v[194:197], v[114:117]
	v_mfma_f32_16x16x32_bf16 v[106:109], v[178:181], v[202:205], v[106:109]
	v_mfma_f32_16x16x32_bf16 v[98:101], v[186:189], v[202:205], v[98:101]
	v_mfma_f32_16x16x32_bf16 v[90:93], v[178:181], v[210:213], v[90:93]
	v_mfma_f32_16x16x32_bf16 v[82:85], v[186:189], v[210:213], v[82:85]
	v_mfma_f32_16x16x32_bf16 v[74:77], v[178:181], v[218:221], v[74:77]
	v_mfma_f32_16x16x32_bf16 v[66:69], v[186:189], v[218:221], v[66:69]
	v_mfma_f32_16x16x32_bf16 v[126:129], v[182:185], v[198:201], v[126:129]
	v_mfma_f32_16x16x32_bf16 v[114:117], v[190:193], v[198:201], v[114:117]
	v_mfma_f32_16x16x32_bf16 v[106:109], v[182:185], v[206:209], v[106:109]
	v_mfma_f32_16x16x32_bf16 v[98:101], v[190:193], v[206:209], v[98:101]
	v_mfma_f32_16x16x32_bf16 v[90:93], v[182:185], v[214:217], v[90:93]
	v_mfma_f32_16x16x32_bf16 v[82:85], v[190:193], v[214:217], v[82:85]
	v_mfma_f32_16x16x32_bf16 v[74:77], v[182:185], v[222:225], v[74:77]
	v_mfma_f32_16x16x32_bf16 v[66:69], v[190:193], v[222:225], v[66:69]
	s_setprio 0
	s_barrier
	s_add_i32 s7, s7, s29
	v_lshl_add_u64 v[226:227], v[230:231], 0, s[16:17]
	s_mov_b32 m0, s7
	ds_read_b128 v[194:197], v163 offset:49152
	ds_read_b128 v[198:201], v163 offset:50176
	ds_read_b128 v[202:205], v163 offset:51200
	ds_read_b128 v[206:209], v163 offset:52224
	ds_read_b128 v[210:213], v163 offset:53248
	ds_read_b128 v[214:217], v163 offset:54272
	ds_read_b128 v[218:221], v163 offset:55296
	ds_read_b128 v[222:225], v163 offset:56320
	global_load_lds_dwordx4 v[226:227], off
	v_lshl_add_u64 v[226:227], v[232:233], 0, s[16:17]
	s_add_i32 m0, s7, 0x2000
	s_add_i32 s7, s49, s29
	global_load_lds_dwordx4 v[226:227], off
	v_lshl_add_u64 v[226:227], v[228:229], 0, s[18:19]
	v_lshl_add_u64 v[228:229], v[226:227], 0, v[132:133]
	s_mov_b32 m0, s7
	v_lshl_add_u64 v[226:227], v[226:227], 0, v[136:137]
	global_load_lds_dwordx4 v[228:229], off
	s_add_i32 m0, s7, 0x2000
	s_nop 0
	global_load_lds_dwordx4 v[226:227], off
	v_lshl_add_u64 v[226:227], v[234:235], 0, s[16:17]
	s_mov_b32 m0, s63
	s_nop 0
	global_load_lds_dwordx4 v[226:227], off
	v_lshl_add_u64 v[226:227], v[236:237], 0, s[16:17]
	s_mov_b32 m0, s64
	s_nop 0
	global_load_lds_dwordx4 v[226:227], off
	s_waitcnt vmcnt(8)
	s_waitcnt lgkmcnt(0)
	s_barrier
	s_setprio 1
	s_waitcnt lgkmcnt(0)
	v_mfma_f32_16x16x32_bf16 v[62:65], v[156:159], v[194:197], v[62:65]
	v_mfma_f32_16x16x32_bf16 v[54:57], v[170:173], v[194:197], v[54:57]
	v_mfma_f32_16x16x32_bf16 v[46:49], v[156:159], v[202:205], v[46:49]
	v_mfma_f32_16x16x32_bf16 v[38:41], v[170:173], v[202:205], v[38:41]
	v_mfma_f32_16x16x32_bf16 v[30:33], v[156:159], v[210:213], v[30:33]
	v_mfma_f32_16x16x32_bf16 v[22:25], v[170:173], v[210:213], v[22:25]
	v_mfma_f32_16x16x32_bf16 v[14:17], v[156:159], v[218:221], v[14:17]
	v_mfma_f32_16x16x32_bf16 v[6:9], v[170:173], v[218:221], v[6:9]
	v_mfma_f32_16x16x32_bf16 v[62:65], v[166:169], v[198:201], v[62:65]
	v_mfma_f32_16x16x32_bf16 v[54:57], v[174:177], v[198:201], v[54:57]
	v_mfma_f32_16x16x32_bf16 v[46:49], v[166:169], v[206:209], v[46:49]
	v_mfma_f32_16x16x32_bf16 v[38:41], v[174:177], v[206:209], v[38:41]
	v_mfma_f32_16x16x32_bf16 v[30:33], v[166:169], v[214:217], v[30:33]
	v_mfma_f32_16x16x32_bf16 v[22:25], v[174:177], v[214:217], v[22:25]
	v_mfma_f32_16x16x32_bf16 v[14:17], v[166:169], v[222:225], v[14:17]
	v_mfma_f32_16x16x32_bf16 v[6:9], v[174:177], v[222:225], v[6:9]
	s_setprio 0
	s_setprio 1
	v_mfma_f32_16x16x32_bf16 v[58:61], v[178:181], v[194:197], v[58:61]
	v_mfma_f32_16x16x32_bf16 v[50:53], v[186:189], v[194:197], v[50:53]
	v_mfma_f32_16x16x32_bf16 v[42:45], v[178:181], v[202:205], v[42:45]
	v_mfma_f32_16x16x32_bf16 v[34:37], v[186:189], v[202:205], v[34:37]
	v_mfma_f32_16x16x32_bf16 v[26:29], v[178:181], v[210:213], v[26:29]
	v_mfma_f32_16x16x32_bf16 v[18:21], v[186:189], v[210:213], v[18:21]
	v_mfma_f32_16x16x32_bf16 v[10:13], v[178:181], v[218:221], v[10:13]
	v_mfma_f32_16x16x32_bf16 v[2:5], v[186:189], v[218:221], v[2:5]
	v_mfma_f32_16x16x32_bf16 v[58:61], v[182:185], v[198:201], v[58:61]
	v_mfma_f32_16x16x32_bf16 v[50:53], v[190:193], v[198:201], v[50:53]
	v_mfma_f32_16x16x32_bf16 v[42:45], v[182:185], v[206:209], v[42:45]
	v_mfma_f32_16x16x32_bf16 v[34:37], v[190:193], v[206:209], v[34:37]
	v_mfma_f32_16x16x32_bf16 v[26:29], v[182:185], v[214:217], v[26:29]
	v_mfma_f32_16x16x32_bf16 v[18:21], v[190:193], v[214:217], v[18:21]
	v_mfma_f32_16x16x32_bf16 v[10:13], v[182:185], v[222:225], v[10:13]
	v_mfma_f32_16x16x32_bf16 v[2:5], v[190:193], v[222:225], v[2:5]
	s_setprio 0
	s_barrier
	v_cmp_ge_i32_e32 vcc, s47, v141
	v_lshl_add_u64 v[152:153], v[152:153], 0, s[22:23]
	v_lshl_add_u64 v[154:155], v[154:155], 0, s[22:23]
	s_mov_b32 s7, s47
	s_cbranch_vccnz .Lmy_kexit_8

.LBB0_1761:
	v_cmp_gt_i32_e32 vcc, 1, v138
	s_cbranch_vccnz .LBB0_1823
	v_lshl_add_u64 v[152:153], v[2:3], 0, s[14:15]
	v_add_u32_e32 v154, -2, v138
	s_waitcnt lgkmcnt(0)
	v_lshl_add_u64 v[150:151], v[4:5], 0, s[18:19]
	s_mov_b32 s5, 0
	v_add_u32_e32 v155, s74, v141
	ds_read_b128 v[164:167], v155
	ds_read_b128 v[168:171], v155 offset:1024
	ds_read_b128 v[172:175], v155 offset:2048
	ds_read_b128 v[176:179], v155 offset:3072
	v_add_u32_e32 v155, s75, v141
	ds_read_b128 v[180:183], v155
	ds_read_b128 v[184:187], v155 offset:1024
	ds_read_b128 v[188:191], v155 offset:2048
	ds_read_b128 v[192:195], v155 offset:3072
	v_lshl_add_u64 v[156:157], v[152:153], 0, s[20:21]
	v_cmp_eq_u32_e32 vcc, s5, v154
	s_add_i32 s29, s5, 2
	s_nop 0
	v_cndmask_b32_e32 v157, v157, v147, vcc
	v_cndmask_b32_e32 v156, v156, v146, vcc
	v_cndmask_b32_e32 v229, v151, v149, vcc
	v_cndmask_b32_e32 v228, v150, v148, vcc
	v_lshl_add_u64 v[230:231], v[152:153], 0, v[144:145]
	s_add_i32 m0, s47, 0xc000
	ds_read_b128 v[196:199], v160
	ds_read_b128 v[200:203], v160 offset:1024
	ds_read_b128 v[204:207], v160 offset:2048
	ds_read_b128 v[208:211], v160 offset:3072
	ds_read_b128 v[212:215], v160 offset:4096
	ds_read_b128 v[216:219], v160 offset:5120
	ds_read_b128 v[220:223], v160 offset:6144
	ds_read_b128 v[224:227], v160 offset:7168
	global_load_lds_dwordx4 v[230:231], off
	v_lshl_add_u64 v[230:231], v[152:153], 0, v[142:143]
	s_add_i32 m0, s47, 0xe000
	s_nop 0
	global_load_lds_dwordx4 v[230:231], off
	s_waitcnt vmcnt(8)
	s_waitcnt lgkmcnt(0)
	s_barrier
	s_setprio 1
	s_waitcnt lgkmcnt(0)
	v_mfma_f32_16x16x32_bf16 v[122:125], v[164:167], v[196:199], 0
	v_mfma_f32_16x16x32_bf16 v[118:121], v[172:175], v[196:199], 0
	v_mfma_f32_16x16x32_bf16 v[110:113], v[164:167], v[204:207], 0
	v_mfma_f32_16x16x32_bf16 v[102:105], v[172:175], v[204:207], 0
	v_mfma_f32_16x16x32_bf16 v[94:97], v[164:167], v[212:215], 0
	v_mfma_f32_16x16x32_bf16 v[86:89], v[172:175], v[212:215], 0
	v_mfma_f32_16x16x32_bf16 v[78:81], v[164:167], v[220:223], 0
	v_mfma_f32_16x16x32_bf16 v[70:73], v[172:175], v[220:223], 0
	v_mfma_f32_16x16x32_bf16 v[122:125], v[168:171], v[200:203], v[122:125]
	v_mfma_f32_16x16x32_bf16 v[118:121], v[176:179], v[200:203], v[118:121]
	v_mfma_f32_16x16x32_bf16 v[110:113], v[168:171], v[208:211], v[110:113]
	v_mfma_f32_16x16x32_bf16 v[102:105], v[176:179], v[208:211], v[102:105]
	v_mfma_f32_16x16x32_bf16 v[94:97], v[168:171], v[216:219], v[94:97]
	v_mfma_f32_16x16x32_bf16 v[86:89], v[176:179], v[216:219], v[86:89]
	v_mfma_f32_16x16x32_bf16 v[78:81], v[168:171], v[224:227], v[78:81]
	v_mfma_f32_16x16x32_bf16 v[70:73], v[176:179], v[224:227], v[70:73]
	s_setprio 0
	s_setprio 1
	v_mfma_f32_16x16x32_bf16 v[126:129], v[180:183], v[196:199], 0
	v_mfma_f32_16x16x32_bf16 v[114:117], v[188:191], v[196:199], 0
	v_mfma_f32_16x16x32_bf16 v[106:109], v[180:183], v[204:207], 0
	v_mfma_f32_16x16x32_bf16 v[98:101], v[188:191], v[204:207], 0
	v_mfma_f32_16x16x32_bf16 v[90:93], v[180:183], v[212:215], 0
	v_mfma_f32_16x16x32_bf16 v[82:85], v[188:191], v[212:215], 0
	v_mfma_f32_16x16x32_bf16 v[74:77], v[180:183], v[220:223], 0
	v_mfma_f32_16x16x32_bf16 v[66:69], v[188:191], v[220:223], 0
	v_mfma_f32_16x16x32_bf16 v[126:129], v[184:187], v[200:203], v[126:129]
	v_mfma_f32_16x16x32_bf16 v[114:117], v[192:195], v[200:203], v[114:117]
	v_mfma_f32_16x16x32_bf16 v[106:109], v[184:187], v[208:211], v[106:109]
	v_mfma_f32_16x16x32_bf16 v[98:101], v[192:195], v[208:211], v[98:101]
	v_mfma_f32_16x16x32_bf16 v[90:93], v[184:187], v[216:219], v[90:93]
	v_mfma_f32_16x16x32_bf16 v[82:85], v[192:195], v[216:219], v[82:85]
	v_mfma_f32_16x16x32_bf16 v[74:77], v[184:187], v[224:227], v[74:77]
	v_mfma_f32_16x16x32_bf16 v[66:69], v[192:195], v[224:227], v[66:69]
	s_setprio 0
	s_barrier
	s_add_i32 s5, s74, s23
	v_lshl_add_u64 v[230:231], v[228:229], 0, v[132:133]
	s_mov_b32 m0, s5
	ds_read_b128 v[196:199], v160 offset:16384
	ds_read_b128 v[200:203], v160 offset:17408
	ds_read_b128 v[204:207], v160 offset:18432
	ds_read_b128 v[208:211], v160 offset:19456
	ds_read_b128 v[212:215], v160 offset:20480
	ds_read_b128 v[216:219], v160 offset:21504
	ds_read_b128 v[220:223], v160 offset:22528
	ds_read_b128 v[224:227], v160 offset:23552
	global_load_lds_dwordx4 v[230:231], off
	v_lshl_add_u64 v[232:233], v[228:229], 0, v[136:137]
	s_add_i32 m0, s5, 0x2000
	v_lshl_add_u64 v[234:235], v[228:229], 0, s[8:9]
	s_add_i32 s5, s75, s23
	global_load_lds_dwordx4 v[232:233], off
	v_lshl_add_u64 v[236:237], v[234:235], 0, v[132:133]
	s_mov_b32 m0, s5
	v_lshl_add_u64 v[234:235], v[234:235], 0, v[136:137]
	global_load_lds_dwordx4 v[236:237], off
	s_add_i32 m0, s5, 0x2000
	v_lshl_add_u64 v[236:237], v[156:157], 0, v[134:135]
	global_load_lds_dwordx4 v[234:235], off
	v_lshl_add_u64 v[234:235], v[156:157], 0, v[130:131]
	s_mov_b32 m0, s47
	s_nop 0
	global_load_lds_dwordx4 v[234:235], off
	s_mov_b32 m0, s56
	s_nop 0
	global_load_lds_dwordx4 v[236:237], off
	s_waitcnt vmcnt(8)
	s_waitcnt lgkmcnt(0)
	s_barrier
	s_setprio 1
	s_waitcnt lgkmcnt(0)
	v_mfma_f32_16x16x32_bf16 v[62:65], v[164:167], v[196:199], 0
	v_mfma_f32_16x16x32_bf16 v[54:57], v[172:175], v[196:199], 0
	v_mfma_f32_16x16x32_bf16 v[46:49], v[164:167], v[204:207], 0
	v_mfma_f32_16x16x32_bf16 v[38:41], v[172:175], v[204:207], 0
	v_mfma_f32_16x16x32_bf16 v[30:33], v[164:167], v[212:215], 0
	v_mfma_f32_16x16x32_bf16 v[22:25], v[172:175], v[212:215], 0
	v_mfma_f32_16x16x32_bf16 v[14:17], v[164:167], v[220:223], 0
	v_mfma_f32_16x16x32_bf16 v[6:9], v[172:175], v[220:223], 0
	v_mfma_f32_16x16x32_bf16 v[62:65], v[168:171], v[200:203], v[62:65]
	v_mfma_f32_16x16x32_bf16 v[54:57], v[176:179], v[200:203], v[54:57]
	v_mfma_f32_16x16x32_bf16 v[46:49], v[168:171], v[208:211], v[46:49]
	v_mfma_f32_16x16x32_bf16 v[38:41], v[176:179], v[208:211], v[38:41]
	v_mfma_f32_16x16x32_bf16 v[30:33], v[168:171], v[216:219], v[30:33]
	v_mfma_f32_16x16x32_bf16 v[22:25], v[176:179], v[216:219], v[22:25]
	v_mfma_f32_16x16x32_bf16 v[14:17], v[168:171], v[224:227], v[14:17]
	v_mfma_f32_16x16x32_bf16 v[6:9], v[176:179], v[224:227], v[6:9]
	s_setprio 0
	s_setprio 1
	v_mfma_f32_16x16x32_bf16 v[58:61], v[180:183], v[196:199], 0
	v_mfma_f32_16x16x32_bf16 v[50:53], v[188:191], v[196:199], 0
	v_mfma_f32_16x16x32_bf16 v[42:45], v[180:183], v[204:207], 0
	v_mfma_f32_16x16x32_bf16 v[34:37], v[188:191], v[204:207], 0
	v_mfma_f32_16x16x32_bf16 v[26:29], v[180:183], v[212:215], 0
	v_mfma_f32_16x16x32_bf16 v[18:21], v[188:191], v[212:215], 0
	v_mfma_f32_16x16x32_bf16 v[10:13], v[180:183], v[220:223], 0
	v_mfma_f32_16x16x32_bf16 v[2:5], v[188:191], v[220:223], 0
	v_mfma_f32_16x16x32_bf16 v[58:61], v[184:187], v[200:203], v[58:61]
	v_mfma_f32_16x16x32_bf16 v[50:53], v[192:195], v[200:203], v[50:53]
	v_mfma_f32_16x16x32_bf16 v[42:45], v[184:187], v[208:211], v[42:45]
	v_mfma_f32_16x16x32_bf16 v[34:37], v[192:195], v[208:211], v[34:37]
	v_mfma_f32_16x16x32_bf16 v[26:29], v[184:187], v[216:219], v[26:29]
	v_mfma_f32_16x16x32_bf16 v[18:21], v[192:195], v[216:219], v[18:21]
	v_mfma_f32_16x16x32_bf16 v[10:13], v[184:187], v[224:227], v[10:13]
	v_mfma_f32_16x16x32_bf16 v[2:5], v[192:195], v[224:227], v[2:5]
	s_setprio 0
	s_barrier
	s_add_i32 s5, 0, 0x18000
	v_add_u32_e32 v155, s5, v141
	s_add_i32 s45, 0, 0x1c000
	ds_read_b128 v[164:167], v155
	ds_read_b128 v[168:171], v155 offset:1024
	ds_read_b128 v[172:175], v155 offset:2048
	ds_read_b128 v[176:179], v155 offset:3072
	v_add_u32_e32 v155, s45, v141
	ds_read_b128 v[180:183], v155
	ds_read_b128 v[184:187], v155 offset:1024
	ds_read_b128 v[188:191], v155 offset:2048
	ds_read_b128 v[192:195], v155 offset:3072
	v_lshl_add_u64 v[156:157], v[156:157], 0, s[8:9]
	s_mov_b32 m0, s57
	v_lshl_add_u64 v[238:239], v[156:157], 0, v[130:131]
	ds_read_b128 v[196:199], v160 offset:32768
	ds_read_b128 v[200:203], v160 offset:33792
	ds_read_b128 v[204:207], v160 offset:34816
	ds_read_b128 v[208:211], v160 offset:35840
	ds_read_b128 v[212:215], v160 offset:36864
	ds_read_b128 v[216:219], v160 offset:37888
	ds_read_b128 v[220:223], v160 offset:38912
	ds_read_b128 v[224:227], v160 offset:39936
	global_load_lds_dwordx4 v[238:239], off
	v_lshl_add_u64 v[156:157], v[156:157], 0, v[134:135]
	s_mov_b32 m0, s58
	s_nop 0
	global_load_lds_dwordx4 v[156:157], off
	s_waitcnt vmcnt(8)
	s_waitcnt lgkmcnt(0)
	s_barrier
	s_setprio 1
	s_waitcnt lgkmcnt(0)
	v_mfma_f32_16x16x32_bf16 v[122:125], v[164:167], v[196:199], v[122:125]
	v_mfma_f32_16x16x32_bf16 v[118:121], v[172:175], v[196:199], v[118:121]
	v_mfma_f32_16x16x32_bf16 v[110:113], v[164:167], v[204:207], v[110:113]
	v_mfma_f32_16x16x32_bf16 v[102:105], v[172:175], v[204:207], v[102:105]
	v_mfma_f32_16x16x32_bf16 v[94:97], v[164:167], v[212:215], v[94:97]
	v_mfma_f32_16x16x32_bf16 v[86:89], v[172:175], v[212:215], v[86:89]
	v_mfma_f32_16x16x32_bf16 v[78:81], v[164:167], v[220:223], v[78:81]
	v_mfma_f32_16x16x32_bf16 v[70:73], v[172:175], v[220:223], v[70:73]
	v_mfma_f32_16x16x32_bf16 v[122:125], v[168:171], v[200:203], v[122:125]
	v_mfma_f32_16x16x32_bf16 v[118:121], v[176:179], v[200:203], v[118:121]
	v_mfma_f32_16x16x32_bf16 v[110:113], v[168:171], v[208:211], v[110:113]
	v_mfma_f32_16x16x32_bf16 v[102:105], v[176:179], v[208:211], v[102:105]
	v_mfma_f32_16x16x32_bf16 v[94:97], v[168:171], v[216:219], v[94:97]
	v_mfma_f32_16x16x32_bf16 v[86:89], v[176:179], v[216:219], v[86:89]
	v_mfma_f32_16x16x32_bf16 v[78:81], v[168:171], v[224:227], v[78:81]
	v_mfma_f32_16x16x32_bf16 v[70:73], v[176:179], v[224:227], v[70:73]
	s_setprio 0
	s_setprio 1
	v_mfma_f32_16x16x32_bf16 v[126:129], v[180:183], v[196:199], v[126:129]
	v_mfma_f32_16x16x32_bf16 v[114:117], v[188:191], v[196:199], v[114:117]
	v_mfma_f32_16x16x32_bf16 v[106:109], v[180:183], v[204:207], v[106:109]
	v_mfma_f32_16x16x32_bf16 v[98:101], v[188:191], v[204:207], v[98:101]
	v_mfma_f32_16x16x32_bf16 v[90:93], v[180:183], v[212:215], v[90:93]
	v_mfma_f32_16x16x32_bf16 v[82:85], v[188:191], v[212:215], v[82:85]
	v_mfma_f32_16x16x32_bf16 v[74:77], v[180:183], v[220:223], v[74:77]
	v_mfma_f32_16x16x32_bf16 v[66:69], v[188:191], v[220:223], v[66:69]
	v_mfma_f32_16x16x32_bf16 v[126:129], v[184:187], v[200:203], v[126:129]
	v_mfma_f32_16x16x32_bf16 v[114:117], v[192:195], v[200:203], v[114:117]
	v_mfma_f32_16x16x32_bf16 v[106:109], v[184:187], v[208:211], v[106:109]
	v_mfma_f32_16x16x32_bf16 v[98:101], v[192:195], v[208:211], v[98:101]
	v_mfma_f32_16x16x32_bf16 v[90:93], v[184:187], v[216:219], v[90:93]
	v_mfma_f32_16x16x32_bf16 v[82:85], v[192:195], v[216:219], v[82:85]
	v_mfma_f32_16x16x32_bf16 v[74:77], v[184:187], v[224:227], v[74:77]
	v_mfma_f32_16x16x32_bf16 v[66:69], v[192:195], v[224:227], v[66:69]
	s_setprio 0
	s_barrier
	s_add_i32 s5, s5, s23
	v_lshl_add_u64 v[156:157], v[230:231], 0, s[12:13]
	s_mov_b32 m0, s5
	ds_read_b128 v[196:199], v160 offset:49152
	ds_read_b128 v[200:203], v160 offset:50176
	ds_read_b128 v[204:207], v160 offset:51200
	ds_read_b128 v[208:211], v160 offset:52224
	ds_read_b128 v[212:215], v160 offset:53248
	ds_read_b128 v[216:219], v160 offset:54272
	ds_read_b128 v[220:223], v160 offset:55296
	ds_read_b128 v[224:227], v160 offset:56320
	global_load_lds_dwordx4 v[156:157], off
	v_lshl_add_u64 v[156:157], v[232:233], 0, s[12:13]
	s_add_i32 m0, s5, 0x2000
	s_add_i32 s5, s45, s23
	global_load_lds_dwordx4 v[156:157], off
	v_lshl_add_u64 v[156:157], v[228:229], 0, s[14:15]
	v_lshl_add_u64 v[228:229], v[156:157], 0, v[132:133]
	s_mov_b32 m0, s5
	v_lshl_add_u64 v[156:157], v[156:157], 0, v[136:137]
	global_load_lds_dwordx4 v[228:229], off
	s_add_i32 m0, s5, 0x2000
	s_nop 0
	global_load_lds_dwordx4 v[156:157], off
	v_lshl_add_u64 v[156:157], v[234:235], 0, s[12:13]
	s_mov_b32 m0, s64
	s_nop 0
	global_load_lds_dwordx4 v[156:157], off
	v_lshl_add_u64 v[156:157], v[236:237], 0, s[12:13]
	s_mov_b32 m0, s65
	s_nop 0
	global_load_lds_dwordx4 v[156:157], off
	s_waitcnt vmcnt(8)
	s_waitcnt lgkmcnt(0)
	s_barrier
	s_setprio 1
	s_waitcnt lgkmcnt(0)
	v_mfma_f32_16x16x32_bf16 v[62:65], v[164:167], v[196:199], v[62:65]
	v_mfma_f32_16x16x32_bf16 v[54:57], v[172:175], v[196:199], v[54:57]
	v_mfma_f32_16x16x32_bf16 v[46:49], v[164:167], v[204:207], v[46:49]
	v_mfma_f32_16x16x32_bf16 v[38:41], v[172:175], v[204:207], v[38:41]
	v_mfma_f32_16x16x32_bf16 v[30:33], v[164:167], v[212:215], v[30:33]
	v_mfma_f32_16x16x32_bf16 v[22:25], v[172:175], v[212:215], v[22:25]
	v_mfma_f32_16x16x32_bf16 v[14:17], v[164:167], v[220:223], v[14:17]
	v_mfma_f32_16x16x32_bf16 v[6:9], v[172:175], v[220:223], v[6:9]
	v_mfma_f32_16x16x32_bf16 v[62:65], v[168:171], v[200:203], v[62:65]
	v_mfma_f32_16x16x32_bf16 v[54:57], v[176:179], v[200:203], v[54:57]
	v_mfma_f32_16x16x32_bf16 v[46:49], v[168:171], v[208:211], v[46:49]
	v_mfma_f32_16x16x32_bf16 v[38:41], v[176:179], v[208:211], v[38:41]
	v_mfma_f32_16x16x32_bf16 v[30:33], v[168:171], v[216:219], v[30:33]
	v_mfma_f32_16x16x32_bf16 v[22:25], v[176:179], v[216:219], v[22:25]
	v_mfma_f32_16x16x32_bf16 v[14:17], v[168:171], v[224:227], v[14:17]
	v_mfma_f32_16x16x32_bf16 v[6:9], v[176:179], v[224:227], v[6:9]
	s_setprio 0
	s_setprio 1
	v_mfma_f32_16x16x32_bf16 v[58:61], v[180:183], v[196:199], v[58:61]
	v_mfma_f32_16x16x32_bf16 v[50:53], v[188:191], v[196:199], v[50:53]
	v_mfma_f32_16x16x32_bf16 v[42:45], v[180:183], v[204:207], v[42:45]
	v_mfma_f32_16x16x32_bf16 v[34:37], v[188:191], v[204:207], v[34:37]
	v_mfma_f32_16x16x32_bf16 v[26:29], v[180:183], v[212:215], v[26:29]
	v_mfma_f32_16x16x32_bf16 v[18:21], v[188:191], v[212:215], v[18:21]
	v_mfma_f32_16x16x32_bf16 v[10:13], v[180:183], v[220:223], v[10:13]
	v_mfma_f32_16x16x32_bf16 v[2:5], v[188:191], v[220:223], v[2:5]
	v_mfma_f32_16x16x32_bf16 v[58:61], v[184:187], v[200:203], v[58:61]
	v_mfma_f32_16x16x32_bf16 v[50:53], v[192:195], v[200:203], v[50:53]
	v_mfma_f32_16x16x32_bf16 v[42:45], v[184:187], v[208:211], v[42:45]
	v_mfma_f32_16x16x32_bf16 v[34:37], v[192:195], v[208:211], v[34:37]
	v_mfma_f32_16x16x32_bf16 v[26:29], v[184:187], v[216:219], v[26:29]
	v_mfma_f32_16x16x32_bf16 v[18:21], v[192:195], v[216:219], v[18:21]
	v_mfma_f32_16x16x32_bf16 v[10:13], v[184:187], v[224:227], v[10:13]
	v_mfma_f32_16x16x32_bf16 v[2:5], v[192:195], v[224:227], v[2:5]
	s_setprio 0
	s_barrier
	v_cmp_ge_i32_e32 vcc, s29, v138
	v_lshl_add_u64 v[150:151], v[150:151], 0, s[18:19]
	v_lshl_add_u64 v[152:153], v[152:153], 0, s[18:19]
	s_mov_b32 s5, s29
	s_cbranch_vccnz .Lmy_kexit_9

.Lmy_kexit_9:
	s_and_b64 vcc, exec, s[16:17]
	s_cbranch_vccz .LBB0_1766

.LBB0_1942:
	v_cmp_gt_i32_e32 vcc, 1, v138
	s_cbranch_vccnz .LBB0_2004
	v_lshl_add_u64 v[152:153], v[2:3], 0, s[16:17]
	v_add_u32_e32 v154, -2, v138
	s_waitcnt lgkmcnt(0)
	v_lshl_add_u64 v[150:151], v[4:5], 0, s[20:21]
	s_mov_b32 s5, 0
	v_add_u32_e32 v155, s72, v141
	ds_read_b128 v[164:167], v155
	ds_read_b128 v[168:171], v155 offset:1024
	ds_read_b128 v[172:175], v155 offset:2048
	ds_read_b128 v[176:179], v155 offset:3072
	v_add_u32_e32 v155, s73, v141
	ds_read_b128 v[180:183], v155
	ds_read_b128 v[184:187], v155 offset:1024
	ds_read_b128 v[188:191], v155 offset:2048
	ds_read_b128 v[192:195], v155 offset:3072
	v_lshl_add_u64 v[156:157], v[152:153], 0, s[22:23]
	v_cmp_eq_u32_e32 vcc, s5, v154
	s_add_i32 s45, s5, 2
	s_nop 0
	v_cndmask_b32_e32 v157, v157, v147, vcc
	v_cndmask_b32_e32 v156, v156, v146, vcc
	v_cndmask_b32_e32 v229, v151, v149, vcc
	v_cndmask_b32_e32 v228, v150, v148, vcc
	s_mov_b32 m0, s74
	v_lshl_add_u64 v[230:231], v[152:153], 0, v[144:145]
	ds_read_b128 v[196:199], v160
	ds_read_b128 v[200:203], v160 offset:1024
	ds_read_b128 v[204:207], v160 offset:2048
	ds_read_b128 v[208:211], v160 offset:3072
	ds_read_b128 v[212:215], v160 offset:4096
	ds_read_b128 v[216:219], v160 offset:5120
	ds_read_b128 v[220:223], v160 offset:6144
	ds_read_b128 v[224:227], v160 offset:7168
	global_load_lds_dwordx4 v[230:231], off
	v_lshl_add_u64 v[230:231], v[152:153], 0, v[142:143]
	s_mov_b32 m0, s75
	s_nop 0
	global_load_lds_dwordx4 v[230:231], off
	s_waitcnt vmcnt(8)
	s_waitcnt lgkmcnt(0)
	s_barrier
	s_setprio 1
	s_waitcnt lgkmcnt(0)
	v_mfma_f32_16x16x32_bf16 v[122:125], v[164:167], v[196:199], 0
	v_mfma_f32_16x16x32_bf16 v[118:121], v[172:175], v[196:199], 0
	v_mfma_f32_16x16x32_bf16 v[110:113], v[164:167], v[204:207], 0
	v_mfma_f32_16x16x32_bf16 v[102:105], v[172:175], v[204:207], 0
	v_mfma_f32_16x16x32_bf16 v[94:97], v[164:167], v[212:215], 0
	v_mfma_f32_16x16x32_bf16 v[86:89], v[172:175], v[212:215], 0
	v_mfma_f32_16x16x32_bf16 v[78:81], v[164:167], v[220:223], 0
	v_mfma_f32_16x16x32_bf16 v[70:73], v[172:175], v[220:223], 0
	v_mfma_f32_16x16x32_bf16 v[122:125], v[168:171], v[200:203], v[122:125]
	v_mfma_f32_16x16x32_bf16 v[118:121], v[176:179], v[200:203], v[118:121]
	v_mfma_f32_16x16x32_bf16 v[110:113], v[168:171], v[208:211], v[110:113]
	v_mfma_f32_16x16x32_bf16 v[102:105], v[176:179], v[208:211], v[102:105]
	v_mfma_f32_16x16x32_bf16 v[94:97], v[168:171], v[216:219], v[94:97]
	v_mfma_f32_16x16x32_bf16 v[86:89], v[176:179], v[216:219], v[86:89]
	v_mfma_f32_16x16x32_bf16 v[78:81], v[168:171], v[224:227], v[78:81]
	v_mfma_f32_16x16x32_bf16 v[70:73], v[176:179], v[224:227], v[70:73]
	s_setprio 0
	s_setprio 1
	v_mfma_f32_16x16x32_bf16 v[126:129], v[180:183], v[196:199], 0
	v_mfma_f32_16x16x32_bf16 v[114:117], v[188:191], v[196:199], 0
	v_mfma_f32_16x16x32_bf16 v[106:109], v[180:183], v[204:207], 0
	v_mfma_f32_16x16x32_bf16 v[98:101], v[188:191], v[204:207], 0
	v_mfma_f32_16x16x32_bf16 v[90:93], v[180:183], v[212:215], 0
	v_mfma_f32_16x16x32_bf16 v[82:85], v[188:191], v[212:215], 0
	v_mfma_f32_16x16x32_bf16 v[74:77], v[180:183], v[220:223], 0
	v_mfma_f32_16x16x32_bf16 v[66:69], v[188:191], v[220:223], 0
	v_mfma_f32_16x16x32_bf16 v[126:129], v[184:187], v[200:203], v[126:129]
	v_mfma_f32_16x16x32_bf16 v[114:117], v[192:195], v[200:203], v[114:117]
	v_mfma_f32_16x16x32_bf16 v[106:109], v[184:187], v[208:211], v[106:109]
	v_mfma_f32_16x16x32_bf16 v[98:101], v[192:195], v[208:211], v[98:101]
	v_mfma_f32_16x16x32_bf16 v[90:93], v[184:187], v[216:219], v[90:93]
	v_mfma_f32_16x16x32_bf16 v[82:85], v[192:195], v[216:219], v[82:85]
	v_mfma_f32_16x16x32_bf16 v[74:77], v[184:187], v[224:227], v[74:77]
	v_mfma_f32_16x16x32_bf16 v[66:69], v[192:195], v[224:227], v[66:69]
	s_setprio 0
	s_barrier
	s_mov_b32 m0, s76
	v_lshl_add_u64 v[230:231], v[228:229], 0, v[132:133]
	ds_read_b128 v[196:199], v160 offset:16384
	ds_read_b128 v[200:203], v160 offset:17408
	ds_read_b128 v[204:207], v160 offset:18432
	ds_read_b128 v[208:211], v160 offset:19456
	ds_read_b128 v[212:215], v160 offset:20480
	ds_read_b128 v[216:219], v160 offset:21504
	ds_read_b128 v[220:223], v160 offset:22528
	ds_read_b128 v[224:227], v160 offset:23552
	global_load_lds_dwordx4 v[230:231], off
	v_lshl_add_u64 v[232:233], v[228:229], 0, v[136:137]
	s_mov_b32 m0, s77
	v_lshl_add_u64 v[234:235], v[228:229], 0, s[8:9]
	s_add_i32 s5, s73, s25
	global_load_lds_dwordx4 v[232:233], off
	v_lshl_add_u64 v[236:237], v[234:235], 0, v[132:133]
	s_mov_b32 m0, s5
	v_lshl_add_u64 v[234:235], v[234:235], 0, v[136:137]
	global_load_lds_dwordx4 v[236:237], off
	s_add_i32 m0, s5, 0x2000
	v_lshl_add_u64 v[236:237], v[156:157], 0, v[134:135]
	global_load_lds_dwordx4 v[234:235], off
	v_lshl_add_u64 v[234:235], v[156:157], 0, v[130:131]
	s_mov_b32 m0, s49
	s_nop 0
	global_load_lds_dwordx4 v[234:235], off
	s_mov_b32 m0, s58
	s_nop 0
	global_load_lds_dwordx4 v[236:237], off
	s_waitcnt vmcnt(8)
	s_waitcnt lgkmcnt(0)
	s_barrier
	s_setprio 1
	s_waitcnt lgkmcnt(0)
	v_mfma_f32_16x16x32_bf16 v[62:65], v[164:167], v[196:199], 0
	v_mfma_f32_16x16x32_bf16 v[54:57], v[172:175], v[196:199], 0
	v_mfma_f32_16x16x32_bf16 v[46:49], v[164:167], v[204:207], 0
	v_mfma_f32_16x16x32_bf16 v[38:41], v[172:175], v[204:207], 0
	v_mfma_f32_16x16x32_bf16 v[30:33], v[164:167], v[212:215], 0
	v_mfma_f32_16x16x32_bf16 v[22:25], v[172:175], v[212:215], 0
	v_mfma_f32_16x16x32_bf16 v[14:17], v[164:167], v[220:223], 0
	v_mfma_f32_16x16x32_bf16 v[6:9], v[172:175], v[220:223], 0
	v_mfma_f32_16x16x32_bf16 v[62:65], v[168:171], v[200:203], v[62:65]
	v_mfma_f32_16x16x32_bf16 v[54:57], v[176:179], v[200:203], v[54:57]
	v_mfma_f32_16x16x32_bf16 v[46:49], v[168:171], v[208:211], v[46:49]
	v_mfma_f32_16x16x32_bf16 v[38:41], v[176:179], v[208:211], v[38:41]
	v_mfma_f32_16x16x32_bf16 v[30:33], v[168:171], v[216:219], v[30:33]
	v_mfma_f32_16x16x32_bf16 v[22:25], v[176:179], v[216:219], v[22:25]
	v_mfma_f32_16x16x32_bf16 v[14:17], v[168:171], v[224:227], v[14:17]
	v_mfma_f32_16x16x32_bf16 v[6:9], v[176:179], v[224:227], v[6:9]
	s_setprio 0
	s_setprio 1
	v_mfma_f32_16x16x32_bf16 v[58:61], v[180:183], v[196:199], 0
	v_mfma_f32_16x16x32_bf16 v[50:53], v[188:191], v[196:199], 0
	v_mfma_f32_16x16x32_bf16 v[42:45], v[180:183], v[204:207], 0
	v_mfma_f32_16x16x32_bf16 v[34:37], v[188:191], v[204:207], 0
	v_mfma_f32_16x16x32_bf16 v[26:29], v[180:183], v[212:215], 0
	v_mfma_f32_16x16x32_bf16 v[18:21], v[188:191], v[212:215], 0
	v_mfma_f32_16x16x32_bf16 v[10:13], v[180:183], v[220:223], 0
	v_mfma_f32_16x16x32_bf16 v[2:5], v[188:191], v[220:223], 0
	v_mfma_f32_16x16x32_bf16 v[58:61], v[184:187], v[200:203], v[58:61]
	v_mfma_f32_16x16x32_bf16 v[50:53], v[192:195], v[200:203], v[50:53]
	v_mfma_f32_16x16x32_bf16 v[42:45], v[184:187], v[208:211], v[42:45]
	v_mfma_f32_16x16x32_bf16 v[34:37], v[192:195], v[208:211], v[34:37]
	v_mfma_f32_16x16x32_bf16 v[26:29], v[184:187], v[216:219], v[26:29]
	v_mfma_f32_16x16x32_bf16 v[18:21], v[192:195], v[216:219], v[18:21]
	v_mfma_f32_16x16x32_bf16 v[10:13], v[184:187], v[224:227], v[10:13]
	v_mfma_f32_16x16x32_bf16 v[2:5], v[192:195], v[224:227], v[2:5]
	s_setprio 0
	s_barrier
	s_add_i32 s5, 0, 0x18000
	v_add_u32_e32 v155, s5, v141
	s_add_i32 s47, 0, 0x1c000
	ds_read_b128 v[164:167], v155
	ds_read_b128 v[168:171], v155 offset:1024
	ds_read_b128 v[172:175], v155 offset:2048
	ds_read_b128 v[176:179], v155 offset:3072
	v_add_u32_e32 v155, s47, v141
	ds_read_b128 v[180:183], v155
	ds_read_b128 v[184:187], v155 offset:1024
	ds_read_b128 v[188:191], v155 offset:2048
	ds_read_b128 v[192:195], v155 offset:3072
	v_lshl_add_u64 v[156:157], v[156:157], 0, s[8:9]
	s_mov_b32 m0, s59
	v_lshl_add_u64 v[238:239], v[156:157], 0, v[130:131]
	ds_read_b128 v[196:199], v160 offset:32768
	ds_read_b128 v[200:203], v160 offset:33792
	ds_read_b128 v[204:207], v160 offset:34816
	ds_read_b128 v[208:211], v160 offset:35840
	ds_read_b128 v[212:215], v160 offset:36864
	ds_read_b128 v[216:219], v160 offset:37888
	ds_read_b128 v[220:223], v160 offset:38912
	ds_read_b128 v[224:227], v160 offset:39936
	global_load_lds_dwordx4 v[238:239], off
	v_lshl_add_u64 v[156:157], v[156:157], 0, v[134:135]
	s_mov_b32 m0, s60
	s_nop 0
	global_load_lds_dwordx4 v[156:157], off
	s_waitcnt vmcnt(8)
	s_waitcnt lgkmcnt(0)
	s_barrier
	s_setprio 1
	s_waitcnt lgkmcnt(0)
	v_mfma_f32_16x16x32_bf16 v[122:125], v[164:167], v[196:199], v[122:125]
	v_mfma_f32_16x16x32_bf16 v[118:121], v[172:175], v[196:199], v[118:121]
	v_mfma_f32_16x16x32_bf16 v[110:113], v[164:167], v[204:207], v[110:113]
	v_mfma_f32_16x16x32_bf16 v[102:105], v[172:175], v[204:207], v[102:105]
	v_mfma_f32_16x16x32_bf16 v[94:97], v[164:167], v[212:215], v[94:97]
	v_mfma_f32_16x16x32_bf16 v[86:89], v[172:175], v[212:215], v[86:89]
	v_mfma_f32_16x16x32_bf16 v[78:81], v[164:167], v[220:223], v[78:81]
	v_mfma_f32_16x16x32_bf16 v[70:73], v[172:175], v[220:223], v[70:73]
	v_mfma_f32_16x16x32_bf16 v[122:125], v[168:171], v[200:203], v[122:125]
	v_mfma_f32_16x16x32_bf16 v[118:121], v[176:179], v[200:203], v[118:121]
	v_mfma_f32_16x16x32_bf16 v[110:113], v[168:171], v[208:211], v[110:113]
	v_mfma_f32_16x16x32_bf16 v[102:105], v[176:179], v[208:211], v[102:105]
	v_mfma_f32_16x16x32_bf16 v[94:97], v[168:171], v[216:219], v[94:97]
	v_mfma_f32_16x16x32_bf16 v[86:89], v[176:179], v[216:219], v[86:89]
	v_mfma_f32_16x16x32_bf16 v[78:81], v[168:171], v[224:227], v[78:81]
	v_mfma_f32_16x16x32_bf16 v[70:73], v[176:179], v[224:227], v[70:73]
	s_setprio 0
	s_setprio 1
	v_mfma_f32_16x16x32_bf16 v[126:129], v[180:183], v[196:199], v[126:129]
	v_mfma_f32_16x16x32_bf16 v[114:117], v[188:191], v[196:199], v[114:117]
	v_mfma_f32_16x16x32_bf16 v[106:109], v[180:183], v[204:207], v[106:109]
	v_mfma_f32_16x16x32_bf16 v[98:101], v[188:191], v[204:207], v[98:101]
	v_mfma_f32_16x16x32_bf16 v[90:93], v[180:183], v[212:215], v[90:93]
	v_mfma_f32_16x16x32_bf16 v[82:85], v[188:191], v[212:215], v[82:85]
	v_mfma_f32_16x16x32_bf16 v[74:77], v[180:183], v[220:223], v[74:77]
	v_mfma_f32_16x16x32_bf16 v[66:69], v[188:191], v[220:223], v[66:69]
	v_mfma_f32_16x16x32_bf16 v[126:129], v[184:187], v[200:203], v[126:129]
	v_mfma_f32_16x16x32_bf16 v[114:117], v[192:195], v[200:203], v[114:117]
	v_mfma_f32_16x16x32_bf16 v[106:109], v[184:187], v[208:211], v[106:109]
	v_mfma_f32_16x16x32_bf16 v[98:101], v[192:195], v[208:211], v[98:101]
	v_mfma_f32_16x16x32_bf16 v[90:93], v[184:187], v[216:219], v[90:93]
	v_mfma_f32_16x16x32_bf16 v[82:85], v[192:195], v[216:219], v[82:85]
	v_mfma_f32_16x16x32_bf16 v[74:77], v[184:187], v[224:227], v[74:77]
	v_mfma_f32_16x16x32_bf16 v[66:69], v[192:195], v[224:227], v[66:69]
	s_setprio 0
	s_barrier
	s_add_i32 s5, s5, s25
	v_lshl_add_u64 v[156:157], v[230:231], 0, s[14:15]
	s_mov_b32 m0, s5
	ds_read_b128 v[196:199], v160 offset:49152
	ds_read_b128 v[200:203], v160 offset:50176
	ds_read_b128 v[204:207], v160 offset:51200
	ds_read_b128 v[208:211], v160 offset:52224
	ds_read_b128 v[212:215], v160 offset:53248
	ds_read_b128 v[216:219], v160 offset:54272
	ds_read_b128 v[220:223], v160 offset:55296
	ds_read_b128 v[224:227], v160 offset:56320
	global_load_lds_dwordx4 v[156:157], off
	v_lshl_add_u64 v[156:157], v[232:233], 0, s[14:15]
	s_add_i32 m0, s5, 0x2000
	s_add_i32 s5, s47, s25
	global_load_lds_dwordx4 v[156:157], off
	v_lshl_add_u64 v[156:157], v[228:229], 0, s[16:17]
	v_lshl_add_u64 v[228:229], v[156:157], 0, v[132:133]
	s_mov_b32 m0, s5
	v_lshl_add_u64 v[156:157], v[156:157], 0, v[136:137]
	global_load_lds_dwordx4 v[228:229], off
	s_add_i32 m0, s5, 0x2000
	s_nop 0
	global_load_lds_dwordx4 v[156:157], off
	v_lshl_add_u64 v[156:157], v[234:235], 0, s[14:15]
	s_mov_b32 m0, s61
	s_nop 0
	global_load_lds_dwordx4 v[156:157], off
	v_lshl_add_u64 v[156:157], v[236:237], 0, s[14:15]
	s_mov_b32 m0, s62
	s_nop 0
	global_load_lds_dwordx4 v[156:157], off
	s_waitcnt vmcnt(8)
	s_waitcnt lgkmcnt(0)
	s_barrier
	s_setprio 1
	s_waitcnt lgkmcnt(0)
	v_mfma_f32_16x16x32_bf16 v[62:65], v[164:167], v[196:199], v[62:65]
	v_mfma_f32_16x16x32_bf16 v[54:57], v[172:175], v[196:199], v[54:57]
	v_mfma_f32_16x16x32_bf16 v[46:49], v[164:167], v[204:207], v[46:49]
	v_mfma_f32_16x16x32_bf16 v[38:41], v[172:175], v[204:207], v[38:41]
	v_mfma_f32_16x16x32_bf16 v[30:33], v[164:167], v[212:215], v[30:33]
	v_mfma_f32_16x16x32_bf16 v[22:25], v[172:175], v[212:215], v[22:25]
	v_mfma_f32_16x16x32_bf16 v[14:17], v[164:167], v[220:223], v[14:17]
	v_mfma_f32_16x16x32_bf16 v[6:9], v[172:175], v[220:223], v[6:9]
	v_mfma_f32_16x16x32_bf16 v[62:65], v[168:171], v[200:203], v[62:65]
	v_mfma_f32_16x16x32_bf16 v[54:57], v[176:179], v[200:203], v[54:57]
	v_mfma_f32_16x16x32_bf16 v[46:49], v[168:171], v[208:211], v[46:49]
	v_mfma_f32_16x16x32_bf16 v[38:41], v[176:179], v[208:211], v[38:41]
	v_mfma_f32_16x16x32_bf16 v[30:33], v[168:171], v[216:219], v[30:33]
	v_mfma_f32_16x16x32_bf16 v[22:25], v[176:179], v[216:219], v[22:25]
	v_mfma_f32_16x16x32_bf16 v[14:17], v[168:171], v[224:227], v[14:17]
	v_mfma_f32_16x16x32_bf16 v[6:9], v[176:179], v[224:227], v[6:9]
	s_setprio 0
	s_setprio 1
	v_mfma_f32_16x16x32_bf16 v[58:61], v[180:183], v[196:199], v[58:61]
	v_mfma_f32_16x16x32_bf16 v[50:53], v[188:191], v[196:199], v[50:53]
	v_mfma_f32_16x16x32_bf16 v[42:45], v[180:183], v[204:207], v[42:45]
	v_mfma_f32_16x16x32_bf16 v[34:37], v[188:191], v[204:207], v[34:37]
	v_mfma_f32_16x16x32_bf16 v[26:29], v[180:183], v[212:215], v[26:29]
	v_mfma_f32_16x16x32_bf16 v[18:21], v[188:191], v[212:215], v[18:21]
	v_mfma_f32_16x16x32_bf16 v[10:13], v[180:183], v[220:223], v[10:13]
	v_mfma_f32_16x16x32_bf16 v[2:5], v[188:191], v[220:223], v[2:5]
	v_mfma_f32_16x16x32_bf16 v[58:61], v[184:187], v[200:203], v[58:61]
	v_mfma_f32_16x16x32_bf16 v[50:53], v[192:195], v[200:203], v[50:53]
	v_mfma_f32_16x16x32_bf16 v[42:45], v[184:187], v[208:211], v[42:45]
	v_mfma_f32_16x16x32_bf16 v[34:37], v[192:195], v[208:211], v[34:37]
	v_mfma_f32_16x16x32_bf16 v[26:29], v[184:187], v[216:219], v[26:29]
	v_mfma_f32_16x16x32_bf16 v[18:21], v[192:195], v[216:219], v[18:21]
	v_mfma_f32_16x16x32_bf16 v[10:13], v[184:187], v[224:227], v[10:13]
	v_mfma_f32_16x16x32_bf16 v[2:5], v[192:195], v[224:227], v[2:5]
	s_setprio 0
	s_barrier
	v_cmp_ge_i32_e32 vcc, s45, v138
	v_lshl_add_u64 v[150:151], v[150:151], 0, s[20:21]
	v_lshl_add_u64 v[152:153], v[152:153], 0, s[20:21]
	s_mov_b32 s5, s45
	s_cbranch_vccnz .Lmy_kexit_10

.LBB0_2073:
	v_cmp_gt_i32_e32 vcc, 1, v156
	s_cbranch_vccnz .LBB0_2135
	v_lshl_add_u64 v[152:153], v[2:3], 0, s[18:19]
	v_add_u32_e32 v138, -2, v156
	s_mov_b32 s4, 0
	v_add_u32_e32 v157, s65, v141
	ds_read_b128 v[164:167], v157
	ds_read_b128 v[168:171], v157 offset:1024
	ds_read_b128 v[172:175], v157 offset:2048
	ds_read_b128 v[176:179], v157 offset:3072
	v_add_u32_e32 v157, s66, v141
	ds_read_b128 v[180:183], v157
	ds_read_b128 v[184:187], v157 offset:1024
	ds_read_b128 v[188:191], v157 offset:2048
	ds_read_b128 v[192:195], v157 offset:3072
	v_lshl_add_u64 v[154:155], v[150:151], 0, s[18:19]
	v_cmp_eq_u32_e32 vcc, s4, v138
	s_add_i32 s5, s4, 2
	s_nop 0
	v_cndmask_b32_e32 v229, v155, v147, vcc
	v_cndmask_b32_e32 v228, v154, v146, vcc
	v_cndmask_b32_e32 v231, v153, v149, vcc
	v_cndmask_b32_e32 v230, v152, v148, vcc
	v_lshl_add_u64 v[232:233], v[150:151], 0, v[144:145]
	s_add_i32 m0, s44, 0xc000
	ds_read_b128 v[196:199], v160
	ds_read_b128 v[200:203], v160 offset:1024
	ds_read_b128 v[204:207], v160 offset:2048
	ds_read_b128 v[208:211], v160 offset:3072
	ds_read_b128 v[212:215], v160 offset:4096
	ds_read_b128 v[216:219], v160 offset:5120
	ds_read_b128 v[220:223], v160 offset:6144
	ds_read_b128 v[224:227], v160 offset:7168
	global_load_lds_dwordx4 v[232:233], off
	v_lshl_add_u64 v[150:151], v[150:151], 0, v[142:143]
	s_add_i32 m0, s44, 0xe000
	s_nop 0
	global_load_lds_dwordx4 v[150:151], off
	s_waitcnt vmcnt(8)
	s_waitcnt lgkmcnt(0)
	s_barrier
	s_setprio 1
	s_waitcnt lgkmcnt(0)
	v_mfma_f32_16x16x32_bf16 v[122:125], v[164:167], v[196:199], 0
	v_mfma_f32_16x16x32_bf16 v[118:121], v[172:175], v[196:199], 0
	v_mfma_f32_16x16x32_bf16 v[110:113], v[164:167], v[204:207], 0
	v_mfma_f32_16x16x32_bf16 v[102:105], v[172:175], v[204:207], 0
	v_mfma_f32_16x16x32_bf16 v[94:97], v[164:167], v[212:215], 0
	v_mfma_f32_16x16x32_bf16 v[86:89], v[172:175], v[212:215], 0
	v_mfma_f32_16x16x32_bf16 v[78:81], v[164:167], v[220:223], 0
	v_mfma_f32_16x16x32_bf16 v[70:73], v[172:175], v[220:223], 0
	v_mfma_f32_16x16x32_bf16 v[122:125], v[168:171], v[200:203], v[122:125]
	v_mfma_f32_16x16x32_bf16 v[118:121], v[176:179], v[200:203], v[118:121]
	v_mfma_f32_16x16x32_bf16 v[110:113], v[168:171], v[208:211], v[110:113]
	v_mfma_f32_16x16x32_bf16 v[102:105], v[176:179], v[208:211], v[102:105]
	v_mfma_f32_16x16x32_bf16 v[94:97], v[168:171], v[216:219], v[94:97]
	v_mfma_f32_16x16x32_bf16 v[86:89], v[176:179], v[216:219], v[86:89]
	v_mfma_f32_16x16x32_bf16 v[78:81], v[168:171], v[224:227], v[78:81]
	v_mfma_f32_16x16x32_bf16 v[70:73], v[176:179], v[224:227], v[70:73]
	s_setprio 0
	s_setprio 1
	v_mfma_f32_16x16x32_bf16 v[126:129], v[180:183], v[196:199], 0
	v_mfma_f32_16x16x32_bf16 v[114:117], v[188:191], v[196:199], 0
	v_mfma_f32_16x16x32_bf16 v[106:109], v[180:183], v[204:207], 0
	v_mfma_f32_16x16x32_bf16 v[98:101], v[188:191], v[204:207], 0
	v_mfma_f32_16x16x32_bf16 v[90:93], v[180:183], v[212:215], 0
	v_mfma_f32_16x16x32_bf16 v[82:85], v[188:191], v[212:215], 0
	v_mfma_f32_16x16x32_bf16 v[74:77], v[180:183], v[220:223], 0
	v_mfma_f32_16x16x32_bf16 v[66:69], v[188:191], v[220:223], 0
	v_mfma_f32_16x16x32_bf16 v[126:129], v[184:187], v[200:203], v[126:129]
	v_mfma_f32_16x16x32_bf16 v[114:117], v[192:195], v[200:203], v[114:117]
	v_mfma_f32_16x16x32_bf16 v[106:109], v[184:187], v[208:211], v[106:109]
	v_mfma_f32_16x16x32_bf16 v[98:101], v[192:195], v[208:211], v[98:101]
	v_mfma_f32_16x16x32_bf16 v[90:93], v[184:187], v[216:219], v[90:93]
	v_mfma_f32_16x16x32_bf16 v[82:85], v[192:195], v[216:219], v[82:85]
	v_mfma_f32_16x16x32_bf16 v[74:77], v[184:187], v[224:227], v[74:77]
	v_mfma_f32_16x16x32_bf16 v[66:69], v[192:195], v[224:227], v[66:69]
	s_setprio 0
	s_barrier
	s_add_i32 s4, s65, s21
	v_lshl_add_u64 v[150:151], v[230:231], 0, v[132:133]
	s_mov_b32 m0, s4
	ds_read_b128 v[196:199], v160 offset:16384
	ds_read_b128 v[200:203], v160 offset:17408
	ds_read_b128 v[204:207], v160 offset:18432
	ds_read_b128 v[208:211], v160 offset:19456
	ds_read_b128 v[212:215], v160 offset:20480
	ds_read_b128 v[216:219], v160 offset:21504
	ds_read_b128 v[220:223], v160 offset:22528
	ds_read_b128 v[224:227], v160 offset:23552
	global_load_lds_dwordx4 v[150:151], off
	v_lshl_add_u64 v[232:233], v[230:231], 0, v[136:137]
	s_add_i32 m0, s4, 0x2000
	v_lshl_add_u64 v[234:235], v[230:231], 0, s[8:9]
	s_add_i32 s4, s66, s21
	global_load_lds_dwordx4 v[232:233], off
	v_lshl_add_u64 v[236:237], v[234:235], 0, v[132:133]
	s_mov_b32 m0, s4
	v_lshl_add_u64 v[234:235], v[234:235], 0, v[136:137]
	global_load_lds_dwordx4 v[236:237], off
	s_add_i32 m0, s4, 0x2000
	v_lshl_add_u64 v[236:237], v[228:229], 0, v[134:135]
	global_load_lds_dwordx4 v[234:235], off
	v_lshl_add_u64 v[234:235], v[228:229], 0, v[130:131]
	s_mov_b32 m0, s44
	s_nop 0
	global_load_lds_dwordx4 v[234:235], off
	s_mov_b32 m0, s45
	s_nop 0
	global_load_lds_dwordx4 v[236:237], off
	s_waitcnt vmcnt(8)
	s_waitcnt lgkmcnt(0)
	s_barrier
	s_setprio 1
	s_waitcnt lgkmcnt(0)
	v_mfma_f32_16x16x32_bf16 v[62:65], v[164:167], v[196:199], 0
	v_mfma_f32_16x16x32_bf16 v[54:57], v[172:175], v[196:199], 0
	v_mfma_f32_16x16x32_bf16 v[46:49], v[164:167], v[204:207], 0
	v_mfma_f32_16x16x32_bf16 v[38:41], v[172:175], v[204:207], 0
	v_mfma_f32_16x16x32_bf16 v[30:33], v[164:167], v[212:215], 0
	v_mfma_f32_16x16x32_bf16 v[22:25], v[172:175], v[212:215], 0
	v_mfma_f32_16x16x32_bf16 v[14:17], v[164:167], v[220:223], 0
	v_mfma_f32_16x16x32_bf16 v[6:9], v[172:175], v[220:223], 0
	v_mfma_f32_16x16x32_bf16 v[62:65], v[168:171], v[200:203], v[62:65]
	v_mfma_f32_16x16x32_bf16 v[54:57], v[176:179], v[200:203], v[54:57]
	v_mfma_f32_16x16x32_bf16 v[46:49], v[168:171], v[208:211], v[46:49]
	v_mfma_f32_16x16x32_bf16 v[38:41], v[176:179], v[208:211], v[38:41]
	v_mfma_f32_16x16x32_bf16 v[30:33], v[168:171], v[216:219], v[30:33]
	v_mfma_f32_16x16x32_bf16 v[22:25], v[176:179], v[216:219], v[22:25]
	v_mfma_f32_16x16x32_bf16 v[14:17], v[168:171], v[224:227], v[14:17]
	v_mfma_f32_16x16x32_bf16 v[6:9], v[176:179], v[224:227], v[6:9]
	s_setprio 0
	s_setprio 1
	v_mfma_f32_16x16x32_bf16 v[58:61], v[180:183], v[196:199], 0
	v_mfma_f32_16x16x32_bf16 v[50:53], v[188:191], v[196:199], 0
	v_mfma_f32_16x16x32_bf16 v[42:45], v[180:183], v[204:207], 0
	v_mfma_f32_16x16x32_bf16 v[34:37], v[188:191], v[204:207], 0
	v_mfma_f32_16x16x32_bf16 v[26:29], v[180:183], v[212:215], 0
	v_mfma_f32_16x16x32_bf16 v[18:21], v[188:191], v[212:215], 0
	v_mfma_f32_16x16x32_bf16 v[10:13], v[180:183], v[220:223], 0
	v_mfma_f32_16x16x32_bf16 v[2:5], v[188:191], v[220:223], 0
	v_mfma_f32_16x16x32_bf16 v[58:61], v[184:187], v[200:203], v[58:61]
	v_mfma_f32_16x16x32_bf16 v[50:53], v[192:195], v[200:203], v[50:53]
	v_mfma_f32_16x16x32_bf16 v[42:45], v[184:187], v[208:211], v[42:45]
	v_mfma_f32_16x16x32_bf16 v[34:37], v[192:195], v[208:211], v[34:37]
	v_mfma_f32_16x16x32_bf16 v[26:29], v[184:187], v[216:219], v[26:29]
	v_mfma_f32_16x16x32_bf16 v[18:21], v[192:195], v[216:219], v[18:21]
	v_mfma_f32_16x16x32_bf16 v[10:13], v[184:187], v[224:227], v[10:13]
	v_mfma_f32_16x16x32_bf16 v[2:5], v[192:195], v[224:227], v[2:5]
	s_setprio 0
	s_barrier
	s_add_i32 s4, 0, 0x18000
	v_add_u32_e32 v157, s4, v141
	s_add_i32 s25, 0, 0x1c000
	ds_read_b128 v[164:167], v157
	ds_read_b128 v[168:171], v157 offset:1024
	ds_read_b128 v[172:175], v157 offset:2048
	ds_read_b128 v[176:179], v157 offset:3072
	v_add_u32_e32 v157, s25, v141
	ds_read_b128 v[180:183], v157
	ds_read_b128 v[184:187], v157 offset:1024
	ds_read_b128 v[188:191], v157 offset:2048
	ds_read_b128 v[192:195], v157 offset:3072
	v_lshl_add_u64 v[228:229], v[228:229], 0, s[8:9]
	s_mov_b32 m0, s46
	v_lshl_add_u64 v[238:239], v[228:229], 0, v[130:131]
	ds_read_b128 v[196:199], v160 offset:32768
	ds_read_b128 v[200:203], v160 offset:33792
	ds_read_b128 v[204:207], v160 offset:34816
	ds_read_b128 v[208:211], v160 offset:35840
	ds_read_b128 v[212:215], v160 offset:36864
	ds_read_b128 v[216:219], v160 offset:37888
	ds_read_b128 v[220:223], v160 offset:38912
	ds_read_b128 v[224:227], v160 offset:39936
	global_load_lds_dwordx4 v[238:239], off
	v_lshl_add_u64 v[228:229], v[228:229], 0, v[134:135]
	s_mov_b32 m0, s47
	s_nop 0
	global_load_lds_dwordx4 v[228:229], off
	s_waitcnt vmcnt(8)
	s_waitcnt lgkmcnt(0)
	s_barrier
	s_setprio 1
	s_waitcnt lgkmcnt(0)
	v_mfma_f32_16x16x32_bf16 v[122:125], v[164:167], v[196:199], v[122:125]
	v_mfma_f32_16x16x32_bf16 v[118:121], v[172:175], v[196:199], v[118:121]
	v_mfma_f32_16x16x32_bf16 v[110:113], v[164:167], v[204:207], v[110:113]
	v_mfma_f32_16x16x32_bf16 v[102:105], v[172:175], v[204:207], v[102:105]
	v_mfma_f32_16x16x32_bf16 v[94:97], v[164:167], v[212:215], v[94:97]
	v_mfma_f32_16x16x32_bf16 v[86:89], v[172:175], v[212:215], v[86:89]
	v_mfma_f32_16x16x32_bf16 v[78:81], v[164:167], v[220:223], v[78:81]
	v_mfma_f32_16x16x32_bf16 v[70:73], v[172:175], v[220:223], v[70:73]
	v_mfma_f32_16x16x32_bf16 v[122:125], v[168:171], v[200:203], v[122:125]
	v_mfma_f32_16x16x32_bf16 v[118:121], v[176:179], v[200:203], v[118:121]
	v_mfma_f32_16x16x32_bf16 v[110:113], v[168:171], v[208:211], v[110:113]
	v_mfma_f32_16x16x32_bf16 v[102:105], v[176:179], v[208:211], v[102:105]
	v_mfma_f32_16x16x32_bf16 v[94:97], v[168:171], v[216:219], v[94:97]
	v_mfma_f32_16x16x32_bf16 v[86:89], v[176:179], v[216:219], v[86:89]
	v_mfma_f32_16x16x32_bf16 v[78:81], v[168:171], v[224:227], v[78:81]
	v_mfma_f32_16x16x32_bf16 v[70:73], v[176:179], v[224:227], v[70:73]
	s_setprio 0
	s_setprio 1
	v_mfma_f32_16x16x32_bf16 v[126:129], v[180:183], v[196:199], v[126:129]
	v_mfma_f32_16x16x32_bf16 v[114:117], v[188:191], v[196:199], v[114:117]
	v_mfma_f32_16x16x32_bf16 v[106:109], v[180:183], v[204:207], v[106:109]
	v_mfma_f32_16x16x32_bf16 v[98:101], v[188:191], v[204:207], v[98:101]
	v_mfma_f32_16x16x32_bf16 v[90:93], v[180:183], v[212:215], v[90:93]
	v_mfma_f32_16x16x32_bf16 v[82:85], v[188:191], v[212:215], v[82:85]
	v_mfma_f32_16x16x32_bf16 v[74:77], v[180:183], v[220:223], v[74:77]
	v_mfma_f32_16x16x32_bf16 v[66:69], v[188:191], v[220:223], v[66:69]
	v_mfma_f32_16x16x32_bf16 v[126:129], v[184:187], v[200:203], v[126:129]
	v_mfma_f32_16x16x32_bf16 v[114:117], v[192:195], v[200:203], v[114:117]
	v_mfma_f32_16x16x32_bf16 v[106:109], v[184:187], v[208:211], v[106:109]
	v_mfma_f32_16x16x32_bf16 v[98:101], v[192:195], v[208:211], v[98:101]
	v_mfma_f32_16x16x32_bf16 v[90:93], v[184:187], v[216:219], v[90:93]
	v_mfma_f32_16x16x32_bf16 v[82:85], v[192:195], v[216:219], v[82:85]
	v_mfma_f32_16x16x32_bf16 v[74:77], v[184:187], v[224:227], v[74:77]
	v_mfma_f32_16x16x32_bf16 v[66:69], v[192:195], v[224:227], v[66:69]
	s_setprio 0
	s_barrier
	s_add_i32 s4, s4, s21
	v_lshl_add_u64 v[150:151], v[150:151], 0, s[12:13]
	s_mov_b32 m0, s4
	ds_read_b128 v[196:199], v160 offset:49152
	ds_read_b128 v[200:203], v160 offset:50176
	ds_read_b128 v[204:207], v160 offset:51200
	ds_read_b128 v[208:211], v160 offset:52224
	ds_read_b128 v[212:215], v160 offset:53248
	ds_read_b128 v[216:219], v160 offset:54272
	ds_read_b128 v[220:223], v160 offset:55296
	ds_read_b128 v[224:227], v160 offset:56320
	global_load_lds_dwordx4 v[150:151], off
	v_lshl_add_u64 v[150:151], v[232:233], 0, s[12:13]
	s_add_i32 m0, s4, 0x2000
	s_add_i32 s4, s25, s21
	global_load_lds_dwordx4 v[150:151], off
	v_lshl_add_u64 v[150:151], v[230:231], 0, s[14:15]
	v_lshl_add_u64 v[228:229], v[150:151], 0, v[132:133]
	s_mov_b32 m0, s4
	v_lshl_add_u64 v[150:151], v[150:151], 0, v[136:137]
	global_load_lds_dwordx4 v[228:229], off
	s_add_i32 m0, s4, 0x2000
	s_nop 0
	global_load_lds_dwordx4 v[150:151], off
	v_lshl_add_u64 v[150:151], v[234:235], 0, s[12:13]
	s_mov_b32 m0, s57
	s_nop 0
	global_load_lds_dwordx4 v[150:151], off
	v_lshl_add_u64 v[150:151], v[236:237], 0, s[12:13]
	s_mov_b32 m0, s58
	s_nop 0
	global_load_lds_dwordx4 v[150:151], off
	s_waitcnt vmcnt(8)
	s_waitcnt lgkmcnt(0)
	s_barrier
	s_setprio 1
	s_waitcnt lgkmcnt(0)
	v_mfma_f32_16x16x32_bf16 v[62:65], v[164:167], v[196:199], v[62:65]
	v_mfma_f32_16x16x32_bf16 v[54:57], v[172:175], v[196:199], v[54:57]
	v_mfma_f32_16x16x32_bf16 v[46:49], v[164:167], v[204:207], v[46:49]
	v_mfma_f32_16x16x32_bf16 v[38:41], v[172:175], v[204:207], v[38:41]
	v_mfma_f32_16x16x32_bf16 v[30:33], v[164:167], v[212:215], v[30:33]
	v_mfma_f32_16x16x32_bf16 v[22:25], v[172:175], v[212:215], v[22:25]
	v_mfma_f32_16x16x32_bf16 v[14:17], v[164:167], v[220:223], v[14:17]
	v_mfma_f32_16x16x32_bf16 v[6:9], v[172:175], v[220:223], v[6:9]
	v_mfma_f32_16x16x32_bf16 v[62:65], v[168:171], v[200:203], v[62:65]
	v_mfma_f32_16x16x32_bf16 v[54:57], v[176:179], v[200:203], v[54:57]
	v_mfma_f32_16x16x32_bf16 v[46:49], v[168:171], v[208:211], v[46:49]
	v_mfma_f32_16x16x32_bf16 v[38:41], v[176:179], v[208:211], v[38:41]
	v_mfma_f32_16x16x32_bf16 v[30:33], v[168:171], v[216:219], v[30:33]
	v_mfma_f32_16x16x32_bf16 v[22:25], v[176:179], v[216:219], v[22:25]
	v_mfma_f32_16x16x32_bf16 v[14:17], v[168:171], v[224:227], v[14:17]
	v_mfma_f32_16x16x32_bf16 v[6:9], v[176:179], v[224:227], v[6:9]
	s_setprio 0
	s_setprio 1
	v_mfma_f32_16x16x32_bf16 v[58:61], v[180:183], v[196:199], v[58:61]
	v_mfma_f32_16x16x32_bf16 v[50:53], v[188:191], v[196:199], v[50:53]
	v_mfma_f32_16x16x32_bf16 v[42:45], v[180:183], v[204:207], v[42:45]
	v_mfma_f32_16x16x32_bf16 v[34:37], v[188:191], v[204:207], v[34:37]
	v_mfma_f32_16x16x32_bf16 v[26:29], v[180:183], v[212:215], v[26:29]
	v_mfma_f32_16x16x32_bf16 v[18:21], v[188:191], v[212:215], v[18:21]
	v_mfma_f32_16x16x32_bf16 v[10:13], v[180:183], v[220:223], v[10:13]
	v_mfma_f32_16x16x32_bf16 v[2:5], v[188:191], v[220:223], v[2:5]
	v_mfma_f32_16x16x32_bf16 v[58:61], v[184:187], v[200:203], v[58:61]
	v_mfma_f32_16x16x32_bf16 v[50:53], v[192:195], v[200:203], v[50:53]
	v_mfma_f32_16x16x32_bf16 v[42:45], v[184:187], v[208:211], v[42:45]
	v_mfma_f32_16x16x32_bf16 v[34:37], v[192:195], v[208:211], v[34:37]
	v_mfma_f32_16x16x32_bf16 v[26:29], v[184:187], v[216:219], v[26:29]
	v_mfma_f32_16x16x32_bf16 v[18:21], v[192:195], v[216:219], v[18:21]
	v_mfma_f32_16x16x32_bf16 v[10:13], v[184:187], v[224:227], v[10:13]
	v_mfma_f32_16x16x32_bf16 v[2:5], v[192:195], v[224:227], v[2:5]
	s_setprio 0
	s_barrier
	v_cmp_ge_i32_e32 vcc, s5, v156
	v_lshl_add_u64 v[152:153], v[152:153], 0, s[18:19]
	v_mov_b64_e32 v[150:151], v[154:155]
	s_mov_b32 s4, s5
	s_cbranch_vccnz .Lmy_kexit_11
